# K-loop MFMA order: each accumulator's k=0 and k=1 MFMAs issued back to back (accumulate chain adjacency), per-accumulator order unchanged
# speedup vs baseline: 1.0199x; 1.0199x over previous
; #define PG8_STAGE(bufoff, gbase, voff) do { _Pragma("unroll") for (int _i = 0; _i < 2; ++_i) \
;         __builtin_amdgcn_global_load_lds((const unsigned*)((const char*)(gbase) + (voff)[_i]), (PG8_LAS unsigned*)(lds + (bufoff) + ldsw + _i * 8192), 16, 0, 0); } while (0)
; #define PG8_LDA(dst, b, h) do { _Pragma("unroll") for (int m = 0; m < 4; ++m) _Pragma("unroll") for (int k = 0; k < 2; ++k) dst[m][k] = *(const PG8_LAS bf16x8*)(lds + PG8_SA(b, h) + aoff + m * 2048 + k * 1024); } while (0)
; #define PG8_LDB(dst, b, h) do { _Pragma("unroll") for (int n = 0; n < 2; ++n) _Pragma("unroll") for (int k = 0; k < 2; ++k) dst[n][k] = *(const PG8_LAS bf16x8*)(lds + PG8_SB(b, h) + boff + n * 2048 + k * 1024); } while (0)
; #define PG8_MMA(ai, bj, At, Bt) do { __builtin_amdgcn_s_setprio(1); _Pragma("unroll") for (int m = 0; m < 4; ++m) _Pragma("unroll") for (int n = 0; n < 2; ++n) _Pragma("unroll") for (int k = 0; k < 2; ++k) \
;         acc[ai][bj][m][n] = __builtin_amdgcn_mfma_f32_16x16x32_bf16(Bt[n][k], At[m][k], acc[ai][bj][m][n], 0, 0, 0); __builtin_amdgcn_s_setprio(0); } while (0)
; #define PG8_WAIT_V(n) asm volatile("s_waitcnt vmcnt(" #n ")" ::: "memory")
; #define PG8_WAIT_L(n) asm volatile("s_waitcnt lgkmcnt(" #n ")" ::: "memory")
; template <class Epi, class Sched, bool ALIGN_EPI = false, bool SP2 = false>
; __device__ __forceinline__ void gemm_phase(PG8_LAS unsigned char* lds, const Gemm g, const Sched& S, const Epi& E) {
;     ...
;             const bool last = (t == nt - 2);
;             const char* a1 = cA + (size_t)(t + 1) * kstep;
;             const char* a2 = last ? nA : cA + (size_t)(t + 2) * kstep; const char* b2 = last ? nB : cB + (size_t)(t + 2) * kstep;
;             const char* a3 = a2 + kstep; const char* b3 = b2 + kstep;
;             if (last && has_next) S.a_ready(nxt);
;             if constexpr (SP2) {
;             PG8_LDB(B0, 0, 0); PG8_LDB(B1, 0, 1); PG8_SCHED; PG8_LDA(At, 0, 0); PG8_STAGE(PG8_SA(1, 1), a1 + hstep, voffA);
;             PG8_WAIT_V(8); PG8_WAIT_L(0); PG8_BAR; PG8_MMA(0, 0, At, B0); PG8_MMA(0, 1, At, B1); PG8_BAR; PG8_SCHED;
;             PG8_LDA(At, 0, 1); PG8_STAGE(PG8_SB(0, 0), b2, voffB); PG8_STAGE(PG8_SB(0, 1), b2 + hstep, voffB); PG8_STAGE(PG8_SA(0, 0), a2, voffA);
;             PG8_WAIT_V(8); PG8_WAIT_L(0); PG8_BAR; PG8_MMA(1, 0, At, B0); PG8_MMA(1, 1, At, B1); PG8_BAR; PG8_SCHED;
.LBB0_816:
	s_add_u32 s0, s50, 0xfff00080
	s_addc_u32 s1, s51, -1
	s_add_i32 s61, 0, 0x10000
	s_cmp_eq_u32 s60, 60
	s_cselect_b32 s27, s47, s1
	s_cselect_b32 s26, s46, s0
	s_cselect_b32 s1, s49, s45
	s_cselect_b32 s0, s48, s43
	s_add_i32 s64, 0, 0x14000
	ds_read_b128 v[142:145], v198
	ds_read_b128 v[146:149], v198 offset:1024
	ds_read_b128 v[154:157], v198 offset:2048
	ds_read_b128 v[158:161], v198 offset:3072
	ds_read_b128 v[162:165], v198 offset:16384
	ds_read_b128 v[166:169], v198 offset:17408
	ds_read_b128 v[170:173], v198 offset:18432
	ds_read_b128 v[174:177], v198 offset:19456
	s_add_i32 m0, s9, 0xc000
	ds_read_b128 v[178:181], v153
	ds_read_b128 v[182:185], v153 offset:1024
	ds_read_b128 v[186:189], v153 offset:2048
	ds_read_b128 v[190:193], v153 offset:3072
	ds_read_b128 v[194:197], v153 offset:4096
	ds_read_b128 v[214:217], v153 offset:5120
	ds_read_b128 v[218:221], v153 offset:6144
	ds_read_b128 v[234:237], v153 offset:7168
	global_load_lds_dwordx4 v138, s[50:51]
	s_add_i32 m0, s9, 0xe000
	s_nop 0
	global_load_lds_dwordx4 v140, s[50:51]
	s_waitcnt vmcnt(8)
	s_waitcnt lgkmcnt(0)
	s_setprio 1
	s_barrier
	v_mfma_f32_16x16x32_bf16 v[128:131], v[142:145], v[178:181], v[128:131]
	v_mfma_f32_16x16x32_bf16 v[128:131], v[146:149], v[182:185], v[128:131]
	v_mfma_f32_16x16x32_bf16 v[124:127], v[154:157], v[178:181], v[124:127]
	v_mfma_f32_16x16x32_bf16 v[124:127], v[158:161], v[182:185], v[124:127]
	v_mfma_f32_16x16x32_bf16 v[108:111], v[154:157], v[186:189], v[108:111]
	v_mfma_f32_16x16x32_bf16 v[108:111], v[158:161], v[190:193], v[108:111]
	v_mfma_f32_16x16x32_bf16 v[116:119], v[142:145], v[186:189], v[116:119]
	v_mfma_f32_16x16x32_bf16 v[116:119], v[146:149], v[190:193], v[116:119]
	v_mfma_f32_16x16x32_bf16 v[100:103], v[142:145], v[194:197], v[100:103]
	v_mfma_f32_16x16x32_bf16 v[100:103], v[146:149], v[214:217], v[100:103]
	v_mfma_f32_16x16x32_bf16 v[92:95], v[154:157], v[194:197], v[92:95]
	v_mfma_f32_16x16x32_bf16 v[92:95], v[158:161], v[214:217], v[92:95]
	v_mfma_f32_16x16x32_bf16 v[76:79], v[154:157], v[218:221], v[76:79]
	v_mfma_f32_16x16x32_bf16 v[76:79], v[158:161], v[234:237], v[76:79]
	v_mfma_f32_16x16x32_bf16 v[84:87], v[142:145], v[218:221], v[84:87]
	v_mfma_f32_16x16x32_bf16 v[84:87], v[146:149], v[234:237], v[84:87]
	s_setprio 0
	s_setprio 1
	v_mfma_f32_16x16x32_bf16 v[120:123], v[162:165], v[178:181], v[120:123]
	v_mfma_f32_16x16x32_bf16 v[120:123], v[166:169], v[182:185], v[120:123]
	v_mfma_f32_16x16x32_bf16 v[112:115], v[170:173], v[178:181], v[112:115]
	v_mfma_f32_16x16x32_bf16 v[112:115], v[174:177], v[182:185], v[112:115]
	v_mfma_f32_16x16x32_bf16 v[96:99], v[170:173], v[186:189], v[96:99]
	v_mfma_f32_16x16x32_bf16 v[96:99], v[174:177], v[190:193], v[96:99]
	v_mfma_f32_16x16x32_bf16 v[104:107], v[162:165], v[186:189], v[104:107]
	v_mfma_f32_16x16x32_bf16 v[104:107], v[166:169], v[190:193], v[104:107]
	v_mfma_f32_16x16x32_bf16 v[88:91], v[162:165], v[194:197], v[88:91]
	v_mfma_f32_16x16x32_bf16 v[88:91], v[166:169], v[214:217], v[88:91]
	v_mfma_f32_16x16x32_bf16 v[80:83], v[170:173], v[194:197], v[80:83]
	v_mfma_f32_16x16x32_bf16 v[80:83], v[174:177], v[214:217], v[80:83]
	v_mfma_f32_16x16x32_bf16 v[68:71], v[170:173], v[218:221], v[68:71]
	v_mfma_f32_16x16x32_bf16 v[68:71], v[174:177], v[234:237], v[68:71]
	v_mfma_f32_16x16x32_bf16 v[72:75], v[162:165], v[218:221], v[72:75]
	v_mfma_f32_16x16x32_bf16 v[72:75], v[166:169], v[234:237], v[72:75]
	s_barrier
	s_setprio 0
	s_add_i32 s61, s61, s8
	s_mov_b32 m0, s61
	ds_read_b128 v[178:181], v153 offset:16384
	ds_read_b128 v[182:185], v153 offset:17408
	ds_read_b128 v[186:189], v153 offset:18432
	ds_read_b128 v[190:193], v153 offset:19456
	ds_read_b128 v[194:197], v153 offset:20480
	ds_read_b128 v[214:217], v153 offset:21504
	ds_read_b128 v[218:221], v153 offset:22528
	ds_read_b128 v[234:237], v153 offset:23552
	global_load_lds_dwordx4 v2, s[0:1]
	s_add_i32 m0, s61, 0x2000
	s_add_u32 s62, s0, 0x100000
	s_addc_u32 s63, s1, 0
	s_add_i32 s61, s64, s8
	global_load_lds_dwordx4 v132, s[0:1]
	s_mov_b32 m0, s61
	s_nop 0
	global_load_lds_dwordx4 v2, s[62:63]
	s_add_i32 m0, s61, 0x2000
	s_nop 0
	global_load_lds_dwordx4 v132, s[62:63]
	s_mov_b32 m0, s9
	s_nop 0
	global_load_lds_dwordx4 v136, s[26:27]
	s_mov_b32 m0, s10
	s_nop 0
	global_load_lds_dwordx4 v134, s[26:27]
	s_add_u32 s100, s26, 0x80
	s_addc_u32 s101, s27, 0
	s_waitcnt vmcnt(8)
	s_waitcnt lgkmcnt(0)
	s_setprio 1
	s_barrier
	v_mfma_f32_16x16x32_bf16 v[64:67], v[142:145], v[178:181], v[64:67]
	v_mfma_f32_16x16x32_bf16 v[64:67], v[146:149], v[182:185], v[64:67]
	v_mfma_f32_16x16x32_bf16 v[60:63], v[154:157], v[178:181], v[60:63]
	v_mfma_f32_16x16x32_bf16 v[60:63], v[158:161], v[182:185], v[60:63]
	v_mfma_f32_16x16x32_bf16 v[44:47], v[154:157], v[186:189], v[44:47]
	v_mfma_f32_16x16x32_bf16 v[44:47], v[158:161], v[190:193], v[44:47]
	v_mfma_f32_16x16x32_bf16 v[52:55], v[142:145], v[186:189], v[52:55]
	v_mfma_f32_16x16x32_bf16 v[52:55], v[146:149], v[190:193], v[52:55]
	v_mfma_f32_16x16x32_bf16 v[36:39], v[142:145], v[194:197], v[36:39]
	v_mfma_f32_16x16x32_bf16 v[36:39], v[146:149], v[214:217], v[36:39]
	v_mfma_f32_16x16x32_bf16 v[28:31], v[154:157], v[194:197], v[28:31]
	v_mfma_f32_16x16x32_bf16 v[28:31], v[158:161], v[214:217], v[28:31]
	v_mfma_f32_16x16x32_bf16 v[12:15], v[154:157], v[218:221], v[12:15]
	v_mfma_f32_16x16x32_bf16 v[12:15], v[158:161], v[234:237], v[12:15]
	v_mfma_f32_16x16x32_bf16 v[16:19], v[142:145], v[218:221], v[16:19]
	v_mfma_f32_16x16x32_bf16 v[16:19], v[146:149], v[234:237], v[16:19]
	s_setprio 0
	s_setprio 1
	v_mfma_f32_16x16x32_bf16 v[56:59], v[162:165], v[178:181], v[56:59]
	v_mfma_f32_16x16x32_bf16 v[56:59], v[166:169], v[182:185], v[56:59]
	v_mfma_f32_16x16x32_bf16 v[48:51], v[170:173], v[178:181], v[48:51]
	v_mfma_f32_16x16x32_bf16 v[48:51], v[174:177], v[182:185], v[48:51]
	v_mfma_f32_16x16x32_bf16 v[32:35], v[170:173], v[186:189], v[32:35]
	v_mfma_f32_16x16x32_bf16 v[32:35], v[174:177], v[190:193], v[32:35]
	v_mfma_f32_16x16x32_bf16 v[40:43], v[162:165], v[186:189], v[40:43]
	v_mfma_f32_16x16x32_bf16 v[40:43], v[166:169], v[190:193], v[40:43]
	v_mfma_f32_16x16x32_bf16 v[24:27], v[162:165], v[194:197], v[24:27]
	v_mfma_f32_16x16x32_bf16 v[24:27], v[166:169], v[214:217], v[24:27]
	v_mfma_f32_16x16x32_bf16 v[20:23], v[170:173], v[194:197], v[20:23]
	v_mfma_f32_16x16x32_bf16 v[20:23], v[174:177], v[214:217], v[20:23]
	v_mfma_f32_16x16x32_bf16 v[4:7], v[170:173], v[218:221], v[4:7]
	v_mfma_f32_16x16x32_bf16 v[4:7], v[174:177], v[234:237], v[4:7]
	v_mfma_f32_16x16x32_bf16 v[8:11], v[162:165], v[218:221], v[8:11]
	v_mfma_f32_16x16x32_bf16 v[8:11], v[166:169], v[234:237], v[8:11]
	s_barrier
; #define PG8_STAGE(bufoff, gbase, voff) do { _Pragma("unroll") for (int _i = 0; _i < 2; ++_i) \
;         __builtin_amdgcn_global_load_lds((const unsigned*)((const char*)(gbase) + (voff)[_i]), (PG8_LAS unsigned*)(lds + (bufoff) + ldsw + _i * 8192), 16, 0, 0); } while (0)
; #define PG8_LDA(dst, b, h) do { _Pragma("unroll") for (int m = 0; m < 4; ++m) _Pragma("unroll") for (int k = 0; k < 2; ++k) dst[m][k] = *(const PG8_LAS bf16x8*)(lds + PG8_SA(b, h) + aoff + m * 2048 + k * 1024); } while (0)
; #define PG8_LDB(dst, b, h) do { _Pragma("unroll") for (int n = 0; n < 2; ++n) _Pragma("unroll") for (int k = 0; k < 2; ++k) dst[n][k] = *(const PG8_LAS bf16x8*)(lds + PG8_SB(b, h) + boff + n * 2048 + k * 1024); } while (0)
; #define PG8_MMA(ai, bj, At, Bt) do { __builtin_amdgcn_s_setprio(1); _Pragma("unroll") for (int m = 0; m < 4; ++m) _Pragma("unroll") for (int n = 0; n < 2; ++n) _Pragma("unroll") for (int k = 0; k < 2; ++k) \
;         acc[ai][bj][m][n] = __builtin_amdgcn_mfma_f32_16x16x32_bf16(Bt[n][k], At[m][k], acc[ai][bj][m][n], 0, 0, 0); __builtin_amdgcn_s_setprio(0); } while (0)
; #define PG8_WAIT_V(n) asm volatile("s_waitcnt vmcnt(" #n ")" ::: "memory")
; #define PG8_WAIT_L(n) asm volatile("s_waitcnt lgkmcnt(" #n ")" ::: "memory")
; #define PG8_BAR __builtin_amdgcn_s_barrier()
; #define PG8_SCHED __builtin_amdgcn_sched_barrier(0)
; template <class Epi, class Sched, bool ALIGN_EPI = false, bool SP2 = false>
; __device__ __forceinline__ void gemm_phase(PG8_LAS unsigned char* lds, const Gemm g, const Sched& S, const Epi& E) {
;     ...
;         for (int t = 0; t < nt; t += 2) {
;             const bool last = (t == nt - 2);
;             const char* a1 = cA + (size_t)(t + 1) * kstep;
;             const char* a2 = last ? nA : cA + (size_t)(t + 2) * kstep; const char* b2 = last ? nB : cB + (size_t)(t + 2) * kstep;
;     ...
;             PG8_LDB(B0, 1, 0); PG8_LDB(B1, 1, 1); PG8_SCHED; PG8_LDA(At, 1, 0); PG8_STAGE(PG8_SA(0, 1), a2 + hstep, voffA);
;             PG8_WAIT_V(8); PG8_WAIT_L(0); PG8_BAR; PG8_MMA(0, 0, At, B0); PG8_MMA(0, 1, At, B1); PG8_BAR; PG8_SCHED;
;             PG8_LDA(At, 1, 1); PG8_STAGE(PG8_SB(1, 0), b3, voffB); PG8_STAGE(PG8_SB(1, 1), b3 + hstep, voffB); PG8_STAGE(PG8_SA(1, 0), a3, voffA);
;             PG8_WAIT_V(8); PG8_WAIT_L(0); PG8_BAR; PG8_MMA(1, 0, At, B0); PG8_MMA(1, 1, At, B1); PG8_BAR; PG8_SCHED;
	s_setprio 0
	s_add_i32 s61, 0, 0x18000
	s_add_i32 s62, 0, 0x1c000
	ds_read_b128 v[142:145], v198 offset:32768
	ds_read_b128 v[146:149], v198 offset:33792
	ds_read_b128 v[154:157], v198 offset:34816
	ds_read_b128 v[158:161], v198 offset:35840
	ds_read_b128 v[162:165], v198 offset:49152
	ds_read_b128 v[166:169], v198 offset:50176
	ds_read_b128 v[170:173], v198 offset:51200
	ds_read_b128 v[174:177], v198 offset:52224
	s_add_u32 s26, s26, 0x100000
	s_addc_u32 s27, s27, 0
	s_mov_b32 m0, s11
	ds_read_b128 v[178:181], v153 offset:32768
	ds_read_b128 v[182:185], v153 offset:33792
	ds_read_b128 v[186:189], v153 offset:34816
	ds_read_b128 v[190:193], v153 offset:35840
	ds_read_b128 v[194:197], v153 offset:36864
	ds_read_b128 v[214:217], v153 offset:37888
	ds_read_b128 v[218:221], v153 offset:38912
	ds_read_b128 v[234:237], v153 offset:39936
	global_load_lds_dwordx4 v136, s[26:27]
	s_mov_b32 m0, s52
	s_nop 0
	global_load_lds_dwordx4 v134, s[26:27]
	s_waitcnt vmcnt(8)
	s_waitcnt lgkmcnt(0)
	s_setprio 1
	s_barrier
	v_mfma_f32_16x16x32_bf16 v[128:131], v[142:145], v[178:181], v[128:131]
	v_mfma_f32_16x16x32_bf16 v[128:131], v[146:149], v[182:185], v[128:131]
	v_mfma_f32_16x16x32_bf16 v[124:127], v[154:157], v[178:181], v[124:127]
	v_mfma_f32_16x16x32_bf16 v[124:127], v[158:161], v[182:185], v[124:127]
	v_mfma_f32_16x16x32_bf16 v[108:111], v[154:157], v[186:189], v[108:111]
	v_mfma_f32_16x16x32_bf16 v[108:111], v[158:161], v[190:193], v[108:111]
	v_mfma_f32_16x16x32_bf16 v[116:119], v[142:145], v[186:189], v[116:119]
	v_mfma_f32_16x16x32_bf16 v[116:119], v[146:149], v[190:193], v[116:119]
	v_mfma_f32_16x16x32_bf16 v[100:103], v[142:145], v[194:197], v[100:103]
	v_mfma_f32_16x16x32_bf16 v[100:103], v[146:149], v[214:217], v[100:103]
	v_mfma_f32_16x16x32_bf16 v[92:95], v[154:157], v[194:197], v[92:95]
	v_mfma_f32_16x16x32_bf16 v[92:95], v[158:161], v[214:217], v[92:95]
	v_mfma_f32_16x16x32_bf16 v[76:79], v[154:157], v[218:221], v[76:79]
	v_mfma_f32_16x16x32_bf16 v[76:79], v[158:161], v[234:237], v[76:79]
	v_mfma_f32_16x16x32_bf16 v[84:87], v[142:145], v[218:221], v[84:87]
	v_mfma_f32_16x16x32_bf16 v[84:87], v[146:149], v[234:237], v[84:87]
	s_setprio 0
	s_setprio 1
	v_mfma_f32_16x16x32_bf16 v[120:123], v[162:165], v[178:181], v[120:123]
	v_mfma_f32_16x16x32_bf16 v[120:123], v[166:169], v[182:185], v[120:123]
	v_mfma_f32_16x16x32_bf16 v[112:115], v[170:173], v[178:181], v[112:115]
	v_mfma_f32_16x16x32_bf16 v[112:115], v[174:177], v[182:185], v[112:115]
	v_mfma_f32_16x16x32_bf16 v[96:99], v[170:173], v[186:189], v[96:99]
	v_mfma_f32_16x16x32_bf16 v[96:99], v[174:177], v[190:193], v[96:99]
	v_mfma_f32_16x16x32_bf16 v[104:107], v[162:165], v[186:189], v[104:107]
	v_mfma_f32_16x16x32_bf16 v[104:107], v[166:169], v[190:193], v[104:107]
	v_mfma_f32_16x16x32_bf16 v[88:91], v[162:165], v[194:197], v[88:91]
	v_mfma_f32_16x16x32_bf16 v[88:91], v[166:169], v[214:217], v[88:91]
	v_mfma_f32_16x16x32_bf16 v[80:83], v[170:173], v[194:197], v[80:83]
	v_mfma_f32_16x16x32_bf16 v[80:83], v[174:177], v[214:217], v[80:83]
	v_mfma_f32_16x16x32_bf16 v[68:71], v[170:173], v[218:221], v[68:71]
	v_mfma_f32_16x16x32_bf16 v[68:71], v[174:177], v[234:237], v[68:71]
	v_mfma_f32_16x16x32_bf16 v[72:75], v[162:165], v[218:221], v[72:75]
	v_mfma_f32_16x16x32_bf16 v[72:75], v[166:169], v[234:237], v[72:75]
	s_barrier
	s_setprio 0
	s_add_i32 s26, s61, s8
	s_mov_b32 m0, s26
	ds_read_b128 v[178:181], v153 offset:49152
	ds_read_b128 v[182:185], v153 offset:50176
	ds_read_b128 v[186:189], v153 offset:51200
	ds_read_b128 v[190:193], v153 offset:52224
	ds_read_b128 v[194:197], v153 offset:53248
	ds_read_b128 v[214:217], v153 offset:54272
	ds_read_b128 v[218:221], v153 offset:55296
	ds_read_b128 v[234:237], v153 offset:56320
	s_add_u32 s0, s0, 0x80
	s_addc_u32 s1, s1, 0
	global_load_lds_dwordx4 v2, s[0:1]
	s_add_i32 m0, s26, 0x2000
	s_add_i32 s26, s62, s8
	global_load_lds_dwordx4 v132, s[0:1]
	s_add_u32 s0, s0, 0x100000
	s_addc_u32 s1, s1, 0
	s_mov_b32 m0, s26
	s_nop 0
	global_load_lds_dwordx4 v2, s[0:1]
	s_add_i32 m0, s26, 0x2000
	s_nop 0
	global_load_lds_dwordx4 v132, s[0:1]
	s_mov_b32 m0, s54
	s_nop 0
	global_load_lds_dwordx4 v136, s[100:101]
	s_mov_b32 m0, s55
	s_nop 0
	global_load_lds_dwordx4 v134, s[100:101]
	s_waitcnt vmcnt(8)
	s_waitcnt lgkmcnt(0)
	s_setprio 1
	s_barrier
	v_mfma_f32_16x16x32_bf16 v[64:67], v[142:145], v[178:181], v[64:67]
	v_mfma_f32_16x16x32_bf16 v[64:67], v[146:149], v[182:185], v[64:67]
	v_mfma_f32_16x16x32_bf16 v[60:63], v[154:157], v[178:181], v[60:63]
	v_mfma_f32_16x16x32_bf16 v[60:63], v[158:161], v[182:185], v[60:63]
	v_mfma_f32_16x16x32_bf16 v[44:47], v[154:157], v[186:189], v[44:47]
	v_mfma_f32_16x16x32_bf16 v[44:47], v[158:161], v[190:193], v[44:47]
	v_mfma_f32_16x16x32_bf16 v[52:55], v[142:145], v[186:189], v[52:55]
	v_mfma_f32_16x16x32_bf16 v[52:55], v[146:149], v[190:193], v[52:55]
	v_mfma_f32_16x16x32_bf16 v[36:39], v[142:145], v[194:197], v[36:39]
	v_mfma_f32_16x16x32_bf16 v[36:39], v[146:149], v[214:217], v[36:39]
	v_mfma_f32_16x16x32_bf16 v[28:31], v[154:157], v[194:197], v[28:31]
	v_mfma_f32_16x16x32_bf16 v[28:31], v[158:161], v[214:217], v[28:31]
	v_mfma_f32_16x16x32_bf16 v[12:15], v[154:157], v[218:221], v[12:15]
	v_mfma_f32_16x16x32_bf16 v[12:15], v[158:161], v[234:237], v[12:15]
	v_mfma_f32_16x16x32_bf16 v[16:19], v[142:145], v[218:221], v[16:19]
	v_mfma_f32_16x16x32_bf16 v[16:19], v[146:149], v[234:237], v[16:19]
	s_setprio 0
	s_setprio 1
	v_mfma_f32_16x16x32_bf16 v[56:59], v[162:165], v[178:181], v[56:59]
	v_mfma_f32_16x16x32_bf16 v[56:59], v[166:169], v[182:185], v[56:59]
	v_mfma_f32_16x16x32_bf16 v[48:51], v[170:173], v[178:181], v[48:51]
	v_mfma_f32_16x16x32_bf16 v[48:51], v[174:177], v[182:185], v[48:51]
	v_mfma_f32_16x16x32_bf16 v[32:35], v[170:173], v[186:189], v[32:35]
	v_mfma_f32_16x16x32_bf16 v[32:35], v[174:177], v[190:193], v[32:35]
	v_mfma_f32_16x16x32_bf16 v[40:43], v[162:165], v[186:189], v[40:43]
	v_mfma_f32_16x16x32_bf16 v[40:43], v[166:169], v[190:193], v[40:43]
	v_mfma_f32_16x16x32_bf16 v[24:27], v[162:165], v[194:197], v[24:27]
	v_mfma_f32_16x16x32_bf16 v[24:27], v[166:169], v[214:217], v[24:27]
	v_mfma_f32_16x16x32_bf16 v[20:23], v[170:173], v[194:197], v[20:23]
	v_mfma_f32_16x16x32_bf16 v[20:23], v[174:177], v[214:217], v[20:23]
	v_mfma_f32_16x16x32_bf16 v[4:7], v[170:173], v[218:221], v[4:7]
	v_mfma_f32_16x16x32_bf16 v[4:7], v[174:177], v[234:237], v[4:7]
	v_mfma_f32_16x16x32_bf16 v[8:11], v[162:165], v[218:221], v[8:11]
	v_mfma_f32_16x16x32_bf16 v[8:11], v[166:169], v[234:237], v[8:11]
	s_barrier
	s_setprio 0
	s_add_i32 s60, s60, 2
	s_add_u32 s50, s50, 0x100
	s_addc_u32 s51, s51, 0
	s_add_u32 s43, s43, 0x100
	s_addc_u32 s45, s45, 0
	s_cmp_gt_u32 s60, 61
	s_cbranch_scc0 .LBB0_816
	s_and_b64 vcc, exec, s[40:41]
	s_cbranch_vccz .LBB0_819
	s_barrier

; #define PG8_STAGE(bufoff, gbase, voff) do { _Pragma("unroll") for (int _i = 0; _i < 2; ++_i) \
;         __builtin_amdgcn_global_load_lds((const unsigned*)((const char*)(gbase) + (voff)[_i]), (PG8_LAS unsigned*)(lds + (bufoff) + ldsw + _i * 8192), 16, 0, 0); } while (0)
; #define PG8_LDA(dst, b, h) do { _Pragma("unroll") for (int m = 0; m < 4; ++m) _Pragma("unroll") for (int k = 0; k < 2; ++k) dst[m][k] = *(const PG8_LAS bf16x8*)(lds + PG8_SA(b, h) + aoff + m * 2048 + k * 1024); } while (0)
; #define PG8_LDB(dst, b, h) do { _Pragma("unroll") for (int n = 0; n < 2; ++n) _Pragma("unroll") for (int k = 0; k < 2; ++k) dst[n][k] = *(const PG8_LAS bf16x8*)(lds + PG8_SB(b, h) + boff + n * 2048 + k * 1024); } while (0)
; #define PG8_MMA(ai, bj, At, Bt) do { __builtin_amdgcn_s_setprio(1); _Pragma("unroll") for (int m = 0; m < 4; ++m) _Pragma("unroll") for (int n = 0; n < 2; ++n) _Pragma("unroll") for (int k = 0; k < 2; ++k) \
;         acc[ai][bj][m][n] = __builtin_amdgcn_mfma_f32_16x16x32_bf16(Bt[n][k], At[m][k], acc[ai][bj][m][n], 0, 0, 0); __builtin_amdgcn_s_setprio(0); } while (0)
; #define PG8_WAIT_V(n) asm volatile("s_waitcnt vmcnt(" #n ")" ::: "memory")
; #define PG8_WAIT_L(n) asm volatile("s_waitcnt lgkmcnt(" #n ")" ::: "memory")
; template <class Epi, class Sched, bool ALIGN_EPI = false, bool SP2 = false>
; __device__ __forceinline__ void gemm_phase(PG8_LAS unsigned char* lds, const Gemm g, const Sched& S, const Epi& E) {
;     ...
;             const bool last = (t == nt - 2);
;             const char* a1 = cA + (size_t)(t + 1) * kstep;
;             const char* a2 = last ? nA : cA + (size_t)(t + 2) * kstep; const char* b2 = last ? nB : cB + (size_t)(t + 2) * kstep;
;             const char* a3 = a2 + kstep; const char* b3 = b2 + kstep;
;             if (last && has_next) S.a_ready(nxt);
;             if constexpr (SP2) {
;             PG8_LDB(B0, 0, 0); PG8_LDB(B1, 0, 1); PG8_SCHED; PG8_LDA(At, 0, 0); PG8_STAGE(PG8_SA(1, 1), a1 + hstep, voffA);
;             PG8_WAIT_V(8); PG8_WAIT_L(0); PG8_BAR; PG8_MMA(0, 0, At, B0); PG8_MMA(0, 1, At, B1); PG8_BAR; PG8_SCHED;
;             PG8_LDA(At, 0, 1); PG8_STAGE(PG8_SB(0, 0), b2, voffB); PG8_STAGE(PG8_SB(0, 1), b2 + hstep, voffB); PG8_STAGE(PG8_SA(0, 0), a2, voffA);
;             PG8_WAIT_V(8); PG8_WAIT_L(0); PG8_BAR; PG8_MMA(1, 0, At, B0); PG8_MMA(1, 1, At, B1); PG8_BAR; PG8_SCHED;
.LBB0_1032:
	s_add_u32 s0, s50, 0xfffc0080
	s_addc_u32 s1, s51, -1
	s_add_i32 s53, 0, 0x10000
	s_cmp_eq_u32 s52, 12
	s_cselect_b32 s27, s47, s1
	s_cselect_b32 s26, s46, s0
	s_cselect_b32 s1, s49, s45
	s_cselect_b32 s0, s48, s43
	s_add_i32 s64, 0, 0x14000
	ds_read_b128 v[146:149], v198
	ds_read_b128 v[150:153], v198 offset:1024
	ds_read_b128 v[154:157], v198 offset:2048
	ds_read_b128 v[158:161], v198 offset:3072
	ds_read_b128 v[162:165], v198 offset:16384
	ds_read_b128 v[166:169], v198 offset:17408
	ds_read_b128 v[170:173], v198 offset:18432
	ds_read_b128 v[174:177], v198 offset:19456
	s_add_i32 m0, s37, 0xc000
	ds_read_b128 v[178:181], v145
	ds_read_b128 v[182:185], v145 offset:1024
	ds_read_b128 v[186:189], v145 offset:2048
	ds_read_b128 v[190:193], v145 offset:3072
	ds_read_b128 v[194:197], v145 offset:4096
	ds_read_b128 v[214:217], v145 offset:5120
	ds_read_b128 v[218:221], v145 offset:6144
	ds_read_b128 v[234:237], v145 offset:7168
	global_load_lds_dwordx4 v138, s[50:51]
	s_add_i32 m0, s37, 0xe000
	s_nop 0
	global_load_lds_dwordx4 v140, s[50:51]
	s_waitcnt vmcnt(8)
	s_waitcnt lgkmcnt(0)
	s_setprio 1
	s_barrier
	v_mfma_f32_16x16x32_bf16 v[128:131], v[146:149], v[178:181], v[128:131]
	v_mfma_f32_16x16x32_bf16 v[128:131], v[150:153], v[182:185], v[128:131]
	v_mfma_f32_16x16x32_bf16 v[124:127], v[154:157], v[178:181], v[124:127]
	v_mfma_f32_16x16x32_bf16 v[124:127], v[158:161], v[182:185], v[124:127]
	v_mfma_f32_16x16x32_bf16 v[116:119], v[154:157], v[186:189], v[116:119]
	v_mfma_f32_16x16x32_bf16 v[116:119], v[158:161], v[190:193], v[116:119]
	v_mfma_f32_16x16x32_bf16 v[120:123], v[146:149], v[186:189], v[120:123]
	v_mfma_f32_16x16x32_bf16 v[120:123], v[150:153], v[190:193], v[120:123]
	v_mfma_f32_16x16x32_bf16 v[104:107], v[146:149], v[194:197], v[104:107]
	v_mfma_f32_16x16x32_bf16 v[104:107], v[150:153], v[214:217], v[104:107]
	v_mfma_f32_16x16x32_bf16 v[100:103], v[154:157], v[194:197], v[100:103]
	v_mfma_f32_16x16x32_bf16 v[100:103], v[158:161], v[214:217], v[100:103]
	v_mfma_f32_16x16x32_bf16 v[84:87], v[154:157], v[218:221], v[84:87]
	v_mfma_f32_16x16x32_bf16 v[84:87], v[158:161], v[234:237], v[84:87]
	v_mfma_f32_16x16x32_bf16 v[88:91], v[146:149], v[218:221], v[88:91]
	v_mfma_f32_16x16x32_bf16 v[88:91], v[150:153], v[234:237], v[88:91]
	s_setprio 0
	s_setprio 1
	v_mfma_f32_16x16x32_bf16 v[112:115], v[162:165], v[178:181], v[112:115]
	v_mfma_f32_16x16x32_bf16 v[112:115], v[166:169], v[182:185], v[112:115]
	v_mfma_f32_16x16x32_bf16 v[108:111], v[170:173], v[178:181], v[108:111]
	v_mfma_f32_16x16x32_bf16 v[108:111], v[174:177], v[182:185], v[108:111]
	v_mfma_f32_16x16x32_bf16 v[92:95], v[170:173], v[186:189], v[92:95]
	v_mfma_f32_16x16x32_bf16 v[92:95], v[174:177], v[190:193], v[92:95]
	v_mfma_f32_16x16x32_bf16 v[96:99], v[162:165], v[186:189], v[96:99]
	v_mfma_f32_16x16x32_bf16 v[96:99], v[166:169], v[190:193], v[96:99]
	v_mfma_f32_16x16x32_bf16 v[80:83], v[162:165], v[194:197], v[80:83]
	v_mfma_f32_16x16x32_bf16 v[80:83], v[166:169], v[214:217], v[80:83]
	v_mfma_f32_16x16x32_bf16 v[76:79], v[170:173], v[194:197], v[76:79]
	v_mfma_f32_16x16x32_bf16 v[76:79], v[174:177], v[214:217], v[76:79]
	v_mfma_f32_16x16x32_bf16 v[68:71], v[170:173], v[218:221], v[68:71]
	v_mfma_f32_16x16x32_bf16 v[68:71], v[174:177], v[234:237], v[68:71]
	v_mfma_f32_16x16x32_bf16 v[72:75], v[162:165], v[218:221], v[72:75]
	v_mfma_f32_16x16x32_bf16 v[72:75], v[166:169], v[234:237], v[72:75]
	s_barrier
	s_setprio 0
	s_add_i32 s53, s53, s10
	s_mov_b32 m0, s53
	ds_read_b128 v[178:181], v145 offset:16384
	ds_read_b128 v[182:185], v145 offset:17408
	ds_read_b128 v[186:189], v145 offset:18432
	ds_read_b128 v[190:193], v145 offset:19456
	ds_read_b128 v[194:197], v145 offset:20480
	ds_read_b128 v[214:217], v145 offset:21504
	ds_read_b128 v[218:221], v145 offset:22528
	ds_read_b128 v[234:237], v145 offset:23552
	global_load_lds_dwordx4 v2, s[0:1]
	s_add_i32 m0, s53, 0x2000
	s_add_u32 s62, s0, 0x40000
	s_addc_u32 s63, s1, 0
	s_add_i32 s53, s64, s10
	global_load_lds_dwordx4 v132, s[0:1]
	s_mov_b32 m0, s53
	s_nop 0
	global_load_lds_dwordx4 v2, s[62:63]
	s_add_i32 m0, s53, 0x2000
	s_nop 0
	global_load_lds_dwordx4 v132, s[62:63]
	s_mov_b32 m0, s37
	s_nop 0
	global_load_lds_dwordx4 v136, s[26:27]
	s_mov_b32 m0, s54
	s_nop 0
	global_load_lds_dwordx4 v134, s[26:27]
	s_add_u32 s100, s26, 0x80
	s_addc_u32 s101, s27, 0
	s_waitcnt vmcnt(8)
	s_waitcnt lgkmcnt(0)
	s_setprio 1
	s_barrier
	v_mfma_f32_16x16x32_bf16 v[64:67], v[146:149], v[178:181], v[64:67]
	v_mfma_f32_16x16x32_bf16 v[64:67], v[150:153], v[182:185], v[64:67]
	v_mfma_f32_16x16x32_bf16 v[60:63], v[154:157], v[178:181], v[60:63]
	v_mfma_f32_16x16x32_bf16 v[60:63], v[158:161], v[182:185], v[60:63]
	v_mfma_f32_16x16x32_bf16 v[52:55], v[154:157], v[186:189], v[52:55]
	v_mfma_f32_16x16x32_bf16 v[52:55], v[158:161], v[190:193], v[52:55]
	v_mfma_f32_16x16x32_bf16 v[56:59], v[146:149], v[186:189], v[56:59]
	v_mfma_f32_16x16x32_bf16 v[56:59], v[150:153], v[190:193], v[56:59]
	v_mfma_f32_16x16x32_bf16 v[40:43], v[146:149], v[194:197], v[40:43]
	v_mfma_f32_16x16x32_bf16 v[40:43], v[150:153], v[214:217], v[40:43]
	v_mfma_f32_16x16x32_bf16 v[36:39], v[154:157], v[194:197], v[36:39]
	v_mfma_f32_16x16x32_bf16 v[36:39], v[158:161], v[214:217], v[36:39]
	v_mfma_f32_16x16x32_bf16 v[20:23], v[154:157], v[218:221], v[20:23]
	v_mfma_f32_16x16x32_bf16 v[20:23], v[158:161], v[234:237], v[20:23]
	v_mfma_f32_16x16x32_bf16 v[24:27], v[146:149], v[218:221], v[24:27]
	v_mfma_f32_16x16x32_bf16 v[24:27], v[150:153], v[234:237], v[24:27]
	s_setprio 0
	s_setprio 1
	v_mfma_f32_16x16x32_bf16 v[48:51], v[162:165], v[178:181], v[48:51]
	v_mfma_f32_16x16x32_bf16 v[48:51], v[166:169], v[182:185], v[48:51]
	v_mfma_f32_16x16x32_bf16 v[44:47], v[170:173], v[178:181], v[44:47]
	v_mfma_f32_16x16x32_bf16 v[44:47], v[174:177], v[182:185], v[44:47]
	v_mfma_f32_16x16x32_bf16 v[28:31], v[170:173], v[186:189], v[28:31]
	v_mfma_f32_16x16x32_bf16 v[28:31], v[174:177], v[190:193], v[28:31]
	v_mfma_f32_16x16x32_bf16 v[32:35], v[162:165], v[186:189], v[32:35]
	v_mfma_f32_16x16x32_bf16 v[32:35], v[166:169], v[190:193], v[32:35]
	v_mfma_f32_16x16x32_bf16 v[16:19], v[162:165], v[194:197], v[16:19]
	v_mfma_f32_16x16x32_bf16 v[16:19], v[166:169], v[214:217], v[16:19]
	v_mfma_f32_16x16x32_bf16 v[12:15], v[170:173], v[194:197], v[12:15]
	v_mfma_f32_16x16x32_bf16 v[12:15], v[174:177], v[214:217], v[12:15]
	v_mfma_f32_16x16x32_bf16 v[4:7], v[170:173], v[218:221], v[4:7]
	v_mfma_f32_16x16x32_bf16 v[4:7], v[174:177], v[234:237], v[4:7]
	v_mfma_f32_16x16x32_bf16 v[8:11], v[162:165], v[218:221], v[8:11]
	v_mfma_f32_16x16x32_bf16 v[8:11], v[166:169], v[234:237], v[8:11]
	s_barrier
; #define PG8_STAGE(bufoff, gbase, voff) do { _Pragma("unroll") for (int _i = 0; _i < 2; ++_i) \
;         __builtin_amdgcn_global_load_lds((const unsigned*)((const char*)(gbase) + (voff)[_i]), (PG8_LAS unsigned*)(lds + (bufoff) + ldsw + _i * 8192), 16, 0, 0); } while (0)
; #define PG8_LDA(dst, b, h) do { _Pragma("unroll") for (int m = 0; m < 4; ++m) _Pragma("unroll") for (int k = 0; k < 2; ++k) dst[m][k] = *(const PG8_LAS bf16x8*)(lds + PG8_SA(b, h) + aoff + m * 2048 + k * 1024); } while (0)
; #define PG8_LDB(dst, b, h) do { _Pragma("unroll") for (int n = 0; n < 2; ++n) _Pragma("unroll") for (int k = 0; k < 2; ++k) dst[n][k] = *(const PG8_LAS bf16x8*)(lds + PG8_SB(b, h) + boff + n * 2048 + k * 1024); } while (0)
; #define PG8_MMA(ai, bj, At, Bt) do { __builtin_amdgcn_s_setprio(1); _Pragma("unroll") for (int m = 0; m < 4; ++m) _Pragma("unroll") for (int n = 0; n < 2; ++n) _Pragma("unroll") for (int k = 0; k < 2; ++k) \
;         acc[ai][bj][m][n] = __builtin_amdgcn_mfma_f32_16x16x32_bf16(Bt[n][k], At[m][k], acc[ai][bj][m][n], 0, 0, 0); __builtin_amdgcn_s_setprio(0); } while (0)
; #define PG8_WAIT_V(n) asm volatile("s_waitcnt vmcnt(" #n ")" ::: "memory")
; #define PG8_WAIT_L(n) asm volatile("s_waitcnt lgkmcnt(" #n ")" ::: "memory")
; #define PG8_BAR __builtin_amdgcn_s_barrier()
; #define PG8_SCHED __builtin_amdgcn_sched_barrier(0)
; template <class Epi, class Sched, bool ALIGN_EPI = false, bool SP2 = false>
; __device__ __forceinline__ void gemm_phase(PG8_LAS unsigned char* lds, const Gemm g, const Sched& S, const Epi& E) {
;     ...
;         for (int t = 0; t < nt; t += 2) {
;             const bool last = (t == nt - 2);
;             const char* a1 = cA + (size_t)(t + 1) * kstep;
;             const char* a2 = last ? nA : cA + (size_t)(t + 2) * kstep; const char* b2 = last ? nB : cB + (size_t)(t + 2) * kstep;
;     ...
;             PG8_LDB(B0, 1, 0); PG8_LDB(B1, 1, 1); PG8_SCHED; PG8_LDA(At, 1, 0); PG8_STAGE(PG8_SA(0, 1), a2 + hstep, voffA);
;             PG8_WAIT_V(8); PG8_WAIT_L(0); PG8_BAR; PG8_MMA(0, 0, At, B0); PG8_MMA(0, 1, At, B1); PG8_BAR; PG8_SCHED;
;             PG8_LDA(At, 1, 1); PG8_STAGE(PG8_SB(1, 0), b3, voffB); PG8_STAGE(PG8_SB(1, 1), b3 + hstep, voffB); PG8_STAGE(PG8_SA(1, 0), a3, voffA);
;             PG8_WAIT_V(8); PG8_WAIT_L(0); PG8_BAR; PG8_MMA(1, 0, At, B0); PG8_MMA(1, 1, At, B1); PG8_BAR; PG8_SCHED;
	s_setprio 0
	s_add_i32 s53, 0, 0x18000
	s_add_i32 s62, 0, 0x1c000
	ds_read_b128 v[146:149], v198 offset:32768
	ds_read_b128 v[150:153], v198 offset:33792
	ds_read_b128 v[154:157], v198 offset:34816
	ds_read_b128 v[158:161], v198 offset:35840
	ds_read_b128 v[162:165], v198 offset:49152
	ds_read_b128 v[166:169], v198 offset:50176
	ds_read_b128 v[170:173], v198 offset:51200
	ds_read_b128 v[174:177], v198 offset:52224
	s_add_u32 s26, s26, 0x40000
	s_addc_u32 s27, s27, 0
	s_mov_b32 m0, s55
	ds_read_b128 v[178:181], v145 offset:32768
	ds_read_b128 v[182:185], v145 offset:33792
	ds_read_b128 v[186:189], v145 offset:34816
	ds_read_b128 v[190:193], v145 offset:35840
	ds_read_b128 v[194:197], v145 offset:36864
	ds_read_b128 v[214:217], v145 offset:37888
	ds_read_b128 v[218:221], v145 offset:38912
	ds_read_b128 v[234:237], v145 offset:39936
	global_load_lds_dwordx4 v136, s[26:27]
	s_mov_b32 m0, s56
	s_nop 0
	global_load_lds_dwordx4 v134, s[26:27]
	s_waitcnt vmcnt(8)
	s_waitcnt lgkmcnt(0)
	s_setprio 1
	s_barrier
	v_mfma_f32_16x16x32_bf16 v[128:131], v[146:149], v[178:181], v[128:131]
	v_mfma_f32_16x16x32_bf16 v[128:131], v[150:153], v[182:185], v[128:131]
	v_mfma_f32_16x16x32_bf16 v[124:127], v[154:157], v[178:181], v[124:127]
	v_mfma_f32_16x16x32_bf16 v[124:127], v[158:161], v[182:185], v[124:127]
	v_mfma_f32_16x16x32_bf16 v[116:119], v[154:157], v[186:189], v[116:119]
	v_mfma_f32_16x16x32_bf16 v[116:119], v[158:161], v[190:193], v[116:119]
	v_mfma_f32_16x16x32_bf16 v[120:123], v[146:149], v[186:189], v[120:123]
	v_mfma_f32_16x16x32_bf16 v[120:123], v[150:153], v[190:193], v[120:123]
	v_mfma_f32_16x16x32_bf16 v[104:107], v[146:149], v[194:197], v[104:107]
	v_mfma_f32_16x16x32_bf16 v[104:107], v[150:153], v[214:217], v[104:107]
	v_mfma_f32_16x16x32_bf16 v[100:103], v[154:157], v[194:197], v[100:103]
	v_mfma_f32_16x16x32_bf16 v[100:103], v[158:161], v[214:217], v[100:103]
	v_mfma_f32_16x16x32_bf16 v[84:87], v[154:157], v[218:221], v[84:87]
	v_mfma_f32_16x16x32_bf16 v[84:87], v[158:161], v[234:237], v[84:87]
	v_mfma_f32_16x16x32_bf16 v[88:91], v[146:149], v[218:221], v[88:91]
	v_mfma_f32_16x16x32_bf16 v[88:91], v[150:153], v[234:237], v[88:91]
	s_setprio 0
	s_setprio 1
	v_mfma_f32_16x16x32_bf16 v[112:115], v[162:165], v[178:181], v[112:115]
	v_mfma_f32_16x16x32_bf16 v[112:115], v[166:169], v[182:185], v[112:115]
	v_mfma_f32_16x16x32_bf16 v[108:111], v[170:173], v[178:181], v[108:111]
	v_mfma_f32_16x16x32_bf16 v[108:111], v[174:177], v[182:185], v[108:111]
	v_mfma_f32_16x16x32_bf16 v[92:95], v[170:173], v[186:189], v[92:95]
	v_mfma_f32_16x16x32_bf16 v[92:95], v[174:177], v[190:193], v[92:95]
	v_mfma_f32_16x16x32_bf16 v[96:99], v[162:165], v[186:189], v[96:99]
	v_mfma_f32_16x16x32_bf16 v[96:99], v[166:169], v[190:193], v[96:99]
	v_mfma_f32_16x16x32_bf16 v[80:83], v[162:165], v[194:197], v[80:83]
	v_mfma_f32_16x16x32_bf16 v[80:83], v[166:169], v[214:217], v[80:83]
	v_mfma_f32_16x16x32_bf16 v[76:79], v[170:173], v[194:197], v[76:79]
	v_mfma_f32_16x16x32_bf16 v[76:79], v[174:177], v[214:217], v[76:79]
	v_mfma_f32_16x16x32_bf16 v[68:71], v[170:173], v[218:221], v[68:71]
	v_mfma_f32_16x16x32_bf16 v[68:71], v[174:177], v[234:237], v[68:71]
	v_mfma_f32_16x16x32_bf16 v[72:75], v[162:165], v[218:221], v[72:75]
	v_mfma_f32_16x16x32_bf16 v[72:75], v[166:169], v[234:237], v[72:75]
	s_barrier
	s_setprio 0
	s_add_i32 s26, s53, s10
	s_mov_b32 m0, s26
	ds_read_b128 v[178:181], v145 offset:49152
	ds_read_b128 v[182:185], v145 offset:50176
	ds_read_b128 v[186:189], v145 offset:51200
	ds_read_b128 v[190:193], v145 offset:52224
	ds_read_b128 v[194:197], v145 offset:53248
	ds_read_b128 v[214:217], v145 offset:54272
	ds_read_b128 v[218:221], v145 offset:55296
	ds_read_b128 v[234:237], v145 offset:56320
	s_add_u32 s0, s0, 0x80
	s_addc_u32 s1, s1, 0
	global_load_lds_dwordx4 v2, s[0:1]
	s_add_i32 m0, s26, 0x2000
	s_add_i32 s26, s62, s10
	global_load_lds_dwordx4 v132, s[0:1]
	s_add_u32 s0, s0, 0x40000
	s_addc_u32 s1, s1, 0
	s_mov_b32 m0, s26
	s_nop 0
	global_load_lds_dwordx4 v2, s[0:1]
	s_add_i32 m0, s26, 0x2000
	s_nop 0
	global_load_lds_dwordx4 v132, s[0:1]
	s_mov_b32 m0, s57
	s_nop 0
	global_load_lds_dwordx4 v136, s[100:101]
	s_mov_b32 m0, s58
	s_nop 0
	global_load_lds_dwordx4 v134, s[100:101]
	s_waitcnt vmcnt(8)
	s_waitcnt lgkmcnt(0)
	s_setprio 1
	s_barrier
	v_mfma_f32_16x16x32_bf16 v[64:67], v[146:149], v[178:181], v[64:67]
	v_mfma_f32_16x16x32_bf16 v[64:67], v[150:153], v[182:185], v[64:67]
	v_mfma_f32_16x16x32_bf16 v[60:63], v[154:157], v[178:181], v[60:63]
	v_mfma_f32_16x16x32_bf16 v[60:63], v[158:161], v[182:185], v[60:63]
	v_mfma_f32_16x16x32_bf16 v[52:55], v[154:157], v[186:189], v[52:55]
	v_mfma_f32_16x16x32_bf16 v[52:55], v[158:161], v[190:193], v[52:55]
	v_mfma_f32_16x16x32_bf16 v[56:59], v[146:149], v[186:189], v[56:59]
	v_mfma_f32_16x16x32_bf16 v[56:59], v[150:153], v[190:193], v[56:59]
	v_mfma_f32_16x16x32_bf16 v[40:43], v[146:149], v[194:197], v[40:43]
	v_mfma_f32_16x16x32_bf16 v[40:43], v[150:153], v[214:217], v[40:43]
	v_mfma_f32_16x16x32_bf16 v[36:39], v[154:157], v[194:197], v[36:39]
	v_mfma_f32_16x16x32_bf16 v[36:39], v[158:161], v[214:217], v[36:39]
	v_mfma_f32_16x16x32_bf16 v[20:23], v[154:157], v[218:221], v[20:23]
	v_mfma_f32_16x16x32_bf16 v[20:23], v[158:161], v[234:237], v[20:23]
	v_mfma_f32_16x16x32_bf16 v[24:27], v[146:149], v[218:221], v[24:27]
	v_mfma_f32_16x16x32_bf16 v[24:27], v[150:153], v[234:237], v[24:27]
	s_setprio 0
	s_setprio 1
	v_mfma_f32_16x16x32_bf16 v[48:51], v[162:165], v[178:181], v[48:51]
	v_mfma_f32_16x16x32_bf16 v[48:51], v[166:169], v[182:185], v[48:51]
	v_mfma_f32_16x16x32_bf16 v[44:47], v[170:173], v[178:181], v[44:47]
	v_mfma_f32_16x16x32_bf16 v[44:47], v[174:177], v[182:185], v[44:47]
	v_mfma_f32_16x16x32_bf16 v[28:31], v[170:173], v[186:189], v[28:31]
	v_mfma_f32_16x16x32_bf16 v[28:31], v[174:177], v[190:193], v[28:31]
	v_mfma_f32_16x16x32_bf16 v[32:35], v[162:165], v[186:189], v[32:35]
	v_mfma_f32_16x16x32_bf16 v[32:35], v[166:169], v[190:193], v[32:35]
	v_mfma_f32_16x16x32_bf16 v[16:19], v[162:165], v[194:197], v[16:19]
	v_mfma_f32_16x16x32_bf16 v[16:19], v[166:169], v[214:217], v[16:19]
	v_mfma_f32_16x16x32_bf16 v[12:15], v[170:173], v[194:197], v[12:15]
	v_mfma_f32_16x16x32_bf16 v[12:15], v[174:177], v[214:217], v[12:15]
	v_mfma_f32_16x16x32_bf16 v[4:7], v[170:173], v[218:221], v[4:7]
	v_mfma_f32_16x16x32_bf16 v[4:7], v[174:177], v[234:237], v[4:7]
	v_mfma_f32_16x16x32_bf16 v[8:11], v[162:165], v[218:221], v[8:11]
	v_mfma_f32_16x16x32_bf16 v[8:11], v[166:169], v[234:237], v[8:11]
	s_barrier
	s_setprio 0
	s_add_i32 s52, s52, 2
	s_add_u32 s50, s50, 0x100
	s_addc_u32 s51, s51, 0
	s_add_u32 s43, s43, 0x100
	s_addc_u32 s45, s45, 0
	s_cmp_gt_u32 s52, 13
	s_cbranch_scc0 .LBB0_1032
	s_and_b64 vcc, exec, s[40:41]
	s_cbranch_vccz .LBB0_1035
	s_barrier

; #define PG8_STAGE(bufoff, gbase, voff) do { _Pragma("unroll") for (int _i = 0; _i < 2; ++_i) \
;         __builtin_amdgcn_global_load_lds((const unsigned*)((const char*)(gbase) + (voff)[_i]), (PG8_LAS unsigned*)(lds + (bufoff) + ldsw + _i * 8192), 16, 0, 0); } while (0)
; #define PG8_LDA(dst, b, h) do { _Pragma("unroll") for (int m = 0; m < 4; ++m) _Pragma("unroll") for (int k = 0; k < 2; ++k) dst[m][k] = *(const PG8_LAS bf16x8*)(lds + PG8_SA(b, h) + aoff + m * 2048 + k * 1024); } while (0)
; #define PG8_LDB(dst, b, h) do { _Pragma("unroll") for (int n = 0; n < 2; ++n) _Pragma("unroll") for (int k = 0; k < 2; ++k) dst[n][k] = *(const PG8_LAS bf16x8*)(lds + PG8_SB(b, h) + boff + n * 2048 + k * 1024); } while (0)
; #define PG8_MMA(ai, bj, At, Bt) do { __builtin_amdgcn_s_setprio(1); _Pragma("unroll") for (int m = 0; m < 4; ++m) _Pragma("unroll") for (int n = 0; n < 2; ++n) _Pragma("unroll") for (int k = 0; k < 2; ++k) \
;         acc[ai][bj][m][n] = __builtin_amdgcn_mfma_f32_16x16x32_bf16(Bt[n][k], At[m][k], acc[ai][bj][m][n], 0, 0, 0); __builtin_amdgcn_s_setprio(0); } while (0)
; #define PG8_WAIT_V(n) asm volatile("s_waitcnt vmcnt(" #n ")" ::: "memory")
; #define PG8_WAIT_L(n) asm volatile("s_waitcnt lgkmcnt(" #n ")" ::: "memory")
; template <class Epi, class Sched, bool ALIGN_EPI = false, bool SP2 = false>
; __device__ __forceinline__ void gemm_phase(PG8_LAS unsigned char* lds, const Gemm g, const Sched& S, const Epi& E) {
;     ...
;             const bool last = (t == nt - 2);
;             const char* a1 = cA + (size_t)(t + 1) * kstep;
;             const char* a2 = last ? nA : cA + (size_t)(t + 2) * kstep; const char* b2 = last ? nB : cB + (size_t)(t + 2) * kstep;
;             const char* a3 = a2 + kstep; const char* b3 = b2 + kstep;
;             if (last && has_next) S.a_ready(nxt);
;             if constexpr (SP2) {
;             PG8_LDB(B0, 0, 0); PG8_LDB(B1, 0, 1); PG8_SCHED; PG8_LDA(At, 0, 0); PG8_STAGE(PG8_SA(1, 1), a1 + hstep, voffA);
;             PG8_WAIT_V(8); PG8_WAIT_L(0); PG8_BAR; PG8_MMA(0, 0, At, B0); PG8_MMA(0, 1, At, B1); PG8_BAR; PG8_SCHED;
;             PG8_LDA(At, 0, 1); PG8_STAGE(PG8_SB(0, 0), b2, voffB); PG8_STAGE(PG8_SB(0, 1), b2 + hstep, voffB); PG8_STAGE(PG8_SA(0, 0), a2, voffA);
;             PG8_WAIT_V(8); PG8_WAIT_L(0); PG8_BAR; PG8_MMA(1, 0, At, B0); PG8_MMA(1, 1, At, B1); PG8_BAR; PG8_SCHED;
.LBB0_1051:
	s_add_u32 s0, s52, 0xfffe0080
	s_addc_u32 s1, s53, -1
	s_add_i32 s63, 0, 0x10000
	s_cmp_eq_u32 s62, 4
	s_cselect_b32 s27, s45, s1
	s_cselect_b32 s26, s58, s0
	s_cselect_b32 s1, s43, s61
	s_cselect_b32 s0, s59, s60
	s_add_i32 s66, 0, 0x14000
	ds_read_b128 v[84:87], v154
	ds_read_b128 v[88:91], v154 offset:1024
	ds_read_b128 v[162:165], v154 offset:2048
	ds_read_b128 v[166:169], v154 offset:3072
	ds_read_b128 v[170:173], v154 offset:16384
	ds_read_b128 v[174:177], v154 offset:17408
	ds_read_b128 v[178:181], v154 offset:18432
	ds_read_b128 v[182:185], v154 offset:19456
	s_add_i32 m0, s10, 0xc000
	ds_read_b128 v[186:189], v160
	ds_read_b128 v[190:193], v160 offset:1024
	ds_read_b128 v[194:197], v160 offset:2048
	ds_read_b128 v[214:217], v160 offset:3072
	ds_read_b128 v[218:221], v160 offset:4096
	ds_read_b128 v[234:237], v160 offset:5120
	ds_read_b128 v[238:241], v160 offset:6144
	ds_read_b128 v[242:245], v160 offset:7168
	global_load_lds_dwordx4 v150, s[52:53]
	s_add_i32 m0, s10, 0xe000
	s_nop 0
	global_load_lds_dwordx4 v152, s[52:53]
	s_waitcnt vmcnt(8)
	s_waitcnt lgkmcnt(0)
	s_setprio 1
	s_barrier
	v_mfma_f32_16x16x32_bf16 v[136:139], v[84:87], v[186:189], v[136:139]
	v_mfma_f32_16x16x32_bf16 v[136:139], v[88:91], v[190:193], v[136:139]
	v_mfma_f32_16x16x32_bf16 v[132:135], v[162:165], v[186:189], v[132:135]
	v_mfma_f32_16x16x32_bf16 v[132:135], v[166:169], v[190:193], v[132:135]
	v_mfma_f32_16x16x32_bf16 v[120:123], v[162:165], v[194:197], v[120:123]
	v_mfma_f32_16x16x32_bf16 v[120:123], v[166:169], v[214:217], v[120:123]
	v_mfma_f32_16x16x32_bf16 v[128:131], v[84:87], v[194:197], v[128:131]
	v_mfma_f32_16x16x32_bf16 v[128:131], v[88:91], v[214:217], v[128:131]
	v_mfma_f32_16x16x32_bf16 v[104:107], v[84:87], v[218:221], v[104:107]
	v_mfma_f32_16x16x32_bf16 v[104:107], v[88:91], v[234:237], v[104:107]
	v_mfma_f32_16x16x32_bf16 v[100:103], v[162:165], v[218:221], v[100:103]
	v_mfma_f32_16x16x32_bf16 v[100:103], v[166:169], v[234:237], v[100:103]
	v_mfma_f32_16x16x32_bf16 v[76:79], v[162:165], v[238:241], v[76:79]
	v_mfma_f32_16x16x32_bf16 v[76:79], v[166:169], v[242:245], v[76:79]
	v_mfma_f32_16x16x32_bf16 v[80:83], v[84:87], v[238:241], v[80:83]
	v_mfma_f32_16x16x32_bf16 v[80:83], v[88:91], v[242:245], v[80:83]
	s_setprio 0
	s_setprio 1
	v_mfma_f32_16x16x32_bf16 v[124:127], v[170:173], v[186:189], v[124:127]
	v_mfma_f32_16x16x32_bf16 v[124:127], v[174:177], v[190:193], v[124:127]
	v_mfma_f32_16x16x32_bf16 v[116:119], v[178:181], v[186:189], v[116:119]
	v_mfma_f32_16x16x32_bf16 v[116:119], v[182:185], v[190:193], v[116:119]
	v_mfma_f32_16x16x32_bf16 v[108:111], v[178:181], v[194:197], v[108:111]
	v_mfma_f32_16x16x32_bf16 v[108:111], v[182:185], v[214:217], v[108:111]
	v_mfma_f32_16x16x32_bf16 v[112:115], v[170:173], v[194:197], v[112:115]
	v_mfma_f32_16x16x32_bf16 v[112:115], v[174:177], v[214:217], v[112:115]
	v_mfma_f32_16x16x32_bf16 v[96:99], v[170:173], v[218:221], v[96:99]
	v_mfma_f32_16x16x32_bf16 v[96:99], v[174:177], v[234:237], v[96:99]
	v_mfma_f32_16x16x32_bf16 v[92:95], v[178:181], v[218:221], v[92:95]
	v_mfma_f32_16x16x32_bf16 v[92:95], v[182:185], v[234:237], v[92:95]
	v_mfma_f32_16x16x32_bf16 v[68:71], v[178:181], v[238:241], v[68:71]
	v_mfma_f32_16x16x32_bf16 v[68:71], v[182:185], v[242:245], v[68:71]
	v_mfma_f32_16x16x32_bf16 v[72:75], v[170:173], v[238:241], v[72:75]
	v_mfma_f32_16x16x32_bf16 v[72:75], v[174:177], v[242:245], v[72:75]
	s_barrier
	s_setprio 0
	s_add_i32 s63, s63, s9
	s_mov_b32 m0, s63
	ds_read_b128 v[186:189], v160 offset:16384
	ds_read_b128 v[190:193], v160 offset:17408
	ds_read_b128 v[194:197], v160 offset:18432
	ds_read_b128 v[214:217], v160 offset:19456
	ds_read_b128 v[218:221], v160 offset:20480
	ds_read_b128 v[234:237], v160 offset:21504
	ds_read_b128 v[238:241], v160 offset:22528
	ds_read_b128 v[242:245], v160 offset:23552
	global_load_lds_dwordx4 v2, s[0:1]
	s_add_i32 m0, s63, 0x2000
	s_add_u32 s64, s0, 0x20000
	s_addc_u32 s65, s1, 0
	s_add_i32 s63, s66, s9
	global_load_lds_dwordx4 v144, s[0:1]
	s_mov_b32 m0, s63
	s_nop 0
	global_load_lds_dwordx4 v2, s[64:65]
	s_add_i32 m0, s63, 0x2000
	s_nop 0
	global_load_lds_dwordx4 v144, s[64:65]
	s_mov_b32 m0, s10
	s_nop 0
	global_load_lds_dwordx4 v140, s[26:27]
	s_mov_b32 m0, s11
	s_nop 0
	global_load_lds_dwordx4 v142, s[26:27]
	s_add_u32 s100, s26, 0x80
	s_addc_u32 s101, s27, 0
	s_waitcnt vmcnt(8)
	s_waitcnt lgkmcnt(0)
	s_setprio 1
	s_barrier
	v_mfma_f32_16x16x32_bf16 v[64:67], v[84:87], v[186:189], v[64:67]
	v_mfma_f32_16x16x32_bf16 v[64:67], v[88:91], v[190:193], v[64:67]
	v_mfma_f32_16x16x32_bf16 v[60:63], v[162:165], v[186:189], v[60:63]
	v_mfma_f32_16x16x32_bf16 v[60:63], v[166:169], v[190:193], v[60:63]
	v_mfma_f32_16x16x32_bf16 v[44:47], v[162:165], v[194:197], v[44:47]
	v_mfma_f32_16x16x32_bf16 v[44:47], v[166:169], v[214:217], v[44:47]
	v_mfma_f32_16x16x32_bf16 v[48:51], v[84:87], v[194:197], v[48:51]
	v_mfma_f32_16x16x32_bf16 v[48:51], v[88:91], v[214:217], v[48:51]
	v_mfma_f32_16x16x32_bf16 v[32:35], v[84:87], v[218:221], v[32:35]
	v_mfma_f32_16x16x32_bf16 v[32:35], v[88:91], v[234:237], v[32:35]
	v_mfma_f32_16x16x32_bf16 v[28:31], v[162:165], v[218:221], v[28:31]
	v_mfma_f32_16x16x32_bf16 v[28:31], v[166:169], v[234:237], v[28:31]
	v_mfma_f32_16x16x32_bf16 v[12:15], v[162:165], v[238:241], v[12:15]
	v_mfma_f32_16x16x32_bf16 v[12:15], v[166:169], v[242:245], v[12:15]
	v_mfma_f32_16x16x32_bf16 v[16:19], v[84:87], v[238:241], v[16:19]
	v_mfma_f32_16x16x32_bf16 v[16:19], v[88:91], v[242:245], v[16:19]
	s_setprio 0
	s_setprio 1
	v_mfma_f32_16x16x32_bf16 v[56:59], v[170:173], v[186:189], v[56:59]
	v_mfma_f32_16x16x32_bf16 v[56:59], v[174:177], v[190:193], v[56:59]
	v_mfma_f32_16x16x32_bf16 v[52:55], v[178:181], v[186:189], v[52:55]
	v_mfma_f32_16x16x32_bf16 v[52:55], v[182:185], v[190:193], v[52:55]
	v_mfma_f32_16x16x32_bf16 v[36:39], v[178:181], v[194:197], v[36:39]
	v_mfma_f32_16x16x32_bf16 v[36:39], v[182:185], v[214:217], v[36:39]
	v_mfma_f32_16x16x32_bf16 v[40:43], v[170:173], v[194:197], v[40:43]
	v_mfma_f32_16x16x32_bf16 v[40:43], v[174:177], v[214:217], v[40:43]
	v_mfma_f32_16x16x32_bf16 v[24:27], v[170:173], v[218:221], v[24:27]
	v_mfma_f32_16x16x32_bf16 v[24:27], v[174:177], v[234:237], v[24:27]
	v_mfma_f32_16x16x32_bf16 v[20:23], v[178:181], v[218:221], v[20:23]
	v_mfma_f32_16x16x32_bf16 v[20:23], v[182:185], v[234:237], v[20:23]
	v_mfma_f32_16x16x32_bf16 v[4:7], v[178:181], v[238:241], v[4:7]
	v_mfma_f32_16x16x32_bf16 v[4:7], v[182:185], v[242:245], v[4:7]
	v_mfma_f32_16x16x32_bf16 v[8:11], v[170:173], v[238:241], v[8:11]
	v_mfma_f32_16x16x32_bf16 v[8:11], v[174:177], v[242:245], v[8:11]
	s_barrier
; #define PG8_STAGE(bufoff, gbase, voff) do { _Pragma("unroll") for (int _i = 0; _i < 2; ++_i) \
;         __builtin_amdgcn_global_load_lds((const unsigned*)((const char*)(gbase) + (voff)[_i]), (PG8_LAS unsigned*)(lds + (bufoff) + ldsw + _i * 8192), 16, 0, 0); } while (0)
; #define PG8_LDA(dst, b, h) do { _Pragma("unroll") for (int m = 0; m < 4; ++m) _Pragma("unroll") for (int k = 0; k < 2; ++k) dst[m][k] = *(const PG8_LAS bf16x8*)(lds + PG8_SA(b, h) + aoff + m * 2048 + k * 1024); } while (0)
; #define PG8_LDB(dst, b, h) do { _Pragma("unroll") for (int n = 0; n < 2; ++n) _Pragma("unroll") for (int k = 0; k < 2; ++k) dst[n][k] = *(const PG8_LAS bf16x8*)(lds + PG8_SB(b, h) + boff + n * 2048 + k * 1024); } while (0)
; #define PG8_MMA(ai, bj, At, Bt) do { __builtin_amdgcn_s_setprio(1); _Pragma("unroll") for (int m = 0; m < 4; ++m) _Pragma("unroll") for (int n = 0; n < 2; ++n) _Pragma("unroll") for (int k = 0; k < 2; ++k) \
;         acc[ai][bj][m][n] = __builtin_amdgcn_mfma_f32_16x16x32_bf16(Bt[n][k], At[m][k], acc[ai][bj][m][n], 0, 0, 0); __builtin_amdgcn_s_setprio(0); } while (0)
; #define PG8_WAIT_V(n) asm volatile("s_waitcnt vmcnt(" #n ")" ::: "memory")
; #define PG8_WAIT_L(n) asm volatile("s_waitcnt lgkmcnt(" #n ")" ::: "memory")
; #define PG8_BAR __builtin_amdgcn_s_barrier()
; #define PG8_SCHED __builtin_amdgcn_sched_barrier(0)
; template <class Epi, class Sched, bool ALIGN_EPI = false, bool SP2 = false>
; __device__ __forceinline__ void gemm_phase(PG8_LAS unsigned char* lds, const Gemm g, const Sched& S, const Epi& E) {
;     ...
;         for (int t = 0; t < nt; t += 2) {
;             const bool last = (t == nt - 2);
;             const char* a1 = cA + (size_t)(t + 1) * kstep;
;             const char* a2 = last ? nA : cA + (size_t)(t + 2) * kstep; const char* b2 = last ? nB : cB + (size_t)(t + 2) * kstep;
;     ...
;             PG8_LDB(B0, 1, 0); PG8_LDB(B1, 1, 1); PG8_SCHED; PG8_LDA(At, 1, 0); PG8_STAGE(PG8_SA(0, 1), a2 + hstep, voffA);
;             PG8_WAIT_V(8); PG8_WAIT_L(0); PG8_BAR; PG8_MMA(0, 0, At, B0); PG8_MMA(0, 1, At, B1); PG8_BAR; PG8_SCHED;
;             PG8_LDA(At, 1, 1); PG8_STAGE(PG8_SB(1, 0), b3, voffB); PG8_STAGE(PG8_SB(1, 1), b3 + hstep, voffB); PG8_STAGE(PG8_SA(1, 0), a3, voffA);
;             PG8_WAIT_V(8); PG8_WAIT_L(0); PG8_BAR; PG8_MMA(1, 0, At, B0); PG8_MMA(1, 1, At, B1); PG8_BAR; PG8_SCHED;
	s_setprio 0
	s_add_i32 s63, 0, 0x18000
	s_add_i32 s64, 0, 0x1c000
	ds_read_b128 v[84:87], v154 offset:32768
	ds_read_b128 v[88:91], v154 offset:33792
	ds_read_b128 v[162:165], v154 offset:34816
	ds_read_b128 v[166:169], v154 offset:35840
	ds_read_b128 v[170:173], v154 offset:49152
	ds_read_b128 v[174:177], v154 offset:50176
	ds_read_b128 v[178:181], v154 offset:51200
	ds_read_b128 v[182:185], v154 offset:52224
	s_add_u32 s26, s26, 0x20000
	s_addc_u32 s27, s27, 0
	s_mov_b32 m0, s25
	ds_read_b128 v[186:189], v160 offset:32768
	ds_read_b128 v[190:193], v160 offset:33792
	ds_read_b128 v[194:197], v160 offset:34816
	ds_read_b128 v[214:217], v160 offset:35840
	ds_read_b128 v[218:221], v160 offset:36864
	ds_read_b128 v[234:237], v160 offset:37888
	ds_read_b128 v[238:241], v160 offset:38912
	ds_read_b128 v[242:245], v160 offset:39936
	global_load_lds_dwordx4 v140, s[26:27]
	s_mov_b32 m0, s51
	s_nop 0
	global_load_lds_dwordx4 v142, s[26:27]
	s_waitcnt vmcnt(8)
	s_waitcnt lgkmcnt(0)
	s_setprio 1
	s_barrier
	v_mfma_f32_16x16x32_bf16 v[136:139], v[84:87], v[186:189], v[136:139]
	v_mfma_f32_16x16x32_bf16 v[136:139], v[88:91], v[190:193], v[136:139]
	v_mfma_f32_16x16x32_bf16 v[132:135], v[162:165], v[186:189], v[132:135]
	v_mfma_f32_16x16x32_bf16 v[132:135], v[166:169], v[190:193], v[132:135]
	v_mfma_f32_16x16x32_bf16 v[120:123], v[162:165], v[194:197], v[120:123]
	v_mfma_f32_16x16x32_bf16 v[120:123], v[166:169], v[214:217], v[120:123]
	v_mfma_f32_16x16x32_bf16 v[128:131], v[84:87], v[194:197], v[128:131]
	v_mfma_f32_16x16x32_bf16 v[128:131], v[88:91], v[214:217], v[128:131]
	v_mfma_f32_16x16x32_bf16 v[104:107], v[84:87], v[218:221], v[104:107]
	v_mfma_f32_16x16x32_bf16 v[104:107], v[88:91], v[234:237], v[104:107]
	v_mfma_f32_16x16x32_bf16 v[100:103], v[162:165], v[218:221], v[100:103]
	v_mfma_f32_16x16x32_bf16 v[100:103], v[166:169], v[234:237], v[100:103]
	v_mfma_f32_16x16x32_bf16 v[76:79], v[162:165], v[238:241], v[76:79]
	v_mfma_f32_16x16x32_bf16 v[76:79], v[166:169], v[242:245], v[76:79]
	v_mfma_f32_16x16x32_bf16 v[80:83], v[84:87], v[238:241], v[80:83]
	v_mfma_f32_16x16x32_bf16 v[80:83], v[88:91], v[242:245], v[80:83]
	s_setprio 0
	s_setprio 1
	v_mfma_f32_16x16x32_bf16 v[124:127], v[170:173], v[186:189], v[124:127]
	v_mfma_f32_16x16x32_bf16 v[124:127], v[174:177], v[190:193], v[124:127]
	v_mfma_f32_16x16x32_bf16 v[116:119], v[178:181], v[186:189], v[116:119]
	v_mfma_f32_16x16x32_bf16 v[116:119], v[182:185], v[190:193], v[116:119]
	v_mfma_f32_16x16x32_bf16 v[108:111], v[178:181], v[194:197], v[108:111]
	v_mfma_f32_16x16x32_bf16 v[108:111], v[182:185], v[214:217], v[108:111]
	v_mfma_f32_16x16x32_bf16 v[112:115], v[170:173], v[194:197], v[112:115]
	v_mfma_f32_16x16x32_bf16 v[112:115], v[174:177], v[214:217], v[112:115]
	v_mfma_f32_16x16x32_bf16 v[96:99], v[170:173], v[218:221], v[96:99]
	v_mfma_f32_16x16x32_bf16 v[96:99], v[174:177], v[234:237], v[96:99]
	v_mfma_f32_16x16x32_bf16 v[92:95], v[178:181], v[218:221], v[92:95]
	v_mfma_f32_16x16x32_bf16 v[92:95], v[182:185], v[234:237], v[92:95]
	v_mfma_f32_16x16x32_bf16 v[68:71], v[178:181], v[238:241], v[68:71]
	v_mfma_f32_16x16x32_bf16 v[68:71], v[182:185], v[242:245], v[68:71]
	v_mfma_f32_16x16x32_bf16 v[72:75], v[170:173], v[238:241], v[72:75]
	v_mfma_f32_16x16x32_bf16 v[72:75], v[174:177], v[242:245], v[72:75]
	s_barrier
	s_setprio 0
	s_add_i32 s26, s63, s9
	s_mov_b32 m0, s26
	ds_read_b128 v[186:189], v160 offset:49152
	ds_read_b128 v[190:193], v160 offset:50176
	ds_read_b128 v[194:197], v160 offset:51200
	ds_read_b128 v[214:217], v160 offset:52224
	ds_read_b128 v[218:221], v160 offset:53248
	ds_read_b128 v[234:237], v160 offset:54272
	ds_read_b128 v[238:241], v160 offset:55296
	ds_read_b128 v[242:245], v160 offset:56320
	s_add_u32 s0, s0, 0x80
	s_addc_u32 s1, s1, 0
	global_load_lds_dwordx4 v2, s[0:1]
	s_add_i32 m0, s26, 0x2000
	s_add_i32 s26, s64, s9
	global_load_lds_dwordx4 v144, s[0:1]
	s_add_u32 s0, s0, 0x20000
	s_addc_u32 s1, s1, 0
	s_mov_b32 m0, s26
	s_nop 0
	global_load_lds_dwordx4 v2, s[0:1]
	s_add_i32 m0, s26, 0x2000
	s_nop 0
	global_load_lds_dwordx4 v144, s[0:1]
	s_mov_b32 m0, s54
	s_nop 0
	global_load_lds_dwordx4 v140, s[100:101]
	s_mov_b32 m0, s55
	s_nop 0
	global_load_lds_dwordx4 v142, s[100:101]
	s_waitcnt vmcnt(8)
	s_waitcnt lgkmcnt(0)
	s_setprio 1
	s_barrier
	v_mfma_f32_16x16x32_bf16 v[64:67], v[84:87], v[186:189], v[64:67]
	v_mfma_f32_16x16x32_bf16 v[64:67], v[88:91], v[190:193], v[64:67]
	v_mfma_f32_16x16x32_bf16 v[60:63], v[162:165], v[186:189], v[60:63]
	v_mfma_f32_16x16x32_bf16 v[60:63], v[166:169], v[190:193], v[60:63]
	v_mfma_f32_16x16x32_bf16 v[44:47], v[162:165], v[194:197], v[44:47]
	v_mfma_f32_16x16x32_bf16 v[44:47], v[166:169], v[214:217], v[44:47]
	v_mfma_f32_16x16x32_bf16 v[48:51], v[84:87], v[194:197], v[48:51]
	v_mfma_f32_16x16x32_bf16 v[48:51], v[88:91], v[214:217], v[48:51]
	v_mfma_f32_16x16x32_bf16 v[32:35], v[84:87], v[218:221], v[32:35]
	v_mfma_f32_16x16x32_bf16 v[32:35], v[88:91], v[234:237], v[32:35]
	v_mfma_f32_16x16x32_bf16 v[28:31], v[162:165], v[218:221], v[28:31]
	v_mfma_f32_16x16x32_bf16 v[28:31], v[166:169], v[234:237], v[28:31]
	v_mfma_f32_16x16x32_bf16 v[12:15], v[162:165], v[238:241], v[12:15]
	v_mfma_f32_16x16x32_bf16 v[12:15], v[166:169], v[242:245], v[12:15]
	v_mfma_f32_16x16x32_bf16 v[16:19], v[84:87], v[238:241], v[16:19]
	v_mfma_f32_16x16x32_bf16 v[16:19], v[88:91], v[242:245], v[16:19]
	s_setprio 0
	s_setprio 1
	v_mfma_f32_16x16x32_bf16 v[56:59], v[170:173], v[186:189], v[56:59]
	v_mfma_f32_16x16x32_bf16 v[56:59], v[174:177], v[190:193], v[56:59]
	v_mfma_f32_16x16x32_bf16 v[52:55], v[178:181], v[186:189], v[52:55]
	v_mfma_f32_16x16x32_bf16 v[52:55], v[182:185], v[190:193], v[52:55]
	v_mfma_f32_16x16x32_bf16 v[36:39], v[178:181], v[194:197], v[36:39]
	v_mfma_f32_16x16x32_bf16 v[36:39], v[182:185], v[214:217], v[36:39]
	v_mfma_f32_16x16x32_bf16 v[40:43], v[170:173], v[194:197], v[40:43]
	v_mfma_f32_16x16x32_bf16 v[40:43], v[174:177], v[214:217], v[40:43]
	v_mfma_f32_16x16x32_bf16 v[24:27], v[170:173], v[218:221], v[24:27]
	v_mfma_f32_16x16x32_bf16 v[24:27], v[174:177], v[234:237], v[24:27]
	v_mfma_f32_16x16x32_bf16 v[20:23], v[178:181], v[218:221], v[20:23]
	v_mfma_f32_16x16x32_bf16 v[20:23], v[182:185], v[234:237], v[20:23]
	v_mfma_f32_16x16x32_bf16 v[4:7], v[178:181], v[238:241], v[4:7]
	v_mfma_f32_16x16x32_bf16 v[4:7], v[182:185], v[242:245], v[4:7]
	v_mfma_f32_16x16x32_bf16 v[8:11], v[170:173], v[238:241], v[8:11]
	v_mfma_f32_16x16x32_bf16 v[8:11], v[174:177], v[242:245], v[8:11]
	s_barrier
	s_setprio 0
	s_add_i32 s62, s62, 2
	s_add_u32 s52, s52, 0x100
	s_addc_u32 s53, s53, 0
	s_add_u32 s60, s60, 0x100
	s_addc_u32 s61, s61, 0
	s_cmp_gt_u32 s62, 5
	s_cbranch_scc0 .LBB0_1051
	s_and_b64 vcc, exec, s[36:37]
	s_cbranch_vccz .LBB0_1054
	s_barrier

; #define PG8_STAGE(bufoff, gbase, voff) do { _Pragma("unroll") for (int _i = 0; _i < 2; ++_i) \
;         __builtin_amdgcn_global_load_lds((const unsigned*)((const char*)(gbase) + (voff)[_i]), (PG8_LAS unsigned*)(lds + (bufoff) + ldsw + _i * 8192), 16, 0, 0); } while (0)
; #define PG8_LDA(dst, b, h) do { _Pragma("unroll") for (int m = 0; m < 4; ++m) _Pragma("unroll") for (int k = 0; k < 2; ++k) dst[m][k] = *(const PG8_LAS bf16x8*)(lds + PG8_SA(b, h) + aoff + m * 2048 + k * 1024); } while (0)
; #define PG8_LDB(dst, b, h) do { _Pragma("unroll") for (int n = 0; n < 2; ++n) _Pragma("unroll") for (int k = 0; k < 2; ++k) dst[n][k] = *(const PG8_LAS bf16x8*)(lds + PG8_SB(b, h) + boff + n * 2048 + k * 1024); } while (0)
; #define PG8_MMA(ai, bj, At, Bt) do { __builtin_amdgcn_s_setprio(1); _Pragma("unroll") for (int m = 0; m < 4; ++m) _Pragma("unroll") for (int n = 0; n < 2; ++n) _Pragma("unroll") for (int k = 0; k < 2; ++k) \
;         acc[ai][bj][m][n] = __builtin_amdgcn_mfma_f32_16x16x32_bf16(Bt[n][k], At[m][k], acc[ai][bj][m][n], 0, 0, 0); __builtin_amdgcn_s_setprio(0); } while (0)
; #define PG8_WAIT_V(n) asm volatile("s_waitcnt vmcnt(" #n ")" ::: "memory")
; #define PG8_WAIT_L(n) asm volatile("s_waitcnt lgkmcnt(" #n ")" ::: "memory")
; template <class Epi, class Sched, bool ALIGN_EPI = false, bool SP2 = false>
; __device__ __forceinline__ void gemm_phase(PG8_LAS unsigned char* lds, const Gemm g, const Sched& S, const Epi& E) {
;     ...
;             const bool last = (t == nt - 2);
;             const char* a1 = cA + (size_t)(t + 1) * kstep;
;             const char* a2 = last ? nA : cA + (size_t)(t + 2) * kstep; const char* b2 = last ? nB : cB + (size_t)(t + 2) * kstep;
;             const char* a3 = a2 + kstep; const char* b3 = b2 + kstep;
;             if (last && has_next) S.a_ready(nxt);
;             if constexpr (SP2) {
;             PG8_LDB(B0, 0, 0); PG8_LDB(B1, 0, 1); PG8_SCHED; PG8_LDA(At, 0, 0); PG8_STAGE(PG8_SA(1, 1), a1 + hstep, voffA);
;             PG8_WAIT_V(8); PG8_WAIT_L(0); PG8_BAR; PG8_MMA(0, 0, At, B0); PG8_MMA(0, 1, At, B1); PG8_BAR; PG8_SCHED;
;             PG8_LDA(At, 0, 1); PG8_STAGE(PG8_SB(0, 0), b2, voffB); PG8_STAGE(PG8_SB(0, 1), b2 + hstep, voffB); PG8_STAGE(PG8_SA(0, 0), a2, voffA);
;             PG8_WAIT_V(8); PG8_WAIT_L(0); PG8_BAR; PG8_MMA(1, 0, At, B0); PG8_MMA(1, 1, At, B1); PG8_BAR; PG8_SCHED;
.LBB0_1624:
	s_add_u32 s0, s56, 0xfff00080
	s_addc_u32 s1, s57, -1
	s_add_i32 s63, 0, 0x10000
	s_cmp_eq_u32 s62, 60
	s_cselect_b32 s27, s51, s1
	s_cselect_b32 s26, s50, s0
	s_cselect_b32 s1, s53, s49
	s_cselect_b32 s0, s52, s47
	s_add_i32 s66, 0, 0x14000
	ds_read_b128 v[142:145], v210
	ds_read_b128 v[150:153], v210 offset:1024
	ds_read_b128 v[154:157], v210 offset:2048
	ds_read_b128 v[158:161], v210 offset:3072
	ds_read_b128 v[162:165], v210 offset:16384
	ds_read_b128 v[166:169], v210 offset:17408
	ds_read_b128 v[170:173], v210 offset:18432
	ds_read_b128 v[174:177], v210 offset:19456
	s_add_i32 m0, s10, 0xc000
	ds_read_b128 v[178:181], v149
	ds_read_b128 v[182:185], v149 offset:1024
	ds_read_b128 v[186:189], v149 offset:2048
	ds_read_b128 v[190:193], v149 offset:3072
	ds_read_b128 v[194:197], v149 offset:4096
	ds_read_b128 v[198:201], v149 offset:5120
	ds_read_b128 v[202:205], v149 offset:6144
	ds_read_b128 v[206:209], v149 offset:7168
	global_load_lds_dwordx4 v138, s[56:57]
	s_add_i32 m0, s10, 0xe000
	s_nop 0
	global_load_lds_dwordx4 v140, s[56:57]
	s_waitcnt vmcnt(8)
	s_waitcnt lgkmcnt(0)
	s_setprio 1
	s_barrier
	v_mfma_f32_16x16x32_bf16 v[128:131], v[142:145], v[178:181], v[128:131]
	v_mfma_f32_16x16x32_bf16 v[128:131], v[150:153], v[182:185], v[128:131]
	v_mfma_f32_16x16x32_bf16 v[124:127], v[154:157], v[178:181], v[124:127]
	v_mfma_f32_16x16x32_bf16 v[124:127], v[158:161], v[182:185], v[124:127]
	v_mfma_f32_16x16x32_bf16 v[108:111], v[154:157], v[186:189], v[108:111]
	v_mfma_f32_16x16x32_bf16 v[108:111], v[158:161], v[190:193], v[108:111]
	v_mfma_f32_16x16x32_bf16 v[112:115], v[142:145], v[186:189], v[112:115]
	v_mfma_f32_16x16x32_bf16 v[112:115], v[150:153], v[190:193], v[112:115]
	v_mfma_f32_16x16x32_bf16 v[96:99], v[142:145], v[194:197], v[96:99]
	v_mfma_f32_16x16x32_bf16 v[96:99], v[150:153], v[198:201], v[96:99]
	v_mfma_f32_16x16x32_bf16 v[92:95], v[154:157], v[194:197], v[92:95]
	v_mfma_f32_16x16x32_bf16 v[92:95], v[158:161], v[198:201], v[92:95]
	v_mfma_f32_16x16x32_bf16 v[76:79], v[154:157], v[202:205], v[76:79]
	v_mfma_f32_16x16x32_bf16 v[76:79], v[158:161], v[206:209], v[76:79]
	v_mfma_f32_16x16x32_bf16 v[80:83], v[142:145], v[202:205], v[80:83]
	v_mfma_f32_16x16x32_bf16 v[80:83], v[150:153], v[206:209], v[80:83]
	s_setprio 0
	s_setprio 1
	v_mfma_f32_16x16x32_bf16 v[120:123], v[162:165], v[178:181], v[120:123]
	v_mfma_f32_16x16x32_bf16 v[120:123], v[166:169], v[182:185], v[120:123]
	v_mfma_f32_16x16x32_bf16 v[116:119], v[170:173], v[178:181], v[116:119]
	v_mfma_f32_16x16x32_bf16 v[116:119], v[174:177], v[182:185], v[116:119]
	v_mfma_f32_16x16x32_bf16 v[100:103], v[170:173], v[186:189], v[100:103]
	v_mfma_f32_16x16x32_bf16 v[100:103], v[174:177], v[190:193], v[100:103]
	v_mfma_f32_16x16x32_bf16 v[104:107], v[162:165], v[186:189], v[104:107]
	v_mfma_f32_16x16x32_bf16 v[104:107], v[166:169], v[190:193], v[104:107]
	v_mfma_f32_16x16x32_bf16 v[88:91], v[162:165], v[194:197], v[88:91]
	v_mfma_f32_16x16x32_bf16 v[88:91], v[166:169], v[198:201], v[88:91]
	v_mfma_f32_16x16x32_bf16 v[84:87], v[170:173], v[194:197], v[84:87]
	v_mfma_f32_16x16x32_bf16 v[84:87], v[174:177], v[198:201], v[84:87]
	v_mfma_f32_16x16x32_bf16 v[68:71], v[170:173], v[202:205], v[68:71]
	v_mfma_f32_16x16x32_bf16 v[68:71], v[174:177], v[206:209], v[68:71]
	v_mfma_f32_16x16x32_bf16 v[72:75], v[162:165], v[202:205], v[72:75]
	v_mfma_f32_16x16x32_bf16 v[72:75], v[166:169], v[206:209], v[72:75]
	s_barrier
	s_setprio 0
	s_add_i32 s63, s63, s9
	s_mov_b32 m0, s63
	ds_read_b128 v[178:181], v149 offset:16384
	ds_read_b128 v[182:185], v149 offset:17408
	ds_read_b128 v[186:189], v149 offset:18432
	ds_read_b128 v[190:193], v149 offset:19456
	ds_read_b128 v[194:197], v149 offset:20480
	ds_read_b128 v[198:201], v149 offset:21504
	ds_read_b128 v[202:205], v149 offset:22528
	ds_read_b128 v[206:209], v149 offset:23552
	global_load_lds_dwordx4 v2, s[0:1]
	s_add_i32 m0, s63, 0x2000
	s_add_u32 s64, s0, 0x100000
	s_addc_u32 s65, s1, 0
	s_add_i32 s63, s66, s9
	global_load_lds_dwordx4 v136, s[0:1]
	s_mov_b32 m0, s63
	s_nop 0
	global_load_lds_dwordx4 v2, s[64:65]
	s_add_i32 m0, s63, 0x2000
	s_nop 0
	global_load_lds_dwordx4 v136, s[64:65]
	s_mov_b32 m0, s10
	s_nop 0
	global_load_lds_dwordx4 v132, s[26:27]
	s_mov_b32 m0, s11
	s_nop 0
	global_load_lds_dwordx4 v134, s[26:27]
	s_add_u32 s100, s26, 0x80
	s_addc_u32 s101, s27, 0
	s_waitcnt vmcnt(8)
	s_waitcnt lgkmcnt(0)
	s_setprio 1
	s_barrier
	v_mfma_f32_16x16x32_bf16 v[64:67], v[142:145], v[178:181], v[64:67]
	v_mfma_f32_16x16x32_bf16 v[64:67], v[150:153], v[182:185], v[64:67]
	v_mfma_f32_16x16x32_bf16 v[60:63], v[154:157], v[178:181], v[60:63]
	v_mfma_f32_16x16x32_bf16 v[60:63], v[158:161], v[182:185], v[60:63]
	v_mfma_f32_16x16x32_bf16 v[44:47], v[154:157], v[186:189], v[44:47]
	v_mfma_f32_16x16x32_bf16 v[44:47], v[158:161], v[190:193], v[44:47]
	v_mfma_f32_16x16x32_bf16 v[48:51], v[142:145], v[186:189], v[48:51]
	v_mfma_f32_16x16x32_bf16 v[48:51], v[150:153], v[190:193], v[48:51]
	v_mfma_f32_16x16x32_bf16 v[32:35], v[142:145], v[194:197], v[32:35]
	v_mfma_f32_16x16x32_bf16 v[32:35], v[150:153], v[198:201], v[32:35]
	v_mfma_f32_16x16x32_bf16 v[28:31], v[154:157], v[194:197], v[28:31]
	v_mfma_f32_16x16x32_bf16 v[28:31], v[158:161], v[198:201], v[28:31]
	v_mfma_f32_16x16x32_bf16 v[12:15], v[154:157], v[202:205], v[12:15]
	v_mfma_f32_16x16x32_bf16 v[12:15], v[158:161], v[206:209], v[12:15]
	v_mfma_f32_16x16x32_bf16 v[16:19], v[142:145], v[202:205], v[16:19]
	v_mfma_f32_16x16x32_bf16 v[16:19], v[150:153], v[206:209], v[16:19]
	s_setprio 0
	s_setprio 1
	v_mfma_f32_16x16x32_bf16 v[56:59], v[162:165], v[178:181], v[56:59]
	v_mfma_f32_16x16x32_bf16 v[56:59], v[166:169], v[182:185], v[56:59]
	v_mfma_f32_16x16x32_bf16 v[52:55], v[170:173], v[178:181], v[52:55]
	v_mfma_f32_16x16x32_bf16 v[52:55], v[174:177], v[182:185], v[52:55]
	v_mfma_f32_16x16x32_bf16 v[36:39], v[170:173], v[186:189], v[36:39]
	v_mfma_f32_16x16x32_bf16 v[36:39], v[174:177], v[190:193], v[36:39]
	v_mfma_f32_16x16x32_bf16 v[40:43], v[162:165], v[186:189], v[40:43]
	v_mfma_f32_16x16x32_bf16 v[40:43], v[166:169], v[190:193], v[40:43]
	v_mfma_f32_16x16x32_bf16 v[24:27], v[162:165], v[194:197], v[24:27]
	v_mfma_f32_16x16x32_bf16 v[24:27], v[166:169], v[198:201], v[24:27]
	v_mfma_f32_16x16x32_bf16 v[20:23], v[170:173], v[194:197], v[20:23]
	v_mfma_f32_16x16x32_bf16 v[20:23], v[174:177], v[198:201], v[20:23]
	v_mfma_f32_16x16x32_bf16 v[4:7], v[170:173], v[202:205], v[4:7]
	v_mfma_f32_16x16x32_bf16 v[4:7], v[174:177], v[206:209], v[4:7]
	v_mfma_f32_16x16x32_bf16 v[8:11], v[162:165], v[202:205], v[8:11]
	v_mfma_f32_16x16x32_bf16 v[8:11], v[166:169], v[206:209], v[8:11]
	s_barrier
; #define PG8_STAGE(bufoff, gbase, voff) do { _Pragma("unroll") for (int _i = 0; _i < 2; ++_i) \
;         __builtin_amdgcn_global_load_lds((const unsigned*)((const char*)(gbase) + (voff)[_i]), (PG8_LAS unsigned*)(lds + (bufoff) + ldsw + _i * 8192), 16, 0, 0); } while (0)
; #define PG8_LDA(dst, b, h) do { _Pragma("unroll") for (int m = 0; m < 4; ++m) _Pragma("unroll") for (int k = 0; k < 2; ++k) dst[m][k] = *(const PG8_LAS bf16x8*)(lds + PG8_SA(b, h) + aoff + m * 2048 + k * 1024); } while (0)
; #define PG8_LDB(dst, b, h) do { _Pragma("unroll") for (int n = 0; n < 2; ++n) _Pragma("unroll") for (int k = 0; k < 2; ++k) dst[n][k] = *(const PG8_LAS bf16x8*)(lds + PG8_SB(b, h) + boff + n * 2048 + k * 1024); } while (0)
; #define PG8_MMA(ai, bj, At, Bt) do { __builtin_amdgcn_s_setprio(1); _Pragma("unroll") for (int m = 0; m < 4; ++m) _Pragma("unroll") for (int n = 0; n < 2; ++n) _Pragma("unroll") for (int k = 0; k < 2; ++k) \
;         acc[ai][bj][m][n] = __builtin_amdgcn_mfma_f32_16x16x32_bf16(Bt[n][k], At[m][k], acc[ai][bj][m][n], 0, 0, 0); __builtin_amdgcn_s_setprio(0); } while (0)
; #define PG8_WAIT_V(n) asm volatile("s_waitcnt vmcnt(" #n ")" ::: "memory")
; #define PG8_WAIT_L(n) asm volatile("s_waitcnt lgkmcnt(" #n ")" ::: "memory")
; #define PG8_BAR __builtin_amdgcn_s_barrier()
; #define PG8_SCHED __builtin_amdgcn_sched_barrier(0)
; template <class Epi, class Sched, bool ALIGN_EPI = false, bool SP2 = false>
; __device__ __forceinline__ void gemm_phase(PG8_LAS unsigned char* lds, const Gemm g, const Sched& S, const Epi& E) {
;     ...
;         for (int t = 0; t < nt; t += 2) {
;             const bool last = (t == nt - 2);
;             const char* a1 = cA + (size_t)(t + 1) * kstep;
;             const char* a2 = last ? nA : cA + (size_t)(t + 2) * kstep; const char* b2 = last ? nB : cB + (size_t)(t + 2) * kstep;
;     ...
;             PG8_LDB(B0, 1, 0); PG8_LDB(B1, 1, 1); PG8_SCHED; PG8_LDA(At, 1, 0); PG8_STAGE(PG8_SA(0, 1), a2 + hstep, voffA);
;             PG8_WAIT_V(8); PG8_WAIT_L(0); PG8_BAR; PG8_MMA(0, 0, At, B0); PG8_MMA(0, 1, At, B1); PG8_BAR; PG8_SCHED;
;             PG8_LDA(At, 1, 1); PG8_STAGE(PG8_SB(1, 0), b3, voffB); PG8_STAGE(PG8_SB(1, 1), b3 + hstep, voffB); PG8_STAGE(PG8_SA(1, 0), a3, voffA);
;             PG8_WAIT_V(8); PG8_WAIT_L(0); PG8_BAR; PG8_MMA(1, 0, At, B0); PG8_MMA(1, 1, At, B1); PG8_BAR; PG8_SCHED;
	s_setprio 0
	s_add_i32 s63, 0, 0x18000
	s_add_i32 s64, 0, 0x1c000
	ds_read_b128 v[142:145], v210 offset:32768
	ds_read_b128 v[150:153], v210 offset:33792
	ds_read_b128 v[154:157], v210 offset:34816
	ds_read_b128 v[158:161], v210 offset:35840
	ds_read_b128 v[162:165], v210 offset:49152
	ds_read_b128 v[166:169], v210 offset:50176
	ds_read_b128 v[170:173], v210 offset:51200
	ds_read_b128 v[174:177], v210 offset:52224
	s_add_u32 s26, s26, 0x100000
	s_addc_u32 s27, s27, 0
	s_mov_b32 m0, s25
	ds_read_b128 v[178:181], v149 offset:32768
	ds_read_b128 v[182:185], v149 offset:33792
	ds_read_b128 v[186:189], v149 offset:34816
	ds_read_b128 v[190:193], v149 offset:35840
	ds_read_b128 v[194:197], v149 offset:36864
	ds_read_b128 v[198:201], v149 offset:37888
	ds_read_b128 v[202:205], v149 offset:38912
	ds_read_b128 v[206:209], v149 offset:39936
	global_load_lds_dwordx4 v132, s[26:27]
	s_mov_b32 m0, s55
	s_nop 0
	global_load_lds_dwordx4 v134, s[26:27]
	s_waitcnt vmcnt(8)
	s_waitcnt lgkmcnt(0)
	s_setprio 1
	s_barrier
	v_mfma_f32_16x16x32_bf16 v[128:131], v[142:145], v[178:181], v[128:131]
	v_mfma_f32_16x16x32_bf16 v[128:131], v[150:153], v[182:185], v[128:131]
	v_mfma_f32_16x16x32_bf16 v[124:127], v[154:157], v[178:181], v[124:127]
	v_mfma_f32_16x16x32_bf16 v[124:127], v[158:161], v[182:185], v[124:127]
	v_mfma_f32_16x16x32_bf16 v[108:111], v[154:157], v[186:189], v[108:111]
	v_mfma_f32_16x16x32_bf16 v[108:111], v[158:161], v[190:193], v[108:111]
	v_mfma_f32_16x16x32_bf16 v[112:115], v[142:145], v[186:189], v[112:115]
	v_mfma_f32_16x16x32_bf16 v[112:115], v[150:153], v[190:193], v[112:115]
	v_mfma_f32_16x16x32_bf16 v[96:99], v[142:145], v[194:197], v[96:99]
	v_mfma_f32_16x16x32_bf16 v[96:99], v[150:153], v[198:201], v[96:99]
	v_mfma_f32_16x16x32_bf16 v[92:95], v[154:157], v[194:197], v[92:95]
	v_mfma_f32_16x16x32_bf16 v[92:95], v[158:161], v[198:201], v[92:95]
	v_mfma_f32_16x16x32_bf16 v[76:79], v[154:157], v[202:205], v[76:79]
	v_mfma_f32_16x16x32_bf16 v[76:79], v[158:161], v[206:209], v[76:79]
	v_mfma_f32_16x16x32_bf16 v[80:83], v[142:145], v[202:205], v[80:83]
	v_mfma_f32_16x16x32_bf16 v[80:83], v[150:153], v[206:209], v[80:83]
	s_setprio 0
	s_setprio 1
	v_mfma_f32_16x16x32_bf16 v[120:123], v[162:165], v[178:181], v[120:123]
	v_mfma_f32_16x16x32_bf16 v[120:123], v[166:169], v[182:185], v[120:123]
	v_mfma_f32_16x16x32_bf16 v[116:119], v[170:173], v[178:181], v[116:119]
	v_mfma_f32_16x16x32_bf16 v[116:119], v[174:177], v[182:185], v[116:119]
	v_mfma_f32_16x16x32_bf16 v[100:103], v[170:173], v[186:189], v[100:103]
	v_mfma_f32_16x16x32_bf16 v[100:103], v[174:177], v[190:193], v[100:103]
	v_mfma_f32_16x16x32_bf16 v[104:107], v[162:165], v[186:189], v[104:107]
	v_mfma_f32_16x16x32_bf16 v[104:107], v[166:169], v[190:193], v[104:107]
	v_mfma_f32_16x16x32_bf16 v[88:91], v[162:165], v[194:197], v[88:91]
	v_mfma_f32_16x16x32_bf16 v[88:91], v[166:169], v[198:201], v[88:91]
	v_mfma_f32_16x16x32_bf16 v[84:87], v[170:173], v[194:197], v[84:87]
	v_mfma_f32_16x16x32_bf16 v[84:87], v[174:177], v[198:201], v[84:87]
	v_mfma_f32_16x16x32_bf16 v[68:71], v[170:173], v[202:205], v[68:71]
	v_mfma_f32_16x16x32_bf16 v[68:71], v[174:177], v[206:209], v[68:71]
	v_mfma_f32_16x16x32_bf16 v[72:75], v[162:165], v[202:205], v[72:75]
	v_mfma_f32_16x16x32_bf16 v[72:75], v[166:169], v[206:209], v[72:75]
	s_barrier
	s_setprio 0
	s_add_i32 s26, s63, s9
	s_mov_b32 m0, s26
	ds_read_b128 v[178:181], v149 offset:49152
	ds_read_b128 v[182:185], v149 offset:50176
	ds_read_b128 v[186:189], v149 offset:51200
	ds_read_b128 v[190:193], v149 offset:52224
	ds_read_b128 v[194:197], v149 offset:53248
	ds_read_b128 v[198:201], v149 offset:54272
	ds_read_b128 v[202:205], v149 offset:55296
	ds_read_b128 v[206:209], v149 offset:56320
	s_add_u32 s0, s0, 0x80
	s_addc_u32 s1, s1, 0
	global_load_lds_dwordx4 v2, s[0:1]
	s_add_i32 m0, s26, 0x2000
	s_add_i32 s26, s64, s9
	global_load_lds_dwordx4 v136, s[0:1]
	s_add_u32 s0, s0, 0x100000
	s_addc_u32 s1, s1, 0
	s_mov_b32 m0, s26
	s_nop 0
	global_load_lds_dwordx4 v2, s[0:1]
	s_add_i32 m0, s26, 0x2000
	s_nop 0
	global_load_lds_dwordx4 v136, s[0:1]
	s_mov_b32 m0, s58
	s_nop 0
	global_load_lds_dwordx4 v132, s[100:101]
	s_mov_b32 m0, s59
	s_nop 0
	global_load_lds_dwordx4 v134, s[100:101]
	s_waitcnt vmcnt(8)
	s_waitcnt lgkmcnt(0)
	s_setprio 1
	s_barrier
	v_mfma_f32_16x16x32_bf16 v[64:67], v[142:145], v[178:181], v[64:67]
	v_mfma_f32_16x16x32_bf16 v[64:67], v[150:153], v[182:185], v[64:67]
	v_mfma_f32_16x16x32_bf16 v[60:63], v[154:157], v[178:181], v[60:63]
	v_mfma_f32_16x16x32_bf16 v[60:63], v[158:161], v[182:185], v[60:63]
	v_mfma_f32_16x16x32_bf16 v[44:47], v[154:157], v[186:189], v[44:47]
	v_mfma_f32_16x16x32_bf16 v[44:47], v[158:161], v[190:193], v[44:47]
	v_mfma_f32_16x16x32_bf16 v[48:51], v[142:145], v[186:189], v[48:51]
	v_mfma_f32_16x16x32_bf16 v[48:51], v[150:153], v[190:193], v[48:51]
	v_mfma_f32_16x16x32_bf16 v[32:35], v[142:145], v[194:197], v[32:35]
	v_mfma_f32_16x16x32_bf16 v[32:35], v[150:153], v[198:201], v[32:35]
	v_mfma_f32_16x16x32_bf16 v[28:31], v[154:157], v[194:197], v[28:31]
	v_mfma_f32_16x16x32_bf16 v[28:31], v[158:161], v[198:201], v[28:31]
	v_mfma_f32_16x16x32_bf16 v[12:15], v[154:157], v[202:205], v[12:15]
	v_mfma_f32_16x16x32_bf16 v[12:15], v[158:161], v[206:209], v[12:15]
	v_mfma_f32_16x16x32_bf16 v[16:19], v[142:145], v[202:205], v[16:19]
	v_mfma_f32_16x16x32_bf16 v[16:19], v[150:153], v[206:209], v[16:19]
	s_setprio 0
	s_setprio 1
	v_mfma_f32_16x16x32_bf16 v[56:59], v[162:165], v[178:181], v[56:59]
	v_mfma_f32_16x16x32_bf16 v[56:59], v[166:169], v[182:185], v[56:59]
	v_mfma_f32_16x16x32_bf16 v[52:55], v[170:173], v[178:181], v[52:55]
	v_mfma_f32_16x16x32_bf16 v[52:55], v[174:177], v[182:185], v[52:55]
	v_mfma_f32_16x16x32_bf16 v[36:39], v[170:173], v[186:189], v[36:39]
	v_mfma_f32_16x16x32_bf16 v[36:39], v[174:177], v[190:193], v[36:39]
	v_mfma_f32_16x16x32_bf16 v[40:43], v[162:165], v[186:189], v[40:43]
	v_mfma_f32_16x16x32_bf16 v[40:43], v[166:169], v[190:193], v[40:43]
	v_mfma_f32_16x16x32_bf16 v[24:27], v[162:165], v[194:197], v[24:27]
	v_mfma_f32_16x16x32_bf16 v[24:27], v[166:169], v[198:201], v[24:27]
	v_mfma_f32_16x16x32_bf16 v[20:23], v[170:173], v[194:197], v[20:23]
	v_mfma_f32_16x16x32_bf16 v[20:23], v[174:177], v[198:201], v[20:23]
	v_mfma_f32_16x16x32_bf16 v[4:7], v[170:173], v[202:205], v[4:7]
	v_mfma_f32_16x16x32_bf16 v[4:7], v[174:177], v[206:209], v[4:7]
	v_mfma_f32_16x16x32_bf16 v[8:11], v[162:165], v[202:205], v[8:11]
	v_mfma_f32_16x16x32_bf16 v[8:11], v[166:169], v[206:209], v[8:11]
	s_barrier
	s_setprio 0
	s_add_i32 s62, s62, 2
	s_add_u32 s56, s56, 0x100
	s_addc_u32 s57, s57, 0
	s_add_u32 s47, s47, 0x100
	s_addc_u32 s49, s49, 0
	s_cmp_gt_u32 s62, 61
	s_cbranch_scc0 .LBB0_1624
	s_and_b64 vcc, exec, s[44:45]
	s_cbranch_vccz .LBB0_1627
	s_barrier

; #define PG8_STAGE(bufoff, gbase, voff) do { _Pragma("unroll") for (int _i = 0; _i < 2; ++_i) \
;         __builtin_amdgcn_global_load_lds((const unsigned*)((const char*)(gbase) + (voff)[_i]), (PG8_LAS unsigned*)(lds + (bufoff) + ldsw + _i * 8192), 16, 0, 0); } while (0)
; #define PG8_LDA(dst, b, h) do { _Pragma("unroll") for (int m = 0; m < 4; ++m) _Pragma("unroll") for (int k = 0; k < 2; ++k) dst[m][k] = *(const PG8_LAS bf16x8*)(lds + PG8_SA(b, h) + aoff + m * 2048 + k * 1024); } while (0)
; #define PG8_LDB(dst, b, h) do { _Pragma("unroll") for (int n = 0; n < 2; ++n) _Pragma("unroll") for (int k = 0; k < 2; ++k) dst[n][k] = *(const PG8_LAS bf16x8*)(lds + PG8_SB(b, h) + boff + n * 2048 + k * 1024); } while (0)
; #define PG8_MMA(ai, bj, At, Bt) do { __builtin_amdgcn_s_setprio(1); _Pragma("unroll") for (int m = 0; m < 4; ++m) _Pragma("unroll") for (int n = 0; n < 2; ++n) _Pragma("unroll") for (int k = 0; k < 2; ++k) \
;         acc[ai][bj][m][n] = __builtin_amdgcn_mfma_f32_16x16x32_bf16(Bt[n][k], At[m][k], acc[ai][bj][m][n], 0, 0, 0); __builtin_amdgcn_s_setprio(0); } while (0)
; #define PG8_WAIT_V(n) asm volatile("s_waitcnt vmcnt(" #n ")" ::: "memory")
; #define PG8_WAIT_L(n) asm volatile("s_waitcnt lgkmcnt(" #n ")" ::: "memory")
; template <class Epi, class Sched, bool ALIGN_EPI = false, bool SP2 = false>
; __device__ __forceinline__ void gemm_phase(PG8_LAS unsigned char* lds, const Gemm g, const Sched& S, const Epi& E) {
;     ...
;             const bool last = (t == nt - 2);
;             const char* a1 = cA + (size_t)(t + 1) * kstep;
;             const char* a2 = last ? nA : cA + (size_t)(t + 2) * kstep; const char* b2 = last ? nB : cB + (size_t)(t + 2) * kstep;
;             const char* a3 = a2 + kstep; const char* b3 = b2 + kstep;
;             if (last && has_next) S.a_ready(nxt);
;             if constexpr (SP2) {
;             PG8_LDB(B0, 0, 0); PG8_LDB(B1, 0, 1); PG8_SCHED; PG8_LDA(At, 0, 0); PG8_STAGE(PG8_SA(1, 1), a1 + hstep, voffA);
;             PG8_WAIT_V(8); PG8_WAIT_L(0); PG8_BAR; PG8_MMA(0, 0, At, B0); PG8_MMA(0, 1, At, B1); PG8_BAR; PG8_SCHED;
;             PG8_LDA(At, 0, 1); PG8_STAGE(PG8_SB(0, 0), b2, voffB); PG8_STAGE(PG8_SB(0, 1), b2 + hstep, voffB); PG8_STAGE(PG8_SA(0, 0), a2, voffA);
;             PG8_WAIT_V(8); PG8_WAIT_L(0); PG8_BAR; PG8_MMA(1, 0, At, B0); PG8_MMA(1, 1, At, B1); PG8_BAR; PG8_SCHED;
.LBB0_2089:
	s_add_u32 s0, s50, 0xfff00080
	s_addc_u32 s1, s51, -1
	s_add_i32 s61, 0, 0x10000
	s_cmp_eq_u32 s60, 60
	s_cselect_b32 s27, s47, s1
	s_cselect_b32 s26, s46, s0
	s_cselect_b32 s1, s49, s45
	s_cselect_b32 s0, s48, s43
	s_add_i32 s64, 0, 0x14000
	ds_read_b128 v[142:145], v210
	ds_read_b128 v[146:149], v210 offset:1024
	ds_read_b128 v[154:157], v210 offset:2048
	ds_read_b128 v[158:161], v210 offset:3072
	ds_read_b128 v[162:165], v210 offset:16384
	ds_read_b128 v[166:169], v210 offset:17408
	ds_read_b128 v[170:173], v210 offset:18432
	ds_read_b128 v[174:177], v210 offset:19456
	s_add_i32 m0, s10, 0xc000
	ds_read_b128 v[178:181], v153
	ds_read_b128 v[182:185], v153 offset:1024
	ds_read_b128 v[186:189], v153 offset:2048
	ds_read_b128 v[190:193], v153 offset:3072
	ds_read_b128 v[194:197], v153 offset:4096
	ds_read_b128 v[198:201], v153 offset:5120
	ds_read_b128 v[202:205], v153 offset:6144
	ds_read_b128 v[206:209], v153 offset:7168
	global_load_lds_dwordx4 v138, s[50:51]
	s_add_i32 m0, s10, 0xe000
	s_nop 0
	global_load_lds_dwordx4 v140, s[50:51]
	s_waitcnt vmcnt(8)
	s_waitcnt lgkmcnt(0)
	s_setprio 1
	s_barrier
	v_mfma_f32_16x16x32_bf16 v[128:131], v[142:145], v[178:181], v[128:131]
	v_mfma_f32_16x16x32_bf16 v[128:131], v[146:149], v[182:185], v[128:131]
	v_mfma_f32_16x16x32_bf16 v[124:127], v[154:157], v[178:181], v[124:127]
	v_mfma_f32_16x16x32_bf16 v[124:127], v[158:161], v[182:185], v[124:127]
	v_mfma_f32_16x16x32_bf16 v[108:111], v[154:157], v[186:189], v[108:111]
	v_mfma_f32_16x16x32_bf16 v[108:111], v[158:161], v[190:193], v[108:111]
	v_mfma_f32_16x16x32_bf16 v[112:115], v[142:145], v[186:189], v[112:115]
	v_mfma_f32_16x16x32_bf16 v[112:115], v[146:149], v[190:193], v[112:115]
	v_mfma_f32_16x16x32_bf16 v[96:99], v[142:145], v[194:197], v[96:99]
	v_mfma_f32_16x16x32_bf16 v[96:99], v[146:149], v[198:201], v[96:99]
	v_mfma_f32_16x16x32_bf16 v[92:95], v[154:157], v[194:197], v[92:95]
	v_mfma_f32_16x16x32_bf16 v[92:95], v[158:161], v[198:201], v[92:95]
	v_mfma_f32_16x16x32_bf16 v[76:79], v[154:157], v[202:205], v[76:79]
	v_mfma_f32_16x16x32_bf16 v[76:79], v[158:161], v[206:209], v[76:79]
	v_mfma_f32_16x16x32_bf16 v[80:83], v[142:145], v[202:205], v[80:83]
	v_mfma_f32_16x16x32_bf16 v[80:83], v[146:149], v[206:209], v[80:83]
	s_setprio 0
	s_setprio 1
	v_mfma_f32_16x16x32_bf16 v[120:123], v[162:165], v[178:181], v[120:123]
	v_mfma_f32_16x16x32_bf16 v[120:123], v[166:169], v[182:185], v[120:123]
	v_mfma_f32_16x16x32_bf16 v[116:119], v[170:173], v[178:181], v[116:119]
	v_mfma_f32_16x16x32_bf16 v[116:119], v[174:177], v[182:185], v[116:119]
	v_mfma_f32_16x16x32_bf16 v[100:103], v[170:173], v[186:189], v[100:103]
	v_mfma_f32_16x16x32_bf16 v[100:103], v[174:177], v[190:193], v[100:103]
	v_mfma_f32_16x16x32_bf16 v[104:107], v[162:165], v[186:189], v[104:107]
	v_mfma_f32_16x16x32_bf16 v[104:107], v[166:169], v[190:193], v[104:107]
	v_mfma_f32_16x16x32_bf16 v[88:91], v[162:165], v[194:197], v[88:91]
	v_mfma_f32_16x16x32_bf16 v[88:91], v[166:169], v[198:201], v[88:91]
	v_mfma_f32_16x16x32_bf16 v[84:87], v[170:173], v[194:197], v[84:87]
	v_mfma_f32_16x16x32_bf16 v[84:87], v[174:177], v[198:201], v[84:87]
	v_mfma_f32_16x16x32_bf16 v[68:71], v[170:173], v[202:205], v[68:71]
	v_mfma_f32_16x16x32_bf16 v[68:71], v[174:177], v[206:209], v[68:71]
	v_mfma_f32_16x16x32_bf16 v[72:75], v[162:165], v[202:205], v[72:75]
	v_mfma_f32_16x16x32_bf16 v[72:75], v[166:169], v[206:209], v[72:75]
	s_barrier
	s_setprio 0
	s_add_i32 s61, s61, s9
	s_mov_b32 m0, s61
	ds_read_b128 v[178:181], v153 offset:16384
	ds_read_b128 v[182:185], v153 offset:17408
	ds_read_b128 v[186:189], v153 offset:18432
	ds_read_b128 v[190:193], v153 offset:19456
	ds_read_b128 v[194:197], v153 offset:20480
	ds_read_b128 v[198:201], v153 offset:21504
	ds_read_b128 v[202:205], v153 offset:22528
	ds_read_b128 v[206:209], v153 offset:23552
	global_load_lds_dwordx4 v2, s[0:1]
	s_add_i32 m0, s61, 0x2000
	s_add_u32 s62, s0, 0x100000
	s_addc_u32 s63, s1, 0
	s_add_i32 s61, s64, s9
	global_load_lds_dwordx4 v132, s[0:1]
	s_mov_b32 m0, s61
	s_nop 0
	global_load_lds_dwordx4 v2, s[62:63]
	s_add_i32 m0, s61, 0x2000
	s_nop 0
	global_load_lds_dwordx4 v132, s[62:63]
	s_mov_b32 m0, s10
	s_nop 0
	global_load_lds_dwordx4 v136, s[26:27]
	s_mov_b32 m0, s11
	s_nop 0
	global_load_lds_dwordx4 v134, s[26:27]
	s_add_u32 s100, s26, 0x80
	s_addc_u32 s101, s27, 0
	s_waitcnt vmcnt(8)
	s_waitcnt lgkmcnt(0)
	s_setprio 1
	s_barrier
	v_mfma_f32_16x16x32_bf16 v[64:67], v[142:145], v[178:181], v[64:67]
	v_mfma_f32_16x16x32_bf16 v[64:67], v[146:149], v[182:185], v[64:67]
	v_mfma_f32_16x16x32_bf16 v[60:63], v[154:157], v[178:181], v[60:63]
	v_mfma_f32_16x16x32_bf16 v[60:63], v[158:161], v[182:185], v[60:63]
	v_mfma_f32_16x16x32_bf16 v[44:47], v[154:157], v[186:189], v[44:47]
	v_mfma_f32_16x16x32_bf16 v[44:47], v[158:161], v[190:193], v[44:47]
	v_mfma_f32_16x16x32_bf16 v[48:51], v[142:145], v[186:189], v[48:51]
	v_mfma_f32_16x16x32_bf16 v[48:51], v[146:149], v[190:193], v[48:51]
	v_mfma_f32_16x16x32_bf16 v[32:35], v[142:145], v[194:197], v[32:35]
	v_mfma_f32_16x16x32_bf16 v[32:35], v[146:149], v[198:201], v[32:35]
	v_mfma_f32_16x16x32_bf16 v[28:31], v[154:157], v[194:197], v[28:31]
	v_mfma_f32_16x16x32_bf16 v[28:31], v[158:161], v[198:201], v[28:31]
	v_mfma_f32_16x16x32_bf16 v[12:15], v[154:157], v[202:205], v[12:15]
	v_mfma_f32_16x16x32_bf16 v[12:15], v[158:161], v[206:209], v[12:15]
	v_mfma_f32_16x16x32_bf16 v[16:19], v[142:145], v[202:205], v[16:19]
	v_mfma_f32_16x16x32_bf16 v[16:19], v[146:149], v[206:209], v[16:19]
	s_setprio 0
	s_setprio 1
	v_mfma_f32_16x16x32_bf16 v[56:59], v[162:165], v[178:181], v[56:59]
	v_mfma_f32_16x16x32_bf16 v[56:59], v[166:169], v[182:185], v[56:59]
	v_mfma_f32_16x16x32_bf16 v[52:55], v[170:173], v[178:181], v[52:55]
	v_mfma_f32_16x16x32_bf16 v[52:55], v[174:177], v[182:185], v[52:55]
	v_mfma_f32_16x16x32_bf16 v[36:39], v[170:173], v[186:189], v[36:39]
	v_mfma_f32_16x16x32_bf16 v[36:39], v[174:177], v[190:193], v[36:39]
	v_mfma_f32_16x16x32_bf16 v[40:43], v[162:165], v[186:189], v[40:43]
	v_mfma_f32_16x16x32_bf16 v[40:43], v[166:169], v[190:193], v[40:43]
	v_mfma_f32_16x16x32_bf16 v[24:27], v[162:165], v[194:197], v[24:27]
	v_mfma_f32_16x16x32_bf16 v[24:27], v[166:169], v[198:201], v[24:27]
	v_mfma_f32_16x16x32_bf16 v[20:23], v[170:173], v[194:197], v[20:23]
	v_mfma_f32_16x16x32_bf16 v[20:23], v[174:177], v[198:201], v[20:23]
	v_mfma_f32_16x16x32_bf16 v[4:7], v[170:173], v[202:205], v[4:7]
	v_mfma_f32_16x16x32_bf16 v[4:7], v[174:177], v[206:209], v[4:7]
	v_mfma_f32_16x16x32_bf16 v[8:11], v[162:165], v[202:205], v[8:11]
	v_mfma_f32_16x16x32_bf16 v[8:11], v[166:169], v[206:209], v[8:11]
	s_barrier
; #define PG8_STAGE(bufoff, gbase, voff) do { _Pragma("unroll") for (int _i = 0; _i < 2; ++_i) \
;         __builtin_amdgcn_global_load_lds((const unsigned*)((const char*)(gbase) + (voff)[_i]), (PG8_LAS unsigned*)(lds + (bufoff) + ldsw + _i * 8192), 16, 0, 0); } while (0)
; #define PG8_LDA(dst, b, h) do { _Pragma("unroll") for (int m = 0; m < 4; ++m) _Pragma("unroll") for (int k = 0; k < 2; ++k) dst[m][k] = *(const PG8_LAS bf16x8*)(lds + PG8_SA(b, h) + aoff + m * 2048 + k * 1024); } while (0)
; #define PG8_LDB(dst, b, h) do { _Pragma("unroll") for (int n = 0; n < 2; ++n) _Pragma("unroll") for (int k = 0; k < 2; ++k) dst[n][k] = *(const PG8_LAS bf16x8*)(lds + PG8_SB(b, h) + boff + n * 2048 + k * 1024); } while (0)
; #define PG8_MMA(ai, bj, At, Bt) do { __builtin_amdgcn_s_setprio(1); _Pragma("unroll") for (int m = 0; m < 4; ++m) _Pragma("unroll") for (int n = 0; n < 2; ++n) _Pragma("unroll") for (int k = 0; k < 2; ++k) \
;         acc[ai][bj][m][n] = __builtin_amdgcn_mfma_f32_16x16x32_bf16(Bt[n][k], At[m][k], acc[ai][bj][m][n], 0, 0, 0); __builtin_amdgcn_s_setprio(0); } while (0)
; #define PG8_WAIT_V(n) asm volatile("s_waitcnt vmcnt(" #n ")" ::: "memory")
; #define PG8_WAIT_L(n) asm volatile("s_waitcnt lgkmcnt(" #n ")" ::: "memory")
; #define PG8_BAR __builtin_amdgcn_s_barrier()
; #define PG8_SCHED __builtin_amdgcn_sched_barrier(0)
; template <class Epi, class Sched, bool ALIGN_EPI = false, bool SP2 = false>
; __device__ __forceinline__ void gemm_phase(PG8_LAS unsigned char* lds, const Gemm g, const Sched& S, const Epi& E) {
;     ...
;         for (int t = 0; t < nt; t += 2) {
;             const bool last = (t == nt - 2);
;             const char* a1 = cA + (size_t)(t + 1) * kstep;
;             const char* a2 = last ? nA : cA + (size_t)(t + 2) * kstep; const char* b2 = last ? nB : cB + (size_t)(t + 2) * kstep;
;     ...
;             PG8_LDB(B0, 1, 0); PG8_LDB(B1, 1, 1); PG8_SCHED; PG8_LDA(At, 1, 0); PG8_STAGE(PG8_SA(0, 1), a2 + hstep, voffA);
;             PG8_WAIT_V(8); PG8_WAIT_L(0); PG8_BAR; PG8_MMA(0, 0, At, B0); PG8_MMA(0, 1, At, B1); PG8_BAR; PG8_SCHED;
;             PG8_LDA(At, 1, 1); PG8_STAGE(PG8_SB(1, 0), b3, voffB); PG8_STAGE(PG8_SB(1, 1), b3 + hstep, voffB); PG8_STAGE(PG8_SA(1, 0), a3, voffA);
;             PG8_WAIT_V(8); PG8_WAIT_L(0); PG8_BAR; PG8_MMA(1, 0, At, B0); PG8_MMA(1, 1, At, B1); PG8_BAR; PG8_SCHED;
	s_setprio 0
	s_add_i32 s61, 0, 0x18000
	s_add_i32 s62, 0, 0x1c000
	ds_read_b128 v[142:145], v210 offset:32768
	ds_read_b128 v[146:149], v210 offset:33792
	ds_read_b128 v[154:157], v210 offset:34816
	ds_read_b128 v[158:161], v210 offset:35840
	ds_read_b128 v[162:165], v210 offset:49152
	ds_read_b128 v[166:169], v210 offset:50176
	ds_read_b128 v[170:173], v210 offset:51200
	ds_read_b128 v[174:177], v210 offset:52224
	s_add_u32 s26, s26, 0x100000
	s_addc_u32 s27, s27, 0
	s_mov_b32 m0, s52
	ds_read_b128 v[178:181], v153 offset:32768
	ds_read_b128 v[182:185], v153 offset:33792
	ds_read_b128 v[186:189], v153 offset:34816
	ds_read_b128 v[190:193], v153 offset:35840
	ds_read_b128 v[194:197], v153 offset:36864
	ds_read_b128 v[198:201], v153 offset:37888
	ds_read_b128 v[202:205], v153 offset:38912
	ds_read_b128 v[206:209], v153 offset:39936
	global_load_lds_dwordx4 v136, s[26:27]
	s_mov_b32 m0, s53
	s_nop 0
	global_load_lds_dwordx4 v134, s[26:27]
	s_waitcnt vmcnt(8)
	s_waitcnt lgkmcnt(0)
	s_setprio 1
	s_barrier
	v_mfma_f32_16x16x32_bf16 v[128:131], v[142:145], v[178:181], v[128:131]
	v_mfma_f32_16x16x32_bf16 v[128:131], v[146:149], v[182:185], v[128:131]
	v_mfma_f32_16x16x32_bf16 v[124:127], v[154:157], v[178:181], v[124:127]
	v_mfma_f32_16x16x32_bf16 v[124:127], v[158:161], v[182:185], v[124:127]
	v_mfma_f32_16x16x32_bf16 v[108:111], v[154:157], v[186:189], v[108:111]
	v_mfma_f32_16x16x32_bf16 v[108:111], v[158:161], v[190:193], v[108:111]
	v_mfma_f32_16x16x32_bf16 v[112:115], v[142:145], v[186:189], v[112:115]
	v_mfma_f32_16x16x32_bf16 v[112:115], v[146:149], v[190:193], v[112:115]
	v_mfma_f32_16x16x32_bf16 v[96:99], v[142:145], v[194:197], v[96:99]
	v_mfma_f32_16x16x32_bf16 v[96:99], v[146:149], v[198:201], v[96:99]
	v_mfma_f32_16x16x32_bf16 v[92:95], v[154:157], v[194:197], v[92:95]
	v_mfma_f32_16x16x32_bf16 v[92:95], v[158:161], v[198:201], v[92:95]
	v_mfma_f32_16x16x32_bf16 v[76:79], v[154:157], v[202:205], v[76:79]
	v_mfma_f32_16x16x32_bf16 v[76:79], v[158:161], v[206:209], v[76:79]
	v_mfma_f32_16x16x32_bf16 v[80:83], v[142:145], v[202:205], v[80:83]
	v_mfma_f32_16x16x32_bf16 v[80:83], v[146:149], v[206:209], v[80:83]
	s_setprio 0
	s_setprio 1
	v_mfma_f32_16x16x32_bf16 v[120:123], v[162:165], v[178:181], v[120:123]
	v_mfma_f32_16x16x32_bf16 v[120:123], v[166:169], v[182:185], v[120:123]
	v_mfma_f32_16x16x32_bf16 v[116:119], v[170:173], v[178:181], v[116:119]
	v_mfma_f32_16x16x32_bf16 v[116:119], v[174:177], v[182:185], v[116:119]
	v_mfma_f32_16x16x32_bf16 v[100:103], v[170:173], v[186:189], v[100:103]
	v_mfma_f32_16x16x32_bf16 v[100:103], v[174:177], v[190:193], v[100:103]
	v_mfma_f32_16x16x32_bf16 v[104:107], v[162:165], v[186:189], v[104:107]
	v_mfma_f32_16x16x32_bf16 v[104:107], v[166:169], v[190:193], v[104:107]
	v_mfma_f32_16x16x32_bf16 v[88:91], v[162:165], v[194:197], v[88:91]
	v_mfma_f32_16x16x32_bf16 v[88:91], v[166:169], v[198:201], v[88:91]
	v_mfma_f32_16x16x32_bf16 v[84:87], v[170:173], v[194:197], v[84:87]
	v_mfma_f32_16x16x32_bf16 v[84:87], v[174:177], v[198:201], v[84:87]
	v_mfma_f32_16x16x32_bf16 v[68:71], v[170:173], v[202:205], v[68:71]
	v_mfma_f32_16x16x32_bf16 v[68:71], v[174:177], v[206:209], v[68:71]
	v_mfma_f32_16x16x32_bf16 v[72:75], v[162:165], v[202:205], v[72:75]
	v_mfma_f32_16x16x32_bf16 v[72:75], v[166:169], v[206:209], v[72:75]
	s_barrier
	s_setprio 0
	s_add_i32 s26, s61, s9
	s_mov_b32 m0, s26
	ds_read_b128 v[178:181], v153 offset:49152
	ds_read_b128 v[182:185], v153 offset:50176
	ds_read_b128 v[186:189], v153 offset:51200
	ds_read_b128 v[190:193], v153 offset:52224
	ds_read_b128 v[194:197], v153 offset:53248
	ds_read_b128 v[198:201], v153 offset:54272
	ds_read_b128 v[202:205], v153 offset:55296
	ds_read_b128 v[206:209], v153 offset:56320
	s_add_u32 s0, s0, 0x80
	s_addc_u32 s1, s1, 0
	global_load_lds_dwordx4 v2, s[0:1]
	s_add_i32 m0, s26, 0x2000
	s_add_i32 s26, s62, s9
	global_load_lds_dwordx4 v132, s[0:1]
	s_add_u32 s0, s0, 0x100000
	s_addc_u32 s1, s1, 0
	s_mov_b32 m0, s26
	s_nop 0
	global_load_lds_dwordx4 v2, s[0:1]
	s_add_i32 m0, s26, 0x2000
	s_nop 0
	global_load_lds_dwordx4 v132, s[0:1]
	s_mov_b32 m0, s54
	s_nop 0
	global_load_lds_dwordx4 v136, s[100:101]
	s_mov_b32 m0, s55
	s_nop 0
	global_load_lds_dwordx4 v134, s[100:101]
	s_waitcnt vmcnt(8)
	s_waitcnt lgkmcnt(0)
	s_setprio 1
	s_barrier
	v_mfma_f32_16x16x32_bf16 v[64:67], v[142:145], v[178:181], v[64:67]
	v_mfma_f32_16x16x32_bf16 v[64:67], v[146:149], v[182:185], v[64:67]
	v_mfma_f32_16x16x32_bf16 v[60:63], v[154:157], v[178:181], v[60:63]
	v_mfma_f32_16x16x32_bf16 v[60:63], v[158:161], v[182:185], v[60:63]
	v_mfma_f32_16x16x32_bf16 v[44:47], v[154:157], v[186:189], v[44:47]
	v_mfma_f32_16x16x32_bf16 v[44:47], v[158:161], v[190:193], v[44:47]
	v_mfma_f32_16x16x32_bf16 v[48:51], v[142:145], v[186:189], v[48:51]
	v_mfma_f32_16x16x32_bf16 v[48:51], v[146:149], v[190:193], v[48:51]
	v_mfma_f32_16x16x32_bf16 v[32:35], v[142:145], v[194:197], v[32:35]
	v_mfma_f32_16x16x32_bf16 v[32:35], v[146:149], v[198:201], v[32:35]
	v_mfma_f32_16x16x32_bf16 v[28:31], v[154:157], v[194:197], v[28:31]
	v_mfma_f32_16x16x32_bf16 v[28:31], v[158:161], v[198:201], v[28:31]
	v_mfma_f32_16x16x32_bf16 v[12:15], v[154:157], v[202:205], v[12:15]
	v_mfma_f32_16x16x32_bf16 v[12:15], v[158:161], v[206:209], v[12:15]
	v_mfma_f32_16x16x32_bf16 v[16:19], v[142:145], v[202:205], v[16:19]
	v_mfma_f32_16x16x32_bf16 v[16:19], v[146:149], v[206:209], v[16:19]
	s_setprio 0
	s_setprio 1
	v_mfma_f32_16x16x32_bf16 v[56:59], v[162:165], v[178:181], v[56:59]
	v_mfma_f32_16x16x32_bf16 v[56:59], v[166:169], v[182:185], v[56:59]
	v_mfma_f32_16x16x32_bf16 v[52:55], v[170:173], v[178:181], v[52:55]
	v_mfma_f32_16x16x32_bf16 v[52:55], v[174:177], v[182:185], v[52:55]
	v_mfma_f32_16x16x32_bf16 v[36:39], v[170:173], v[186:189], v[36:39]
	v_mfma_f32_16x16x32_bf16 v[36:39], v[174:177], v[190:193], v[36:39]
	v_mfma_f32_16x16x32_bf16 v[40:43], v[162:165], v[186:189], v[40:43]
	v_mfma_f32_16x16x32_bf16 v[40:43], v[166:169], v[190:193], v[40:43]
	v_mfma_f32_16x16x32_bf16 v[24:27], v[162:165], v[194:197], v[24:27]
	v_mfma_f32_16x16x32_bf16 v[24:27], v[166:169], v[198:201], v[24:27]
	v_mfma_f32_16x16x32_bf16 v[20:23], v[170:173], v[194:197], v[20:23]
	v_mfma_f32_16x16x32_bf16 v[20:23], v[174:177], v[198:201], v[20:23]
	v_mfma_f32_16x16x32_bf16 v[4:7], v[170:173], v[202:205], v[4:7]
	v_mfma_f32_16x16x32_bf16 v[4:7], v[174:177], v[206:209], v[4:7]
	v_mfma_f32_16x16x32_bf16 v[8:11], v[162:165], v[202:205], v[8:11]
	v_mfma_f32_16x16x32_bf16 v[8:11], v[166:169], v[206:209], v[8:11]
	s_barrier
	s_setprio 0
	s_add_i32 s60, s60, 2
	s_add_u32 s50, s50, 0x100
	s_addc_u32 s51, s51, 0
	s_add_u32 s43, s43, 0x100
	s_addc_u32 s45, s45, 0
	s_cmp_gt_u32 s60, 61
	s_cbranch_scc0 .LBB0_2089
	s_and_b64 vcc, exec, s[40:41]
	s_cbranch_vccz .LBB0_2092
	s_barrier

; #define PG8_STAGE(bufoff, gbase, voff) do { _Pragma("unroll") for (int _i = 0; _i < 2; ++_i) \
;         __builtin_amdgcn_global_load_lds((const unsigned*)((const char*)(gbase) + (voff)[_i]), (PG8_LAS unsigned*)(lds + (bufoff) + ldsw + _i * 8192), 16, 0, 0); } while (0)
; #define PG8_LDA(dst, b, h) do { _Pragma("unroll") for (int m = 0; m < 4; ++m) _Pragma("unroll") for (int k = 0; k < 2; ++k) dst[m][k] = *(const PG8_LAS bf16x8*)(lds + PG8_SA(b, h) + aoff + m * 2048 + k * 1024); } while (0)
; #define PG8_LDB(dst, b, h) do { _Pragma("unroll") for (int n = 0; n < 2; ++n) _Pragma("unroll") for (int k = 0; k < 2; ++k) dst[n][k] = *(const PG8_LAS bf16x8*)(lds + PG8_SB(b, h) + boff + n * 2048 + k * 1024); } while (0)
; #define PG8_MMA(ai, bj, At, Bt) do { __builtin_amdgcn_s_setprio(1); _Pragma("unroll") for (int m = 0; m < 4; ++m) _Pragma("unroll") for (int n = 0; n < 2; ++n) _Pragma("unroll") for (int k = 0; k < 2; ++k) \
;         acc[ai][bj][m][n] = __builtin_amdgcn_mfma_f32_16x16x32_bf16(Bt[n][k], At[m][k], acc[ai][bj][m][n], 0, 0, 0); __builtin_amdgcn_s_setprio(0); } while (0)
; #define PG8_WAIT_V(n) asm volatile("s_waitcnt vmcnt(" #n ")" ::: "memory")
; #define PG8_WAIT_L(n) asm volatile("s_waitcnt lgkmcnt(" #n ")" ::: "memory")
; template <class Epi, class Sched, bool ALIGN_EPI = false, bool SP2 = false>
; __device__ __forceinline__ void gemm_phase(PG8_LAS unsigned char* lds, const Gemm g, const Sched& S, const Epi& E) {
;     ...
;             const bool last = (t == nt - 2);
;             const char* a1 = cA + (size_t)(t + 1) * kstep;
;             const char* a2 = last ? nA : cA + (size_t)(t + 2) * kstep; const char* b2 = last ? nB : cB + (size_t)(t + 2) * kstep;
;             const char* a3 = a2 + kstep; const char* b3 = b2 + kstep;
;             if (last && has_next) S.a_ready(nxt);
;             if constexpr (SP2) {
;             PG8_LDB(B0, 0, 0); PG8_LDB(B1, 0, 1); PG8_SCHED; PG8_LDA(At, 0, 0); PG8_STAGE(PG8_SA(1, 1), a1 + hstep, voffA);
;             PG8_WAIT_V(8); PG8_WAIT_L(0); PG8_BAR; PG8_MMA(0, 0, At, B0); PG8_MMA(0, 1, At, B1); PG8_BAR; PG8_SCHED;
;             PG8_LDA(At, 0, 1); PG8_STAGE(PG8_SB(0, 0), b2, voffB); PG8_STAGE(PG8_SB(0, 1), b2 + hstep, voffB); PG8_STAGE(PG8_SA(0, 0), a2, voffA);
;             PG8_WAIT_V(8); PG8_WAIT_L(0); PG8_BAR; PG8_MMA(1, 0, At, B0); PG8_MMA(1, 1, At, B1); PG8_BAR; PG8_SCHED;
.LBB0_2115:
	s_add_u32 s0, s40, 0xfff00080
	s_addc_u32 s1, s41, -1
	s_add_i32 s77, 0, 0x10000
	s_cmp_eq_u32 s76, 60
	s_cselect_b32 s27, s49, s1
	s_cselect_b32 s26, s57, s0
	s_cselect_b32 s1, s47, s59
	s_cselect_b32 s0, s73, s58
	s_add_i32 s80, 0, 0x14000
	s_waitcnt vmcnt(0)
	ds_read_b128 v[132:135], v188
	ds_read_b128 v[136:139], v188 offset:1024
	ds_read_b128 v[152:155], v188 offset:2048
	ds_read_b128 v[156:159], v188 offset:3072
	ds_read_b128 v[160:163], v188 offset:16384
	ds_read_b128 v[164:167], v188 offset:17408
	ds_read_b128 v[168:171], v188 offset:18432
	ds_read_b128 v[172:175], v188 offset:19456
	s_add_i32 m0, s11, 0xc000
	ds_read_b128 v[176:179], v194
	ds_read_b128 v[180:183], v194 offset:1024
	ds_read_b128 v[184:187], v194 offset:2048
	ds_read_b128 v[196:199], v194 offset:3072
	ds_read_b128 v[200:203], v194 offset:4096
	ds_read_b128 v[204:207], v194 offset:5120
	ds_read_b128 v[208:211], v194 offset:6144
	ds_read_b128 v[212:215], v194 offset:7168
	global_load_lds_dwordx4 v148, s[40:41]
	s_add_i32 m0, s11, 0xe000
	s_nop 0
	global_load_lds_dwordx4 v150, s[40:41]
	s_waitcnt vmcnt(8)
	s_waitcnt lgkmcnt(0)
	s_setprio 1
	s_barrier
	v_mfma_f32_16x16x32_bf16 v[128:131], v[132:135], v[176:179], v[128:131]
	v_mfma_f32_16x16x32_bf16 v[128:131], v[136:139], v[180:183], v[128:131]
	v_mfma_f32_16x16x32_bf16 v[124:127], v[152:155], v[176:179], v[124:127]
	v_mfma_f32_16x16x32_bf16 v[124:127], v[156:159], v[180:183], v[124:127]
	v_mfma_f32_16x16x32_bf16 v[108:111], v[152:155], v[184:187], v[108:111]
	v_mfma_f32_16x16x32_bf16 v[108:111], v[156:159], v[196:199], v[108:111]
	v_mfma_f32_16x16x32_bf16 v[112:115], v[132:135], v[184:187], v[112:115]
	v_mfma_f32_16x16x32_bf16 v[112:115], v[136:139], v[196:199], v[112:115]
	v_mfma_f32_16x16x32_bf16 v[96:99], v[132:135], v[200:203], v[96:99]
	v_mfma_f32_16x16x32_bf16 v[96:99], v[136:139], v[204:207], v[96:99]
	v_mfma_f32_16x16x32_bf16 v[92:95], v[152:155], v[200:203], v[92:95]
	v_mfma_f32_16x16x32_bf16 v[92:95], v[156:159], v[204:207], v[92:95]
	v_mfma_f32_16x16x32_bf16 v[76:79], v[152:155], v[208:211], v[76:79]
	v_mfma_f32_16x16x32_bf16 v[76:79], v[156:159], v[212:215], v[76:79]
	v_mfma_f32_16x16x32_bf16 v[80:83], v[132:135], v[208:211], v[80:83]
	v_mfma_f32_16x16x32_bf16 v[80:83], v[136:139], v[212:215], v[80:83]
	s_setprio 0
	s_setprio 1
	v_mfma_f32_16x16x32_bf16 v[120:123], v[160:163], v[176:179], v[120:123]
	v_mfma_f32_16x16x32_bf16 v[120:123], v[164:167], v[180:183], v[120:123]
	v_mfma_f32_16x16x32_bf16 v[116:119], v[168:171], v[176:179], v[116:119]
	v_mfma_f32_16x16x32_bf16 v[116:119], v[172:175], v[180:183], v[116:119]
	v_mfma_f32_16x16x32_bf16 v[100:103], v[168:171], v[184:187], v[100:103]
	v_mfma_f32_16x16x32_bf16 v[100:103], v[172:175], v[196:199], v[100:103]
	v_mfma_f32_16x16x32_bf16 v[104:107], v[160:163], v[184:187], v[104:107]
	v_mfma_f32_16x16x32_bf16 v[104:107], v[164:167], v[196:199], v[104:107]
	v_mfma_f32_16x16x32_bf16 v[88:91], v[160:163], v[200:203], v[88:91]
	v_mfma_f32_16x16x32_bf16 v[88:91], v[164:167], v[204:207], v[88:91]
	v_mfma_f32_16x16x32_bf16 v[84:87], v[168:171], v[200:203], v[84:87]
	v_mfma_f32_16x16x32_bf16 v[84:87], v[172:175], v[204:207], v[84:87]
	v_mfma_f32_16x16x32_bf16 v[68:71], v[168:171], v[208:211], v[68:71]
	v_mfma_f32_16x16x32_bf16 v[68:71], v[172:175], v[212:215], v[68:71]
	v_mfma_f32_16x16x32_bf16 v[72:75], v[160:163], v[208:211], v[72:75]
	v_mfma_f32_16x16x32_bf16 v[72:75], v[164:167], v[212:215], v[72:75]
	s_barrier
	s_setprio 0
	s_add_i32 s77, s77, s10
	s_mov_b32 m0, s77
	ds_read_b128 v[176:179], v194 offset:16384
	ds_read_b128 v[180:183], v194 offset:17408
	ds_read_b128 v[184:187], v194 offset:18432
	ds_read_b128 v[196:199], v194 offset:19456
	ds_read_b128 v[200:203], v194 offset:20480
	ds_read_b128 v[204:207], v194 offset:21504
	ds_read_b128 v[208:211], v194 offset:22528
	ds_read_b128 v[212:215], v194 offset:23552
	global_load_lds_dwordx4 v2, s[0:1]
	s_add_i32 m0, s77, 0x2000
	s_add_u32 s78, s0, 0x100000
	s_addc_u32 s79, s1, 0
	s_add_i32 s77, s80, s10
	global_load_lds_dwordx4 v144, s[0:1]
	s_mov_b32 m0, s77
	s_nop 0
	global_load_lds_dwordx4 v2, s[78:79]
	s_add_i32 m0, s77, 0x2000
	s_nop 0
	global_load_lds_dwordx4 v144, s[78:79]
	s_mov_b32 m0, s11
	s_nop 0
	global_load_lds_dwordx4 v140, s[26:27]
	s_mov_b32 m0, s55
	s_nop 0
	global_load_lds_dwordx4 v142, s[26:27]
	s_add_u32 s100, s26, 0x80
	s_addc_u32 s101, s27, 0
	s_waitcnt vmcnt(8)
	s_waitcnt lgkmcnt(0)
	s_setprio 1
	s_barrier
	v_mfma_f32_16x16x32_bf16 v[64:67], v[132:135], v[176:179], v[64:67]
	v_mfma_f32_16x16x32_bf16 v[64:67], v[136:139], v[180:183], v[64:67]
	v_mfma_f32_16x16x32_bf16 v[60:63], v[152:155], v[176:179], v[60:63]
	v_mfma_f32_16x16x32_bf16 v[60:63], v[156:159], v[180:183], v[60:63]
	v_mfma_f32_16x16x32_bf16 v[44:47], v[152:155], v[184:187], v[44:47]
	v_mfma_f32_16x16x32_bf16 v[44:47], v[156:159], v[196:199], v[44:47]
	v_mfma_f32_16x16x32_bf16 v[48:51], v[132:135], v[184:187], v[48:51]
	v_mfma_f32_16x16x32_bf16 v[48:51], v[136:139], v[196:199], v[48:51]
	v_mfma_f32_16x16x32_bf16 v[32:35], v[132:135], v[200:203], v[32:35]
	v_mfma_f32_16x16x32_bf16 v[32:35], v[136:139], v[204:207], v[32:35]
	v_mfma_f32_16x16x32_bf16 v[28:31], v[152:155], v[200:203], v[28:31]
	v_mfma_f32_16x16x32_bf16 v[28:31], v[156:159], v[204:207], v[28:31]
	v_mfma_f32_16x16x32_bf16 v[12:15], v[152:155], v[208:211], v[12:15]
	v_mfma_f32_16x16x32_bf16 v[12:15], v[156:159], v[212:215], v[12:15]
	v_mfma_f32_16x16x32_bf16 v[16:19], v[132:135], v[208:211], v[16:19]
	v_mfma_f32_16x16x32_bf16 v[16:19], v[136:139], v[212:215], v[16:19]
	s_setprio 0
	s_setprio 1
	v_mfma_f32_16x16x32_bf16 v[56:59], v[160:163], v[176:179], v[56:59]
	v_mfma_f32_16x16x32_bf16 v[56:59], v[164:167], v[180:183], v[56:59]
	v_mfma_f32_16x16x32_bf16 v[52:55], v[168:171], v[176:179], v[52:55]
	v_mfma_f32_16x16x32_bf16 v[52:55], v[172:175], v[180:183], v[52:55]
	v_mfma_f32_16x16x32_bf16 v[36:39], v[168:171], v[184:187], v[36:39]
	v_mfma_f32_16x16x32_bf16 v[36:39], v[172:175], v[196:199], v[36:39]
	v_mfma_f32_16x16x32_bf16 v[40:43], v[160:163], v[184:187], v[40:43]
	v_mfma_f32_16x16x32_bf16 v[40:43], v[164:167], v[196:199], v[40:43]
	v_mfma_f32_16x16x32_bf16 v[24:27], v[160:163], v[200:203], v[24:27]
	v_mfma_f32_16x16x32_bf16 v[24:27], v[164:167], v[204:207], v[24:27]
	v_mfma_f32_16x16x32_bf16 v[20:23], v[168:171], v[200:203], v[20:23]
	v_mfma_f32_16x16x32_bf16 v[20:23], v[172:175], v[204:207], v[20:23]
	v_mfma_f32_16x16x32_bf16 v[4:7], v[168:171], v[208:211], v[4:7]
	v_mfma_f32_16x16x32_bf16 v[4:7], v[172:175], v[212:215], v[4:7]
	v_mfma_f32_16x16x32_bf16 v[8:11], v[160:163], v[208:211], v[8:11]
	v_mfma_f32_16x16x32_bf16 v[8:11], v[164:167], v[212:215], v[8:11]
	s_barrier
; #define PG8_STAGE(bufoff, gbase, voff) do { _Pragma("unroll") for (int _i = 0; _i < 2; ++_i) \
;         __builtin_amdgcn_global_load_lds((const unsigned*)((const char*)(gbase) + (voff)[_i]), (PG8_LAS unsigned*)(lds + (bufoff) + ldsw + _i * 8192), 16, 0, 0); } while (0)
; #define PG8_LDA(dst, b, h) do { _Pragma("unroll") for (int m = 0; m < 4; ++m) _Pragma("unroll") for (int k = 0; k < 2; ++k) dst[m][k] = *(const PG8_LAS bf16x8*)(lds + PG8_SA(b, h) + aoff + m * 2048 + k * 1024); } while (0)
; #define PG8_LDB(dst, b, h) do { _Pragma("unroll") for (int n = 0; n < 2; ++n) _Pragma("unroll") for (int k = 0; k < 2; ++k) dst[n][k] = *(const PG8_LAS bf16x8*)(lds + PG8_SB(b, h) + boff + n * 2048 + k * 1024); } while (0)
; #define PG8_MMA(ai, bj, At, Bt) do { __builtin_amdgcn_s_setprio(1); _Pragma("unroll") for (int m = 0; m < 4; ++m) _Pragma("unroll") for (int n = 0; n < 2; ++n) _Pragma("unroll") for (int k = 0; k < 2; ++k) \
;         acc[ai][bj][m][n] = __builtin_amdgcn_mfma_f32_16x16x32_bf16(Bt[n][k], At[m][k], acc[ai][bj][m][n], 0, 0, 0); __builtin_amdgcn_s_setprio(0); } while (0)
; #define PG8_WAIT_V(n) asm volatile("s_waitcnt vmcnt(" #n ")" ::: "memory")
; #define PG8_WAIT_L(n) asm volatile("s_waitcnt lgkmcnt(" #n ")" ::: "memory")
; #define PG8_BAR __builtin_amdgcn_s_barrier()
; #define PG8_SCHED __builtin_amdgcn_sched_barrier(0)
; template <class Epi, class Sched, bool ALIGN_EPI = false, bool SP2 = false>
; __device__ __forceinline__ void gemm_phase(PG8_LAS unsigned char* lds, const Gemm g, const Sched& S, const Epi& E) {
;     ...
;         for (int t = 0; t < nt; t += 2) {
;             const bool last = (t == nt - 2);
;             const char* a1 = cA + (size_t)(t + 1) * kstep;
;             const char* a2 = last ? nA : cA + (size_t)(t + 2) * kstep; const char* b2 = last ? nB : cB + (size_t)(t + 2) * kstep;
;     ...
;             PG8_LDB(B0, 1, 0); PG8_LDB(B1, 1, 1); PG8_SCHED; PG8_LDA(At, 1, 0); PG8_STAGE(PG8_SA(0, 1), a2 + hstep, voffA);
;             PG8_WAIT_V(8); PG8_WAIT_L(0); PG8_BAR; PG8_MMA(0, 0, At, B0); PG8_MMA(0, 1, At, B1); PG8_BAR; PG8_SCHED;
;             PG8_LDA(At, 1, 1); PG8_STAGE(PG8_SB(1, 0), b3, voffB); PG8_STAGE(PG8_SB(1, 1), b3 + hstep, voffB); PG8_STAGE(PG8_SA(1, 0), a3, voffA);
;             PG8_WAIT_V(8); PG8_WAIT_L(0); PG8_BAR; PG8_MMA(1, 0, At, B0); PG8_MMA(1, 1, At, B1); PG8_BAR; PG8_SCHED;
	s_setprio 0
	s_add_i32 s77, 0, 0x18000
	s_add_i32 s78, 0, 0x1c000
	ds_read_b128 v[132:135], v188 offset:32768
	ds_read_b128 v[136:139], v188 offset:33792
	ds_read_b128 v[152:155], v188 offset:34816
	ds_read_b128 v[156:159], v188 offset:35840
	ds_read_b128 v[160:163], v188 offset:49152
	ds_read_b128 v[164:167], v188 offset:50176
	ds_read_b128 v[168:171], v188 offset:51200
	ds_read_b128 v[172:175], v188 offset:52224
	s_add_u32 s26, s26, 0x100000
	s_addc_u32 s27, s27, 0
	s_mov_b32 m0, s60
	ds_read_b128 v[176:179], v194 offset:32768
	ds_read_b128 v[180:183], v194 offset:33792
	ds_read_b128 v[184:187], v194 offset:34816
	ds_read_b128 v[196:199], v194 offset:35840
	ds_read_b128 v[200:203], v194 offset:36864
	ds_read_b128 v[204:207], v194 offset:37888
	ds_read_b128 v[208:211], v194 offset:38912
	ds_read_b128 v[212:215], v194 offset:39936
	global_load_lds_dwordx4 v140, s[26:27]
	s_mov_b32 m0, s61
	s_nop 0
	global_load_lds_dwordx4 v142, s[26:27]
	s_waitcnt vmcnt(8)
	s_waitcnt lgkmcnt(0)
	s_setprio 1
	s_barrier
	v_mfma_f32_16x16x32_bf16 v[128:131], v[132:135], v[176:179], v[128:131]
	v_mfma_f32_16x16x32_bf16 v[128:131], v[136:139], v[180:183], v[128:131]
	v_mfma_f32_16x16x32_bf16 v[124:127], v[152:155], v[176:179], v[124:127]
	v_mfma_f32_16x16x32_bf16 v[124:127], v[156:159], v[180:183], v[124:127]
	v_mfma_f32_16x16x32_bf16 v[108:111], v[152:155], v[184:187], v[108:111]
	v_mfma_f32_16x16x32_bf16 v[108:111], v[156:159], v[196:199], v[108:111]
	v_mfma_f32_16x16x32_bf16 v[112:115], v[132:135], v[184:187], v[112:115]
	v_mfma_f32_16x16x32_bf16 v[112:115], v[136:139], v[196:199], v[112:115]
	v_mfma_f32_16x16x32_bf16 v[96:99], v[132:135], v[200:203], v[96:99]
	v_mfma_f32_16x16x32_bf16 v[96:99], v[136:139], v[204:207], v[96:99]
	v_mfma_f32_16x16x32_bf16 v[92:95], v[152:155], v[200:203], v[92:95]
	v_mfma_f32_16x16x32_bf16 v[92:95], v[156:159], v[204:207], v[92:95]
	v_mfma_f32_16x16x32_bf16 v[76:79], v[152:155], v[208:211], v[76:79]
	v_mfma_f32_16x16x32_bf16 v[76:79], v[156:159], v[212:215], v[76:79]
	v_mfma_f32_16x16x32_bf16 v[80:83], v[132:135], v[208:211], v[80:83]
	v_mfma_f32_16x16x32_bf16 v[80:83], v[136:139], v[212:215], v[80:83]
	s_setprio 0
	s_setprio 1
	v_mfma_f32_16x16x32_bf16 v[120:123], v[160:163], v[176:179], v[120:123]
	v_mfma_f32_16x16x32_bf16 v[120:123], v[164:167], v[180:183], v[120:123]
	v_mfma_f32_16x16x32_bf16 v[116:119], v[168:171], v[176:179], v[116:119]
	v_mfma_f32_16x16x32_bf16 v[116:119], v[172:175], v[180:183], v[116:119]
	v_mfma_f32_16x16x32_bf16 v[100:103], v[168:171], v[184:187], v[100:103]
	v_mfma_f32_16x16x32_bf16 v[100:103], v[172:175], v[196:199], v[100:103]
	v_mfma_f32_16x16x32_bf16 v[104:107], v[160:163], v[184:187], v[104:107]
	v_mfma_f32_16x16x32_bf16 v[104:107], v[164:167], v[196:199], v[104:107]
	v_mfma_f32_16x16x32_bf16 v[88:91], v[160:163], v[200:203], v[88:91]
	v_mfma_f32_16x16x32_bf16 v[88:91], v[164:167], v[204:207], v[88:91]
	v_mfma_f32_16x16x32_bf16 v[84:87], v[168:171], v[200:203], v[84:87]
	v_mfma_f32_16x16x32_bf16 v[84:87], v[172:175], v[204:207], v[84:87]
	v_mfma_f32_16x16x32_bf16 v[68:71], v[168:171], v[208:211], v[68:71]
	v_mfma_f32_16x16x32_bf16 v[68:71], v[172:175], v[212:215], v[68:71]
	v_mfma_f32_16x16x32_bf16 v[72:75], v[160:163], v[208:211], v[72:75]
	v_mfma_f32_16x16x32_bf16 v[72:75], v[164:167], v[212:215], v[72:75]
	s_barrier
	s_setprio 0
	s_add_i32 s26, s77, s10
	s_mov_b32 m0, s26
	ds_read_b128 v[176:179], v194 offset:49152
	ds_read_b128 v[180:183], v194 offset:50176
	ds_read_b128 v[184:187], v194 offset:51200
	ds_read_b128 v[196:199], v194 offset:52224
	ds_read_b128 v[200:203], v194 offset:53248
	ds_read_b128 v[204:207], v194 offset:54272
	ds_read_b128 v[208:211], v194 offset:55296
	ds_read_b128 v[212:215], v194 offset:56320
	s_add_u32 s0, s0, 0x80
	s_addc_u32 s1, s1, 0
	global_load_lds_dwordx4 v2, s[0:1]
	s_add_i32 m0, s26, 0x2000
	s_add_i32 s26, s78, s10
	global_load_lds_dwordx4 v144, s[0:1]
	s_add_u32 s0, s0, 0x100000
	s_addc_u32 s1, s1, 0
	s_mov_b32 m0, s26
	s_nop 0
	global_load_lds_dwordx4 v2, s[0:1]
	s_add_i32 m0, s26, 0x2000
	s_nop 0
	global_load_lds_dwordx4 v144, s[0:1]
	s_mov_b32 m0, s62
	s_nop 0
	global_load_lds_dwordx4 v140, s[100:101]
	s_mov_b32 m0, s63
	s_nop 0
	global_load_lds_dwordx4 v142, s[100:101]
	s_waitcnt vmcnt(8)
	s_waitcnt lgkmcnt(0)
	s_setprio 1
	s_barrier
	v_mfma_f32_16x16x32_bf16 v[64:67], v[132:135], v[176:179], v[64:67]
	v_mfma_f32_16x16x32_bf16 v[64:67], v[136:139], v[180:183], v[64:67]
	v_mfma_f32_16x16x32_bf16 v[60:63], v[152:155], v[176:179], v[60:63]
	v_mfma_f32_16x16x32_bf16 v[60:63], v[156:159], v[180:183], v[60:63]
	v_mfma_f32_16x16x32_bf16 v[44:47], v[152:155], v[184:187], v[44:47]
	v_mfma_f32_16x16x32_bf16 v[44:47], v[156:159], v[196:199], v[44:47]
	v_mfma_f32_16x16x32_bf16 v[48:51], v[132:135], v[184:187], v[48:51]
	v_mfma_f32_16x16x32_bf16 v[48:51], v[136:139], v[196:199], v[48:51]
	v_mfma_f32_16x16x32_bf16 v[32:35], v[132:135], v[200:203], v[32:35]
	v_mfma_f32_16x16x32_bf16 v[32:35], v[136:139], v[204:207], v[32:35]
	v_mfma_f32_16x16x32_bf16 v[28:31], v[152:155], v[200:203], v[28:31]
	v_mfma_f32_16x16x32_bf16 v[28:31], v[156:159], v[204:207], v[28:31]
	v_mfma_f32_16x16x32_bf16 v[12:15], v[152:155], v[208:211], v[12:15]
	v_mfma_f32_16x16x32_bf16 v[12:15], v[156:159], v[212:215], v[12:15]
	v_mfma_f32_16x16x32_bf16 v[16:19], v[132:135], v[208:211], v[16:19]
	v_mfma_f32_16x16x32_bf16 v[16:19], v[136:139], v[212:215], v[16:19]
	s_setprio 0
	s_setprio 1
	v_mfma_f32_16x16x32_bf16 v[56:59], v[160:163], v[176:179], v[56:59]
	v_mfma_f32_16x16x32_bf16 v[56:59], v[164:167], v[180:183], v[56:59]
	v_mfma_f32_16x16x32_bf16 v[52:55], v[168:171], v[176:179], v[52:55]
	v_mfma_f32_16x16x32_bf16 v[52:55], v[172:175], v[180:183], v[52:55]
	v_mfma_f32_16x16x32_bf16 v[36:39], v[168:171], v[184:187], v[36:39]
	v_mfma_f32_16x16x32_bf16 v[36:39], v[172:175], v[196:199], v[36:39]
	v_mfma_f32_16x16x32_bf16 v[40:43], v[160:163], v[184:187], v[40:43]
	v_mfma_f32_16x16x32_bf16 v[40:43], v[164:167], v[196:199], v[40:43]
	v_mfma_f32_16x16x32_bf16 v[24:27], v[160:163], v[200:203], v[24:27]
	v_mfma_f32_16x16x32_bf16 v[24:27], v[164:167], v[204:207], v[24:27]
	v_mfma_f32_16x16x32_bf16 v[20:23], v[168:171], v[200:203], v[20:23]
	v_mfma_f32_16x16x32_bf16 v[20:23], v[172:175], v[204:207], v[20:23]
	v_mfma_f32_16x16x32_bf16 v[4:7], v[168:171], v[208:211], v[4:7]
	v_mfma_f32_16x16x32_bf16 v[4:7], v[172:175], v[212:215], v[4:7]
	v_mfma_f32_16x16x32_bf16 v[8:11], v[160:163], v[208:211], v[8:11]
	v_mfma_f32_16x16x32_bf16 v[8:11], v[164:167], v[212:215], v[8:11]
	s_barrier
	s_setprio 0
	s_add_i32 s76, s76, 2
	s_add_u32 s40, s40, 0x100
	s_addc_u32 s41, s41, 0
	s_add_u32 s58, s58, 0x100
	s_addc_u32 s59, s59, 0
	s_cmp_gt_u32 s76, 61
	s_cbranch_scc0 .LBB0_2115
	s_and_b64 vcc, exec, s[36:37]
	s_cbranch_vccz .LBB0_2118
	s_barrier

; #define PG8_STAGE(bufoff, gbase, voff) do { _Pragma("unroll") for (int _i = 0; _i < 2; ++_i) \
;         __builtin_amdgcn_global_load_lds((const unsigned*)((const char*)(gbase) + (voff)[_i]), (PG8_LAS unsigned*)(lds + (bufoff) + ldsw + _i * 8192), 16, 0, 0); } while (0)
; #define PG8_LDA(dst, b, h) do { _Pragma("unroll") for (int m = 0; m < 4; ++m) _Pragma("unroll") for (int k = 0; k < 2; ++k) dst[m][k] = *(const PG8_LAS bf16x8*)(lds + PG8_SA(b, h) + aoff + m * 2048 + k * 1024); } while (0)
; #define PG8_LDB(dst, b, h) do { _Pragma("unroll") for (int n = 0; n < 2; ++n) _Pragma("unroll") for (int k = 0; k < 2; ++k) dst[n][k] = *(const PG8_LAS bf16x8*)(lds + PG8_SB(b, h) + boff + n * 2048 + k * 1024); } while (0)
; #define PG8_MMA(ai, bj, At, Bt) do { __builtin_amdgcn_s_setprio(1); _Pragma("unroll") for (int m = 0; m < 4; ++m) _Pragma("unroll") for (int n = 0; n < 2; ++n) _Pragma("unroll") for (int k = 0; k < 2; ++k) \
;         acc[ai][bj][m][n] = __builtin_amdgcn_mfma_f32_16x16x32_bf16(Bt[n][k], At[m][k], acc[ai][bj][m][n], 0, 0, 0); __builtin_amdgcn_s_setprio(0); } while (0)
; #define PG8_WAIT_V(n) asm volatile("s_waitcnt vmcnt(" #n ")" ::: "memory")
; #define PG8_WAIT_L(n) asm volatile("s_waitcnt lgkmcnt(" #n ")" ::: "memory")
; template <class Epi, class Sched, bool ALIGN_EPI = false, bool SP2 = false>
; __device__ __forceinline__ void gemm_phase(PG8_LAS unsigned char* lds, const Gemm g, const Sched& S, const Epi& E) {
;     ...
;             const bool last = (t == nt - 2);
;             const char* a1 = cA + (size_t)(t + 1) * kstep;
;             const char* a2 = last ? nA : cA + (size_t)(t + 2) * kstep; const char* b2 = last ? nB : cB + (size_t)(t + 2) * kstep;
;             const char* a3 = a2 + kstep; const char* b3 = b2 + kstep;
;             if (last && has_next) S.a_ready(nxt);
;             if constexpr (SP2) {
;             PG8_LDB(B0, 0, 0); PG8_LDB(B1, 0, 1); PG8_SCHED; PG8_LDA(At, 0, 0); PG8_STAGE(PG8_SA(1, 1), a1 + hstep, voffA);
;             PG8_WAIT_V(8); PG8_WAIT_L(0); PG8_BAR; PG8_MMA(0, 0, At, B0); PG8_MMA(0, 1, At, B1); PG8_BAR; PG8_SCHED;
;             PG8_LDA(At, 0, 1); PG8_STAGE(PG8_SB(0, 0), b2, voffB); PG8_STAGE(PG8_SB(0, 1), b2 + hstep, voffB); PG8_STAGE(PG8_SA(0, 0), a2, voffA);
;             PG8_WAIT_V(8); PG8_WAIT_L(0); PG8_BAR; PG8_MMA(1, 0, At, B0); PG8_MMA(1, 1, At, B1); PG8_BAR; PG8_SCHED;
.LBB0_2692:
	s_add_u32 s0, s56, 0xfffe0080
	s_addc_u32 s1, s57, -1
	s_add_i32 s63, 0, 0x10000
	s_cmp_eq_u32 s62, 4
	s_cselect_b32 s27, s51, s1
	s_cselect_b32 s26, s50, s0
	s_cselect_b32 s1, s53, s49
	s_cselect_b32 s0, s52, s47
	s_add_i32 s66, 0, 0x14000
	ds_read_b128 v[142:145], v210
	ds_read_b128 v[150:153], v210 offset:1024
	ds_read_b128 v[154:157], v210 offset:2048
	ds_read_b128 v[158:161], v210 offset:3072
	ds_read_b128 v[162:165], v210 offset:16384
	ds_read_b128 v[166:169], v210 offset:17408
	ds_read_b128 v[170:173], v210 offset:18432
	ds_read_b128 v[174:177], v210 offset:19456
	s_add_i32 m0, s10, 0xc000
	ds_read_b128 v[178:181], v149
	ds_read_b128 v[182:185], v149 offset:1024
	ds_read_b128 v[186:189], v149 offset:2048
	ds_read_b128 v[190:193], v149 offset:3072
	ds_read_b128 v[194:197], v149 offset:4096
	ds_read_b128 v[198:201], v149 offset:5120
	ds_read_b128 v[202:205], v149 offset:6144
	ds_read_b128 v[206:209], v149 offset:7168
	global_load_lds_dwordx4 v138, s[56:57]
	s_add_i32 m0, s10, 0xe000
	s_nop 0
	global_load_lds_dwordx4 v140, s[56:57]
	s_waitcnt vmcnt(8)
	s_waitcnt lgkmcnt(0)
	s_setprio 1
	s_barrier
	v_mfma_f32_16x16x32_bf16 v[128:131], v[142:145], v[178:181], v[128:131]
	v_mfma_f32_16x16x32_bf16 v[128:131], v[150:153], v[182:185], v[128:131]
	v_mfma_f32_16x16x32_bf16 v[124:127], v[154:157], v[178:181], v[124:127]
	v_mfma_f32_16x16x32_bf16 v[124:127], v[158:161], v[182:185], v[124:127]
	v_mfma_f32_16x16x32_bf16 v[108:111], v[154:157], v[186:189], v[108:111]
	v_mfma_f32_16x16x32_bf16 v[108:111], v[158:161], v[190:193], v[108:111]
	v_mfma_f32_16x16x32_bf16 v[112:115], v[142:145], v[186:189], v[112:115]
	v_mfma_f32_16x16x32_bf16 v[112:115], v[150:153], v[190:193], v[112:115]
	v_mfma_f32_16x16x32_bf16 v[96:99], v[142:145], v[194:197], v[96:99]
	v_mfma_f32_16x16x32_bf16 v[96:99], v[150:153], v[198:201], v[96:99]
	v_mfma_f32_16x16x32_bf16 v[92:95], v[154:157], v[194:197], v[92:95]
	v_mfma_f32_16x16x32_bf16 v[92:95], v[158:161], v[198:201], v[92:95]
	v_mfma_f32_16x16x32_bf16 v[76:79], v[154:157], v[202:205], v[76:79]
	v_mfma_f32_16x16x32_bf16 v[76:79], v[158:161], v[206:209], v[76:79]
	v_mfma_f32_16x16x32_bf16 v[80:83], v[142:145], v[202:205], v[80:83]
	v_mfma_f32_16x16x32_bf16 v[80:83], v[150:153], v[206:209], v[80:83]
	s_setprio 0
	s_setprio 1
	v_mfma_f32_16x16x32_bf16 v[120:123], v[162:165], v[178:181], v[120:123]
	v_mfma_f32_16x16x32_bf16 v[120:123], v[166:169], v[182:185], v[120:123]
	v_mfma_f32_16x16x32_bf16 v[116:119], v[170:173], v[178:181], v[116:119]
	v_mfma_f32_16x16x32_bf16 v[116:119], v[174:177], v[182:185], v[116:119]
	v_mfma_f32_16x16x32_bf16 v[100:103], v[170:173], v[186:189], v[100:103]
	v_mfma_f32_16x16x32_bf16 v[100:103], v[174:177], v[190:193], v[100:103]
	v_mfma_f32_16x16x32_bf16 v[104:107], v[162:165], v[186:189], v[104:107]
	v_mfma_f32_16x16x32_bf16 v[104:107], v[166:169], v[190:193], v[104:107]
	v_mfma_f32_16x16x32_bf16 v[88:91], v[162:165], v[194:197], v[88:91]
	v_mfma_f32_16x16x32_bf16 v[88:91], v[166:169], v[198:201], v[88:91]
	v_mfma_f32_16x16x32_bf16 v[84:87], v[170:173], v[194:197], v[84:87]
	v_mfma_f32_16x16x32_bf16 v[84:87], v[174:177], v[198:201], v[84:87]
	v_mfma_f32_16x16x32_bf16 v[68:71], v[170:173], v[202:205], v[68:71]
	v_mfma_f32_16x16x32_bf16 v[68:71], v[174:177], v[206:209], v[68:71]
	v_mfma_f32_16x16x32_bf16 v[72:75], v[162:165], v[202:205], v[72:75]
	v_mfma_f32_16x16x32_bf16 v[72:75], v[166:169], v[206:209], v[72:75]
	s_barrier
	s_setprio 0
	s_add_i32 s63, s63, s9
	s_mov_b32 m0, s63
	ds_read_b128 v[178:181], v149 offset:16384
	ds_read_b128 v[182:185], v149 offset:17408
	ds_read_b128 v[186:189], v149 offset:18432
	ds_read_b128 v[190:193], v149 offset:19456
	ds_read_b128 v[194:197], v149 offset:20480
	ds_read_b128 v[198:201], v149 offset:21504
	ds_read_b128 v[202:205], v149 offset:22528
	ds_read_b128 v[206:209], v149 offset:23552
	global_load_lds_dwordx4 v2, s[0:1]
	s_add_i32 m0, s63, 0x2000
	s_add_u32 s64, s0, 0x20000
	s_addc_u32 s65, s1, 0
	s_add_i32 s63, s66, s9
	global_load_lds_dwordx4 v136, s[0:1]
	s_mov_b32 m0, s63
	s_nop 0
	global_load_lds_dwordx4 v2, s[64:65]
	s_add_i32 m0, s63, 0x2000
	s_nop 0
	global_load_lds_dwordx4 v136, s[64:65]
	s_mov_b32 m0, s10
	s_nop 0
	global_load_lds_dwordx4 v132, s[26:27]
	s_mov_b32 m0, s11
	s_nop 0
	global_load_lds_dwordx4 v134, s[26:27]
	s_add_u32 s100, s26, 0x80
	s_addc_u32 s101, s27, 0
	s_waitcnt vmcnt(8)
	s_waitcnt lgkmcnt(0)
	s_setprio 1
	s_barrier
	v_mfma_f32_16x16x32_bf16 v[64:67], v[142:145], v[178:181], v[64:67]
	v_mfma_f32_16x16x32_bf16 v[64:67], v[150:153], v[182:185], v[64:67]
	v_mfma_f32_16x16x32_bf16 v[60:63], v[154:157], v[178:181], v[60:63]
	v_mfma_f32_16x16x32_bf16 v[60:63], v[158:161], v[182:185], v[60:63]
	v_mfma_f32_16x16x32_bf16 v[44:47], v[154:157], v[186:189], v[44:47]
	v_mfma_f32_16x16x32_bf16 v[44:47], v[158:161], v[190:193], v[44:47]
	v_mfma_f32_16x16x32_bf16 v[48:51], v[142:145], v[186:189], v[48:51]
	v_mfma_f32_16x16x32_bf16 v[48:51], v[150:153], v[190:193], v[48:51]
	v_mfma_f32_16x16x32_bf16 v[32:35], v[142:145], v[194:197], v[32:35]
	v_mfma_f32_16x16x32_bf16 v[32:35], v[150:153], v[198:201], v[32:35]
	v_mfma_f32_16x16x32_bf16 v[28:31], v[154:157], v[194:197], v[28:31]
	v_mfma_f32_16x16x32_bf16 v[28:31], v[158:161], v[198:201], v[28:31]
	v_mfma_f32_16x16x32_bf16 v[12:15], v[154:157], v[202:205], v[12:15]
	v_mfma_f32_16x16x32_bf16 v[12:15], v[158:161], v[206:209], v[12:15]
	v_mfma_f32_16x16x32_bf16 v[16:19], v[142:145], v[202:205], v[16:19]
	v_mfma_f32_16x16x32_bf16 v[16:19], v[150:153], v[206:209], v[16:19]
	s_setprio 0
	s_setprio 1
	v_mfma_f32_16x16x32_bf16 v[56:59], v[162:165], v[178:181], v[56:59]
	v_mfma_f32_16x16x32_bf16 v[56:59], v[166:169], v[182:185], v[56:59]
	v_mfma_f32_16x16x32_bf16 v[52:55], v[170:173], v[178:181], v[52:55]
	v_mfma_f32_16x16x32_bf16 v[52:55], v[174:177], v[182:185], v[52:55]
	v_mfma_f32_16x16x32_bf16 v[36:39], v[170:173], v[186:189], v[36:39]
	v_mfma_f32_16x16x32_bf16 v[36:39], v[174:177], v[190:193], v[36:39]
	v_mfma_f32_16x16x32_bf16 v[40:43], v[162:165], v[186:189], v[40:43]
	v_mfma_f32_16x16x32_bf16 v[40:43], v[166:169], v[190:193], v[40:43]
	v_mfma_f32_16x16x32_bf16 v[24:27], v[162:165], v[194:197], v[24:27]
	v_mfma_f32_16x16x32_bf16 v[24:27], v[166:169], v[198:201], v[24:27]
	v_mfma_f32_16x16x32_bf16 v[20:23], v[170:173], v[194:197], v[20:23]
	v_mfma_f32_16x16x32_bf16 v[20:23], v[174:177], v[198:201], v[20:23]
	v_mfma_f32_16x16x32_bf16 v[4:7], v[170:173], v[202:205], v[4:7]
	v_mfma_f32_16x16x32_bf16 v[4:7], v[174:177], v[206:209], v[4:7]
	v_mfma_f32_16x16x32_bf16 v[8:11], v[162:165], v[202:205], v[8:11]
	v_mfma_f32_16x16x32_bf16 v[8:11], v[166:169], v[206:209], v[8:11]
	s_barrier
; #define PG8_STAGE(bufoff, gbase, voff) do { _Pragma("unroll") for (int _i = 0; _i < 2; ++_i) \
;         __builtin_amdgcn_global_load_lds((const unsigned*)((const char*)(gbase) + (voff)[_i]), (PG8_LAS unsigned*)(lds + (bufoff) + ldsw + _i * 8192), 16, 0, 0); } while (0)
; #define PG8_LDA(dst, b, h) do { _Pragma("unroll") for (int m = 0; m < 4; ++m) _Pragma("unroll") for (int k = 0; k < 2; ++k) dst[m][k] = *(const PG8_LAS bf16x8*)(lds + PG8_SA(b, h) + aoff + m * 2048 + k * 1024); } while (0)
; #define PG8_LDB(dst, b, h) do { _Pragma("unroll") for (int n = 0; n < 2; ++n) _Pragma("unroll") for (int k = 0; k < 2; ++k) dst[n][k] = *(const PG8_LAS bf16x8*)(lds + PG8_SB(b, h) + boff + n * 2048 + k * 1024); } while (0)
; #define PG8_MMA(ai, bj, At, Bt) do { __builtin_amdgcn_s_setprio(1); _Pragma("unroll") for (int m = 0; m < 4; ++m) _Pragma("unroll") for (int n = 0; n < 2; ++n) _Pragma("unroll") for (int k = 0; k < 2; ++k) \
;         acc[ai][bj][m][n] = __builtin_amdgcn_mfma_f32_16x16x32_bf16(Bt[n][k], At[m][k], acc[ai][bj][m][n], 0, 0, 0); __builtin_amdgcn_s_setprio(0); } while (0)
; #define PG8_WAIT_V(n) asm volatile("s_waitcnt vmcnt(" #n ")" ::: "memory")
; #define PG8_WAIT_L(n) asm volatile("s_waitcnt lgkmcnt(" #n ")" ::: "memory")
; #define PG8_BAR __builtin_amdgcn_s_barrier()
; #define PG8_SCHED __builtin_amdgcn_sched_barrier(0)
; template <class Epi, class Sched, bool ALIGN_EPI = false, bool SP2 = false>
; __device__ __forceinline__ void gemm_phase(PG8_LAS unsigned char* lds, const Gemm g, const Sched& S, const Epi& E) {
;     ...
;         for (int t = 0; t < nt; t += 2) {
;             const bool last = (t == nt - 2);
;             const char* a1 = cA + (size_t)(t + 1) * kstep;
;             const char* a2 = last ? nA : cA + (size_t)(t + 2) * kstep; const char* b2 = last ? nB : cB + (size_t)(t + 2) * kstep;
;     ...
;             PG8_LDB(B0, 1, 0); PG8_LDB(B1, 1, 1); PG8_SCHED; PG8_LDA(At, 1, 0); PG8_STAGE(PG8_SA(0, 1), a2 + hstep, voffA);
;             PG8_WAIT_V(8); PG8_WAIT_L(0); PG8_BAR; PG8_MMA(0, 0, At, B0); PG8_MMA(0, 1, At, B1); PG8_BAR; PG8_SCHED;
;             PG8_LDA(At, 1, 1); PG8_STAGE(PG8_SB(1, 0), b3, voffB); PG8_STAGE(PG8_SB(1, 1), b3 + hstep, voffB); PG8_STAGE(PG8_SA(1, 0), a3, voffA);
;             PG8_WAIT_V(8); PG8_WAIT_L(0); PG8_BAR; PG8_MMA(1, 0, At, B0); PG8_MMA(1, 1, At, B1); PG8_BAR; PG8_SCHED;
	s_setprio 0
	s_add_i32 s63, 0, 0x18000
	s_add_i32 s64, 0, 0x1c000
	ds_read_b128 v[142:145], v210 offset:32768
	ds_read_b128 v[150:153], v210 offset:33792
	ds_read_b128 v[154:157], v210 offset:34816
	ds_read_b128 v[158:161], v210 offset:35840
	ds_read_b128 v[162:165], v210 offset:49152
	ds_read_b128 v[166:169], v210 offset:50176
	ds_read_b128 v[170:173], v210 offset:51200
	ds_read_b128 v[174:177], v210 offset:52224
	s_add_u32 s26, s26, 0x20000
	s_addc_u32 s27, s27, 0
	s_mov_b32 m0, s25
	ds_read_b128 v[178:181], v149 offset:32768
	ds_read_b128 v[182:185], v149 offset:33792
	ds_read_b128 v[186:189], v149 offset:34816
	ds_read_b128 v[190:193], v149 offset:35840
	ds_read_b128 v[194:197], v149 offset:36864
	ds_read_b128 v[198:201], v149 offset:37888
	ds_read_b128 v[202:205], v149 offset:38912
	ds_read_b128 v[206:209], v149 offset:39936
	global_load_lds_dwordx4 v132, s[26:27]
	s_mov_b32 m0, s55
	s_nop 0
	global_load_lds_dwordx4 v134, s[26:27]
	s_waitcnt vmcnt(8)
	s_waitcnt lgkmcnt(0)
	s_setprio 1
	s_barrier
	v_mfma_f32_16x16x32_bf16 v[128:131], v[142:145], v[178:181], v[128:131]
	v_mfma_f32_16x16x32_bf16 v[128:131], v[150:153], v[182:185], v[128:131]
	v_mfma_f32_16x16x32_bf16 v[124:127], v[154:157], v[178:181], v[124:127]
	v_mfma_f32_16x16x32_bf16 v[124:127], v[158:161], v[182:185], v[124:127]
	v_mfma_f32_16x16x32_bf16 v[108:111], v[154:157], v[186:189], v[108:111]
	v_mfma_f32_16x16x32_bf16 v[108:111], v[158:161], v[190:193], v[108:111]
	v_mfma_f32_16x16x32_bf16 v[112:115], v[142:145], v[186:189], v[112:115]
	v_mfma_f32_16x16x32_bf16 v[112:115], v[150:153], v[190:193], v[112:115]
	v_mfma_f32_16x16x32_bf16 v[96:99], v[142:145], v[194:197], v[96:99]
	v_mfma_f32_16x16x32_bf16 v[96:99], v[150:153], v[198:201], v[96:99]
	v_mfma_f32_16x16x32_bf16 v[92:95], v[154:157], v[194:197], v[92:95]
	v_mfma_f32_16x16x32_bf16 v[92:95], v[158:161], v[198:201], v[92:95]
	v_mfma_f32_16x16x32_bf16 v[76:79], v[154:157], v[202:205], v[76:79]
	v_mfma_f32_16x16x32_bf16 v[76:79], v[158:161], v[206:209], v[76:79]
	v_mfma_f32_16x16x32_bf16 v[80:83], v[142:145], v[202:205], v[80:83]
	v_mfma_f32_16x16x32_bf16 v[80:83], v[150:153], v[206:209], v[80:83]
	s_setprio 0
	s_setprio 1
	v_mfma_f32_16x16x32_bf16 v[120:123], v[162:165], v[178:181], v[120:123]
	v_mfma_f32_16x16x32_bf16 v[120:123], v[166:169], v[182:185], v[120:123]
	v_mfma_f32_16x16x32_bf16 v[116:119], v[170:173], v[178:181], v[116:119]
	v_mfma_f32_16x16x32_bf16 v[116:119], v[174:177], v[182:185], v[116:119]
	v_mfma_f32_16x16x32_bf16 v[100:103], v[170:173], v[186:189], v[100:103]
	v_mfma_f32_16x16x32_bf16 v[100:103], v[174:177], v[190:193], v[100:103]
	v_mfma_f32_16x16x32_bf16 v[104:107], v[162:165], v[186:189], v[104:107]
	v_mfma_f32_16x16x32_bf16 v[104:107], v[166:169], v[190:193], v[104:107]
	v_mfma_f32_16x16x32_bf16 v[88:91], v[162:165], v[194:197], v[88:91]
	v_mfma_f32_16x16x32_bf16 v[88:91], v[166:169], v[198:201], v[88:91]
	v_mfma_f32_16x16x32_bf16 v[84:87], v[170:173], v[194:197], v[84:87]
	v_mfma_f32_16x16x32_bf16 v[84:87], v[174:177], v[198:201], v[84:87]
	v_mfma_f32_16x16x32_bf16 v[68:71], v[170:173], v[202:205], v[68:71]
	v_mfma_f32_16x16x32_bf16 v[68:71], v[174:177], v[206:209], v[68:71]
	v_mfma_f32_16x16x32_bf16 v[72:75], v[162:165], v[202:205], v[72:75]
	v_mfma_f32_16x16x32_bf16 v[72:75], v[166:169], v[206:209], v[72:75]
	s_barrier
	s_setprio 0
	s_add_i32 s26, s63, s9
	s_mov_b32 m0, s26
	ds_read_b128 v[178:181], v149 offset:49152
	ds_read_b128 v[182:185], v149 offset:50176
	ds_read_b128 v[186:189], v149 offset:51200
	ds_read_b128 v[190:193], v149 offset:52224
	ds_read_b128 v[194:197], v149 offset:53248
	ds_read_b128 v[198:201], v149 offset:54272
	ds_read_b128 v[202:205], v149 offset:55296
	ds_read_b128 v[206:209], v149 offset:56320
	s_add_u32 s0, s0, 0x80
	s_addc_u32 s1, s1, 0
	global_load_lds_dwordx4 v2, s[0:1]
	s_add_i32 m0, s26, 0x2000
	s_add_i32 s26, s64, s9
	global_load_lds_dwordx4 v136, s[0:1]
	s_add_u32 s0, s0, 0x20000
	s_addc_u32 s1, s1, 0
	s_mov_b32 m0, s26
	s_nop 0
	global_load_lds_dwordx4 v2, s[0:1]
	s_add_i32 m0, s26, 0x2000
	s_nop 0
	global_load_lds_dwordx4 v136, s[0:1]
	s_mov_b32 m0, s58
	s_nop 0
	global_load_lds_dwordx4 v132, s[100:101]
	s_mov_b32 m0, s59
	s_nop 0
	global_load_lds_dwordx4 v134, s[100:101]
	s_waitcnt vmcnt(8)
	s_waitcnt lgkmcnt(0)
	s_setprio 1
	s_barrier
	v_mfma_f32_16x16x32_bf16 v[64:67], v[142:145], v[178:181], v[64:67]
	v_mfma_f32_16x16x32_bf16 v[64:67], v[150:153], v[182:185], v[64:67]
	v_mfma_f32_16x16x32_bf16 v[60:63], v[154:157], v[178:181], v[60:63]
	v_mfma_f32_16x16x32_bf16 v[60:63], v[158:161], v[182:185], v[60:63]
	v_mfma_f32_16x16x32_bf16 v[44:47], v[154:157], v[186:189], v[44:47]
	v_mfma_f32_16x16x32_bf16 v[44:47], v[158:161], v[190:193], v[44:47]
	v_mfma_f32_16x16x32_bf16 v[48:51], v[142:145], v[186:189], v[48:51]
	v_mfma_f32_16x16x32_bf16 v[48:51], v[150:153], v[190:193], v[48:51]
	v_mfma_f32_16x16x32_bf16 v[32:35], v[142:145], v[194:197], v[32:35]
	v_mfma_f32_16x16x32_bf16 v[32:35], v[150:153], v[198:201], v[32:35]
	v_mfma_f32_16x16x32_bf16 v[28:31], v[154:157], v[194:197], v[28:31]
	v_mfma_f32_16x16x32_bf16 v[28:31], v[158:161], v[198:201], v[28:31]
	v_mfma_f32_16x16x32_bf16 v[12:15], v[154:157], v[202:205], v[12:15]
	v_mfma_f32_16x16x32_bf16 v[12:15], v[158:161], v[206:209], v[12:15]
	v_mfma_f32_16x16x32_bf16 v[16:19], v[142:145], v[202:205], v[16:19]
	v_mfma_f32_16x16x32_bf16 v[16:19], v[150:153], v[206:209], v[16:19]
	s_setprio 0
	s_setprio 1
	v_mfma_f32_16x16x32_bf16 v[56:59], v[162:165], v[178:181], v[56:59]
	v_mfma_f32_16x16x32_bf16 v[56:59], v[166:169], v[182:185], v[56:59]
	v_mfma_f32_16x16x32_bf16 v[52:55], v[170:173], v[178:181], v[52:55]
	v_mfma_f32_16x16x32_bf16 v[52:55], v[174:177], v[182:185], v[52:55]
	v_mfma_f32_16x16x32_bf16 v[36:39], v[170:173], v[186:189], v[36:39]
	v_mfma_f32_16x16x32_bf16 v[36:39], v[174:177], v[190:193], v[36:39]
	v_mfma_f32_16x16x32_bf16 v[40:43], v[162:165], v[186:189], v[40:43]
	v_mfma_f32_16x16x32_bf16 v[40:43], v[166:169], v[190:193], v[40:43]
	v_mfma_f32_16x16x32_bf16 v[24:27], v[162:165], v[194:197], v[24:27]
	v_mfma_f32_16x16x32_bf16 v[24:27], v[166:169], v[198:201], v[24:27]
	v_mfma_f32_16x16x32_bf16 v[20:23], v[170:173], v[194:197], v[20:23]
	v_mfma_f32_16x16x32_bf16 v[20:23], v[174:177], v[198:201], v[20:23]
	v_mfma_f32_16x16x32_bf16 v[4:7], v[170:173], v[202:205], v[4:7]
	v_mfma_f32_16x16x32_bf16 v[4:7], v[174:177], v[206:209], v[4:7]
	v_mfma_f32_16x16x32_bf16 v[8:11], v[162:165], v[202:205], v[8:11]
	v_mfma_f32_16x16x32_bf16 v[8:11], v[166:169], v[206:209], v[8:11]
	s_barrier
	s_setprio 0
	s_add_i32 s62, s62, 2
	s_add_u32 s56, s56, 0x100
	s_addc_u32 s57, s57, 0
	s_add_u32 s47, s47, 0x100
	s_addc_u32 s49, s49, 0
	s_cmp_gt_u32 s62, 5
	s_cbranch_scc0 .LBB0_2692
	s_and_b64 vcc, exec, s[44:45]
	s_cbranch_vccz .LBB0_2695
	s_barrier

; #define PG8_STAGE(bufoff, gbase, voff) do { _Pragma("unroll") for (int _i = 0; _i < 2; ++_i) \
;         __builtin_amdgcn_global_load_lds((const unsigned*)((const char*)(gbase) + (voff)[_i]), (PG8_LAS unsigned*)(lds + (bufoff) + ldsw + _i * 8192), 16, 0, 0); } while (0)
; #define PG8_LDA(dst, b, h) do { _Pragma("unroll") for (int m = 0; m < 4; ++m) _Pragma("unroll") for (int k = 0; k < 2; ++k) dst[m][k] = *(const PG8_LAS bf16x8*)(lds + PG8_SA(b, h) + aoff + m * 2048 + k * 1024); } while (0)
; #define PG8_LDB(dst, b, h) do { _Pragma("unroll") for (int n = 0; n < 2; ++n) _Pragma("unroll") for (int k = 0; k < 2; ++k) dst[n][k] = *(const PG8_LAS bf16x8*)(lds + PG8_SB(b, h) + boff + n * 2048 + k * 1024); } while (0)
; #define PG8_MMA(ai, bj, At, Bt) do { __builtin_amdgcn_s_setprio(1); _Pragma("unroll") for (int m = 0; m < 4; ++m) _Pragma("unroll") for (int n = 0; n < 2; ++n) _Pragma("unroll") for (int k = 0; k < 2; ++k) \
;         acc[ai][bj][m][n] = __builtin_amdgcn_mfma_f32_16x16x32_bf16(Bt[n][k], At[m][k], acc[ai][bj][m][n], 0, 0, 0); __builtin_amdgcn_s_setprio(0); } while (0)
; #define PG8_WAIT_V(n) asm volatile("s_waitcnt vmcnt(" #n ")" ::: "memory")
; #define PG8_WAIT_L(n) asm volatile("s_waitcnt lgkmcnt(" #n ")" ::: "memory")
; template <class Epi, class Sched, bool ALIGN_EPI = false, bool SP2 = false>
; __device__ __forceinline__ void gemm_phase(PG8_LAS unsigned char* lds, const Gemm g, const Sched& S, const Epi& E) {
;     ...
;             const bool last = (t == nt - 2);
;             const char* a1 = cA + (size_t)(t + 1) * kstep;
;             const char* a2 = last ? nA : cA + (size_t)(t + 2) * kstep; const char* b2 = last ? nB : cB + (size_t)(t + 2) * kstep;
;             const char* a3 = a2 + kstep; const char* b3 = b2 + kstep;
;             if (last && has_next) S.a_ready(nxt);
;             if constexpr (SP2) {
;             PG8_LDB(B0, 0, 0); PG8_LDB(B1, 0, 1); PG8_SCHED; PG8_LDA(At, 0, 0); PG8_STAGE(PG8_SA(1, 1), a1 + hstep, voffA);
;             PG8_WAIT_V(8); PG8_WAIT_L(0); PG8_BAR; PG8_MMA(0, 0, At, B0); PG8_MMA(0, 1, At, B1); PG8_BAR; PG8_SCHED;
;             PG8_LDA(At, 0, 1); PG8_STAGE(PG8_SB(0, 0), b2, voffB); PG8_STAGE(PG8_SB(0, 1), b2 + hstep, voffB); PG8_STAGE(PG8_SA(0, 0), a2, voffA);
;             PG8_WAIT_V(8); PG8_WAIT_L(0); PG8_BAR; PG8_MMA(1, 0, At, B0); PG8_MMA(1, 1, At, B1); PG8_BAR; PG8_SCHED;
.LBB0_3159:
	s_add_u32 s0, s24, 0xfff00080
	s_addc_u32 s1, s25, -1
	s_add_i32 s65, 0, 0x10000
	s_cmp_eq_u32 s64, 60
	s_cselect_b32 s27, s51, s1
	s_cselect_b32 s26, s60, s0
	s_cselect_b32 s1, s49, s63
	s_cselect_b32 s0, s61, s62
	s_add_i32 s70, 0, 0x14000
	ds_read_b128 v[142:145], v146
	ds_read_b128 v[152:155], v146 offset:1024
	ds_read_b128 v[156:159], v146 offset:2048
	ds_read_b128 v[160:163], v146 offset:3072
	ds_read_b128 v[164:167], v146 offset:16384
	ds_read_b128 v[168:171], v146 offset:17408
	ds_read_b128 v[172:175], v146 offset:18432
	ds_read_b128 v[176:179], v146 offset:19456
	s_add_i32 m0, s34, 0xc000
	ds_read_b128 v[180:183], v151
	ds_read_b128 v[184:187], v151 offset:1024
	ds_read_b128 v[188:191], v151 offset:2048
	ds_read_b128 v[192:195], v151 offset:3072
	ds_read_b128 v[196:199], v151 offset:4096
	ds_read_b128 v[200:203], v151 offset:5120
	ds_read_b128 v[204:207], v151 offset:6144
	ds_read_b128 v[208:211], v151 offset:7168
	global_load_lds_dwordx4 v138, s[24:25]
	s_add_i32 m0, s34, 0xe000
	s_nop 0
	global_load_lds_dwordx4 v140, s[24:25]
	s_waitcnt vmcnt(8)
	s_waitcnt lgkmcnt(0)
	s_setprio 1
	s_barrier
	v_mfma_f32_16x16x32_bf16 v[128:131], v[142:145], v[180:183], v[128:131]
	v_mfma_f32_16x16x32_bf16 v[128:131], v[152:155], v[184:187], v[128:131]
	v_mfma_f32_16x16x32_bf16 v[124:127], v[156:159], v[180:183], v[124:127]
	v_mfma_f32_16x16x32_bf16 v[124:127], v[160:163], v[184:187], v[124:127]
	v_mfma_f32_16x16x32_bf16 v[108:111], v[156:159], v[188:191], v[108:111]
	v_mfma_f32_16x16x32_bf16 v[108:111], v[160:163], v[192:195], v[108:111]
	v_mfma_f32_16x16x32_bf16 v[112:115], v[142:145], v[188:191], v[112:115]
	v_mfma_f32_16x16x32_bf16 v[112:115], v[152:155], v[192:195], v[112:115]
	v_mfma_f32_16x16x32_bf16 v[96:99], v[142:145], v[196:199], v[96:99]
	v_mfma_f32_16x16x32_bf16 v[96:99], v[152:155], v[200:203], v[96:99]
	v_mfma_f32_16x16x32_bf16 v[92:95], v[156:159], v[196:199], v[92:95]
	v_mfma_f32_16x16x32_bf16 v[92:95], v[160:163], v[200:203], v[92:95]
	v_mfma_f32_16x16x32_bf16 v[76:79], v[156:159], v[204:207], v[76:79]
	v_mfma_f32_16x16x32_bf16 v[76:79], v[160:163], v[208:211], v[76:79]
	v_mfma_f32_16x16x32_bf16 v[80:83], v[142:145], v[204:207], v[80:83]
	v_mfma_f32_16x16x32_bf16 v[80:83], v[152:155], v[208:211], v[80:83]
	s_setprio 0
	s_setprio 1
	v_mfma_f32_16x16x32_bf16 v[120:123], v[164:167], v[180:183], v[120:123]
	v_mfma_f32_16x16x32_bf16 v[120:123], v[168:171], v[184:187], v[120:123]
	v_mfma_f32_16x16x32_bf16 v[116:119], v[172:175], v[180:183], v[116:119]
	v_mfma_f32_16x16x32_bf16 v[116:119], v[176:179], v[184:187], v[116:119]
	v_mfma_f32_16x16x32_bf16 v[100:103], v[172:175], v[188:191], v[100:103]
	v_mfma_f32_16x16x32_bf16 v[100:103], v[176:179], v[192:195], v[100:103]
	v_mfma_f32_16x16x32_bf16 v[104:107], v[164:167], v[188:191], v[104:107]
	v_mfma_f32_16x16x32_bf16 v[104:107], v[168:171], v[192:195], v[104:107]
	v_mfma_f32_16x16x32_bf16 v[88:91], v[164:167], v[196:199], v[88:91]
	v_mfma_f32_16x16x32_bf16 v[88:91], v[168:171], v[200:203], v[88:91]
	v_mfma_f32_16x16x32_bf16 v[84:87], v[172:175], v[196:199], v[84:87]
	v_mfma_f32_16x16x32_bf16 v[84:87], v[176:179], v[200:203], v[84:87]
	v_mfma_f32_16x16x32_bf16 v[68:71], v[172:175], v[204:207], v[68:71]
	v_mfma_f32_16x16x32_bf16 v[68:71], v[176:179], v[208:211], v[68:71]
	v_mfma_f32_16x16x32_bf16 v[72:75], v[164:167], v[204:207], v[72:75]
	v_mfma_f32_16x16x32_bf16 v[72:75], v[168:171], v[208:211], v[72:75]
	s_barrier
	s_setprio 0
	s_add_i32 s65, s65, s9
	s_mov_b32 m0, s65
	ds_read_b128 v[180:183], v151 offset:16384
	ds_read_b128 v[184:187], v151 offset:17408
	ds_read_b128 v[188:191], v151 offset:18432
	ds_read_b128 v[192:195], v151 offset:19456
	ds_read_b128 v[196:199], v151 offset:20480
	ds_read_b128 v[200:203], v151 offset:21504
	ds_read_b128 v[204:207], v151 offset:22528
	ds_read_b128 v[208:211], v151 offset:23552
	global_load_lds_dwordx4 v2, s[0:1]
	s_add_i32 m0, s65, 0x2000
	s_add_u32 s66, s0, 0x100000
	s_addc_u32 s67, s1, 0
	s_add_i32 s65, s70, s9
	global_load_lds_dwordx4 v132, s[0:1]
	s_mov_b32 m0, s65
	s_nop 0
	global_load_lds_dwordx4 v2, s[66:67]
	s_add_i32 m0, s65, 0x2000
	s_nop 0
	global_load_lds_dwordx4 v132, s[66:67]
	s_mov_b32 m0, s34
	s_nop 0
	global_load_lds_dwordx4 v136, s[26:27]
	s_mov_b32 m0, s35
	s_nop 0
	global_load_lds_dwordx4 v134, s[26:27]
	s_add_u32 s100, s26, 0x80
	s_addc_u32 s101, s27, 0
	s_waitcnt vmcnt(8)
	s_waitcnt lgkmcnt(0)
	s_setprio 1
	s_barrier
	v_mfma_f32_16x16x32_bf16 v[64:67], v[142:145], v[180:183], v[64:67]
	v_mfma_f32_16x16x32_bf16 v[64:67], v[152:155], v[184:187], v[64:67]
	v_mfma_f32_16x16x32_bf16 v[60:63], v[156:159], v[180:183], v[60:63]
	v_mfma_f32_16x16x32_bf16 v[60:63], v[160:163], v[184:187], v[60:63]
	v_mfma_f32_16x16x32_bf16 v[44:47], v[156:159], v[188:191], v[44:47]
	v_mfma_f32_16x16x32_bf16 v[44:47], v[160:163], v[192:195], v[44:47]
	v_mfma_f32_16x16x32_bf16 v[48:51], v[142:145], v[188:191], v[48:51]
	v_mfma_f32_16x16x32_bf16 v[48:51], v[152:155], v[192:195], v[48:51]
	v_mfma_f32_16x16x32_bf16 v[32:35], v[142:145], v[196:199], v[32:35]
	v_mfma_f32_16x16x32_bf16 v[32:35], v[152:155], v[200:203], v[32:35]
	v_mfma_f32_16x16x32_bf16 v[28:31], v[156:159], v[196:199], v[28:31]
	v_mfma_f32_16x16x32_bf16 v[28:31], v[160:163], v[200:203], v[28:31]
	v_mfma_f32_16x16x32_bf16 v[12:15], v[156:159], v[204:207], v[12:15]
	v_mfma_f32_16x16x32_bf16 v[12:15], v[160:163], v[208:211], v[12:15]
	v_mfma_f32_16x16x32_bf16 v[16:19], v[142:145], v[204:207], v[16:19]
	v_mfma_f32_16x16x32_bf16 v[16:19], v[152:155], v[208:211], v[16:19]
	s_setprio 0
	s_setprio 1
	v_mfma_f32_16x16x32_bf16 v[56:59], v[164:167], v[180:183], v[56:59]
	v_mfma_f32_16x16x32_bf16 v[56:59], v[168:171], v[184:187], v[56:59]
	v_mfma_f32_16x16x32_bf16 v[52:55], v[172:175], v[180:183], v[52:55]
	v_mfma_f32_16x16x32_bf16 v[52:55], v[176:179], v[184:187], v[52:55]
	v_mfma_f32_16x16x32_bf16 v[36:39], v[172:175], v[188:191], v[36:39]
	v_mfma_f32_16x16x32_bf16 v[36:39], v[176:179], v[192:195], v[36:39]
	v_mfma_f32_16x16x32_bf16 v[40:43], v[164:167], v[188:191], v[40:43]
	v_mfma_f32_16x16x32_bf16 v[40:43], v[168:171], v[192:195], v[40:43]
	v_mfma_f32_16x16x32_bf16 v[24:27], v[164:167], v[196:199], v[24:27]
	v_mfma_f32_16x16x32_bf16 v[24:27], v[168:171], v[200:203], v[24:27]
	v_mfma_f32_16x16x32_bf16 v[20:23], v[172:175], v[196:199], v[20:23]
	v_mfma_f32_16x16x32_bf16 v[20:23], v[176:179], v[200:203], v[20:23]
	v_mfma_f32_16x16x32_bf16 v[4:7], v[172:175], v[204:207], v[4:7]
	v_mfma_f32_16x16x32_bf16 v[4:7], v[176:179], v[208:211], v[4:7]
	v_mfma_f32_16x16x32_bf16 v[8:11], v[164:167], v[204:207], v[8:11]
	v_mfma_f32_16x16x32_bf16 v[8:11], v[168:171], v[208:211], v[8:11]
	s_barrier
; #define PG8_STAGE(bufoff, gbase, voff) do { _Pragma("unroll") for (int _i = 0; _i < 2; ++_i) \
;         __builtin_amdgcn_global_load_lds((const unsigned*)((const char*)(gbase) + (voff)[_i]), (PG8_LAS unsigned*)(lds + (bufoff) + ldsw + _i * 8192), 16, 0, 0); } while (0)
; #define PG8_LDA(dst, b, h) do { _Pragma("unroll") for (int m = 0; m < 4; ++m) _Pragma("unroll") for (int k = 0; k < 2; ++k) dst[m][k] = *(const PG8_LAS bf16x8*)(lds + PG8_SA(b, h) + aoff + m * 2048 + k * 1024); } while (0)
; #define PG8_LDB(dst, b, h) do { _Pragma("unroll") for (int n = 0; n < 2; ++n) _Pragma("unroll") for (int k = 0; k < 2; ++k) dst[n][k] = *(const PG8_LAS bf16x8*)(lds + PG8_SB(b, h) + boff + n * 2048 + k * 1024); } while (0)
; #define PG8_MMA(ai, bj, At, Bt) do { __builtin_amdgcn_s_setprio(1); _Pragma("unroll") for (int m = 0; m < 4; ++m) _Pragma("unroll") for (int n = 0; n < 2; ++n) _Pragma("unroll") for (int k = 0; k < 2; ++k) \
;         acc[ai][bj][m][n] = __builtin_amdgcn_mfma_f32_16x16x32_bf16(Bt[n][k], At[m][k], acc[ai][bj][m][n], 0, 0, 0); __builtin_amdgcn_s_setprio(0); } while (0)
; #define PG8_WAIT_V(n) asm volatile("s_waitcnt vmcnt(" #n ")" ::: "memory")
; #define PG8_WAIT_L(n) asm volatile("s_waitcnt lgkmcnt(" #n ")" ::: "memory")
; #define PG8_BAR __builtin_amdgcn_s_barrier()
; #define PG8_SCHED __builtin_amdgcn_sched_barrier(0)
; template <class Epi, class Sched, bool ALIGN_EPI = false, bool SP2 = false>
; __device__ __forceinline__ void gemm_phase(PG8_LAS unsigned char* lds, const Gemm g, const Sched& S, const Epi& E) {
;     ...
;             PG8_LDB(B0, 1, 0); PG8_LDB(B1, 1, 1); PG8_SCHED; PG8_LDA(At, 1, 0); PG8_STAGE(PG8_SA(0, 1), a2 + hstep, voffA);
;             PG8_WAIT_V(8); PG8_WAIT_L(0); PG8_BAR; PG8_MMA(0, 0, At, B0); PG8_MMA(0, 1, At, B1); PG8_BAR; PG8_SCHED;
;             PG8_LDA(At, 1, 1); PG8_STAGE(PG8_SB(1, 0), b3, voffB); PG8_STAGE(PG8_SB(1, 1), b3 + hstep, voffB); PG8_STAGE(PG8_SA(1, 0), a3, voffA);
;             PG8_WAIT_V(8); PG8_WAIT_L(0); PG8_BAR; PG8_MMA(1, 0, At, B0); PG8_MMA(1, 1, At, B1); PG8_BAR; PG8_SCHED;
	s_setprio 0
	s_add_i32 s65, 0, 0x18000
	s_add_i32 s66, 0, 0x1c000
	ds_read_b128 v[142:145], v146 offset:32768
	ds_read_b128 v[152:155], v146 offset:33792
	ds_read_b128 v[156:159], v146 offset:34816
	ds_read_b128 v[160:163], v146 offset:35840
	ds_read_b128 v[164:167], v146 offset:49152
	ds_read_b128 v[168:171], v146 offset:50176
	ds_read_b128 v[172:175], v146 offset:51200
	ds_read_b128 v[176:179], v146 offset:52224
	s_add_u32 s26, s26, 0x100000
	s_addc_u32 s27, s27, 0
	s_mov_b32 m0, s54
	ds_read_b128 v[180:183], v151 offset:32768
	ds_read_b128 v[184:187], v151 offset:33792
	ds_read_b128 v[188:191], v151 offset:34816
	ds_read_b128 v[192:195], v151 offset:35840
	ds_read_b128 v[196:199], v151 offset:36864
	ds_read_b128 v[200:203], v151 offset:37888
	ds_read_b128 v[204:207], v151 offset:38912
	ds_read_b128 v[208:211], v151 offset:39936
	global_load_lds_dwordx4 v136, s[26:27]
	s_mov_b32 m0, s55
	s_nop 0
	global_load_lds_dwordx4 v134, s[26:27]
	s_waitcnt vmcnt(8)
	s_waitcnt lgkmcnt(0)
	s_setprio 1
	s_barrier
	v_mfma_f32_16x16x32_bf16 v[128:131], v[142:145], v[180:183], v[128:131]
	v_mfma_f32_16x16x32_bf16 v[128:131], v[152:155], v[184:187], v[128:131]
	v_mfma_f32_16x16x32_bf16 v[124:127], v[156:159], v[180:183], v[124:127]
	v_mfma_f32_16x16x32_bf16 v[124:127], v[160:163], v[184:187], v[124:127]
	v_mfma_f32_16x16x32_bf16 v[108:111], v[156:159], v[188:191], v[108:111]
	v_mfma_f32_16x16x32_bf16 v[108:111], v[160:163], v[192:195], v[108:111]
	v_mfma_f32_16x16x32_bf16 v[112:115], v[142:145], v[188:191], v[112:115]
	v_mfma_f32_16x16x32_bf16 v[112:115], v[152:155], v[192:195], v[112:115]
	v_mfma_f32_16x16x32_bf16 v[96:99], v[142:145], v[196:199], v[96:99]
	v_mfma_f32_16x16x32_bf16 v[96:99], v[152:155], v[200:203], v[96:99]
	v_mfma_f32_16x16x32_bf16 v[92:95], v[156:159], v[196:199], v[92:95]
	v_mfma_f32_16x16x32_bf16 v[92:95], v[160:163], v[200:203], v[92:95]
	v_mfma_f32_16x16x32_bf16 v[76:79], v[156:159], v[204:207], v[76:79]
	v_mfma_f32_16x16x32_bf16 v[76:79], v[160:163], v[208:211], v[76:79]
	v_mfma_f32_16x16x32_bf16 v[80:83], v[142:145], v[204:207], v[80:83]
	v_mfma_f32_16x16x32_bf16 v[80:83], v[152:155], v[208:211], v[80:83]
	s_setprio 0
	s_setprio 1
	v_mfma_f32_16x16x32_bf16 v[120:123], v[164:167], v[180:183], v[120:123]
	v_mfma_f32_16x16x32_bf16 v[120:123], v[168:171], v[184:187], v[120:123]
	v_mfma_f32_16x16x32_bf16 v[116:119], v[172:175], v[180:183], v[116:119]
	v_mfma_f32_16x16x32_bf16 v[116:119], v[176:179], v[184:187], v[116:119]
	v_mfma_f32_16x16x32_bf16 v[100:103], v[172:175], v[188:191], v[100:103]
	v_mfma_f32_16x16x32_bf16 v[100:103], v[176:179], v[192:195], v[100:103]
	v_mfma_f32_16x16x32_bf16 v[104:107], v[164:167], v[188:191], v[104:107]
	v_mfma_f32_16x16x32_bf16 v[104:107], v[168:171], v[192:195], v[104:107]
	v_mfma_f32_16x16x32_bf16 v[88:91], v[164:167], v[196:199], v[88:91]
	v_mfma_f32_16x16x32_bf16 v[88:91], v[168:171], v[200:203], v[88:91]
	v_mfma_f32_16x16x32_bf16 v[84:87], v[172:175], v[196:199], v[84:87]
	v_mfma_f32_16x16x32_bf16 v[84:87], v[176:179], v[200:203], v[84:87]
	v_mfma_f32_16x16x32_bf16 v[68:71], v[172:175], v[204:207], v[68:71]
	v_mfma_f32_16x16x32_bf16 v[68:71], v[176:179], v[208:211], v[68:71]
	v_mfma_f32_16x16x32_bf16 v[72:75], v[164:167], v[204:207], v[72:75]
	v_mfma_f32_16x16x32_bf16 v[72:75], v[168:171], v[208:211], v[72:75]
	s_barrier
	s_setprio 0
	s_add_i32 s26, s65, s9
	s_mov_b32 m0, s26
	ds_read_b128 v[180:183], v151 offset:49152
	ds_read_b128 v[184:187], v151 offset:50176
	ds_read_b128 v[188:191], v151 offset:51200
	ds_read_b128 v[192:195], v151 offset:52224
	ds_read_b128 v[196:199], v151 offset:53248
	ds_read_b128 v[200:203], v151 offset:54272
	ds_read_b128 v[204:207], v151 offset:55296
	ds_read_b128 v[208:211], v151 offset:56320
	s_add_u32 s0, s0, 0x80
	s_addc_u32 s1, s1, 0
	global_load_lds_dwordx4 v2, s[0:1]
	s_add_i32 m0, s26, 0x2000
	s_add_i32 s26, s66, s9
	global_load_lds_dwordx4 v132, s[0:1]
	s_add_u32 s0, s0, 0x100000
	s_addc_u32 s1, s1, 0
	s_mov_b32 m0, s26
	s_nop 0
	global_load_lds_dwordx4 v2, s[0:1]
	s_add_i32 m0, s26, 0x2000
	s_nop 0
	global_load_lds_dwordx4 v132, s[0:1]
	s_mov_b32 m0, s56
	s_nop 0
	global_load_lds_dwordx4 v136, s[100:101]
	s_mov_b32 m0, s57
	s_nop 0
	global_load_lds_dwordx4 v134, s[100:101]
	s_waitcnt vmcnt(8)
	s_waitcnt lgkmcnt(0)
	s_setprio 1
	s_barrier
	v_mfma_f32_16x16x32_bf16 v[64:67], v[142:145], v[180:183], v[64:67]
	v_mfma_f32_16x16x32_bf16 v[64:67], v[152:155], v[184:187], v[64:67]
	v_mfma_f32_16x16x32_bf16 v[60:63], v[156:159], v[180:183], v[60:63]
	v_mfma_f32_16x16x32_bf16 v[60:63], v[160:163], v[184:187], v[60:63]
	v_mfma_f32_16x16x32_bf16 v[44:47], v[156:159], v[188:191], v[44:47]
	v_mfma_f32_16x16x32_bf16 v[44:47], v[160:163], v[192:195], v[44:47]
	v_mfma_f32_16x16x32_bf16 v[48:51], v[142:145], v[188:191], v[48:51]
	v_mfma_f32_16x16x32_bf16 v[48:51], v[152:155], v[192:195], v[48:51]
	v_mfma_f32_16x16x32_bf16 v[32:35], v[142:145], v[196:199], v[32:35]
	v_mfma_f32_16x16x32_bf16 v[32:35], v[152:155], v[200:203], v[32:35]
	v_mfma_f32_16x16x32_bf16 v[28:31], v[156:159], v[196:199], v[28:31]
	v_mfma_f32_16x16x32_bf16 v[28:31], v[160:163], v[200:203], v[28:31]
	v_mfma_f32_16x16x32_bf16 v[12:15], v[156:159], v[204:207], v[12:15]
	v_mfma_f32_16x16x32_bf16 v[12:15], v[160:163], v[208:211], v[12:15]
	v_mfma_f32_16x16x32_bf16 v[16:19], v[142:145], v[204:207], v[16:19]
	v_mfma_f32_16x16x32_bf16 v[16:19], v[152:155], v[208:211], v[16:19]
	s_setprio 0
	s_setprio 1
	v_mfma_f32_16x16x32_bf16 v[56:59], v[164:167], v[180:183], v[56:59]
	v_mfma_f32_16x16x32_bf16 v[56:59], v[168:171], v[184:187], v[56:59]
	v_mfma_f32_16x16x32_bf16 v[52:55], v[172:175], v[180:183], v[52:55]
	v_mfma_f32_16x16x32_bf16 v[52:55], v[176:179], v[184:187], v[52:55]
	v_mfma_f32_16x16x32_bf16 v[36:39], v[172:175], v[188:191], v[36:39]
	v_mfma_f32_16x16x32_bf16 v[36:39], v[176:179], v[192:195], v[36:39]
	v_mfma_f32_16x16x32_bf16 v[40:43], v[164:167], v[188:191], v[40:43]
	v_mfma_f32_16x16x32_bf16 v[40:43], v[168:171], v[192:195], v[40:43]
	v_mfma_f32_16x16x32_bf16 v[24:27], v[164:167], v[196:199], v[24:27]
	v_mfma_f32_16x16x32_bf16 v[24:27], v[168:171], v[200:203], v[24:27]
	v_mfma_f32_16x16x32_bf16 v[20:23], v[172:175], v[196:199], v[20:23]
	v_mfma_f32_16x16x32_bf16 v[20:23], v[176:179], v[200:203], v[20:23]
	v_mfma_f32_16x16x32_bf16 v[4:7], v[172:175], v[204:207], v[4:7]
	v_mfma_f32_16x16x32_bf16 v[4:7], v[176:179], v[208:211], v[4:7]
	v_mfma_f32_16x16x32_bf16 v[8:11], v[164:167], v[204:207], v[8:11]
	v_mfma_f32_16x16x32_bf16 v[8:11], v[168:171], v[208:211], v[8:11]
	s_barrier
	s_setprio 0
	s_add_i32 s64, s64, 2
	s_add_u32 s24, s24, 0x100
	s_addc_u32 s25, s25, 0
	s_add_u32 s62, s62, 0x100
	s_addc_u32 s63, s63, 0
	s_cmp_gt_u32 s64, 61
	s_cbranch_scc0 .LBB0_3159
	s_and_b64 vcc, exec, s[46:47]
	s_cbranch_vccz .LBB0_3162
	s_barrier

; #define PG8_STAGE(bufoff, gbase, voff) do { _Pragma("unroll") for (int _i = 0; _i < 2; ++_i) \
;         __builtin_amdgcn_global_load_lds((const unsigned*)((const char*)(gbase) + (voff)[_i]), (PG8_LAS unsigned*)(lds + (bufoff) + ldsw + _i * 8192), 16, 0, 0); } while (0)
; #define PG8_LDA(dst, b, h) do { _Pragma("unroll") for (int m = 0; m < 4; ++m) _Pragma("unroll") for (int k = 0; k < 2; ++k) dst[m][k] = *(const PG8_LAS bf16x8*)(lds + PG8_SA(b, h) + aoff + m * 2048 + k * 1024); } while (0)
; #define PG8_LDB(dst, b, h) do { _Pragma("unroll") for (int n = 0; n < 2; ++n) _Pragma("unroll") for (int k = 0; k < 2; ++k) dst[n][k] = *(const PG8_LAS bf16x8*)(lds + PG8_SB(b, h) + boff + n * 2048 + k * 1024); } while (0)
; #define PG8_MMA(ai, bj, At, Bt) do { __builtin_amdgcn_s_setprio(1); _Pragma("unroll") for (int m = 0; m < 4; ++m) _Pragma("unroll") for (int n = 0; n < 2; ++n) _Pragma("unroll") for (int k = 0; k < 2; ++k) \
;         acc[ai][bj][m][n] = __builtin_amdgcn_mfma_f32_16x16x32_bf16(Bt[n][k], At[m][k], acc[ai][bj][m][n], 0, 0, 0); __builtin_amdgcn_s_setprio(0); } while (0)
; #define PG8_WAIT_V(n) asm volatile("s_waitcnt vmcnt(" #n ")" ::: "memory")
; #define PG8_WAIT_L(n) asm volatile("s_waitcnt lgkmcnt(" #n ")" ::: "memory")
; template <class Epi, class Sched, bool ALIGN_EPI = false, bool SP2 = false>
; __device__ __forceinline__ void gemm_phase(PG8_LAS unsigned char* lds, const Gemm g, const Sched& S, const Epi& E) {
;     ...
;             const bool last = (t == nt - 2);
;             const char* a1 = cA + (size_t)(t + 1) * kstep;
;             const char* a2 = last ? nA : cA + (size_t)(t + 2) * kstep; const char* b2 = last ? nB : cB + (size_t)(t + 2) * kstep;
;             const char* a3 = a2 + kstep; const char* b3 = b2 + kstep;
;             if (last && has_next) S.a_ready(nxt);
;             if constexpr (SP2) {
;             PG8_LDB(B0, 0, 0); PG8_LDB(B1, 0, 1); PG8_SCHED; PG8_LDA(At, 0, 0); PG8_STAGE(PG8_SA(1, 1), a1 + hstep, voffA);
;             PG8_WAIT_V(8); PG8_WAIT_L(0); PG8_BAR; PG8_MMA(0, 0, At, B0); PG8_MMA(0, 1, At, B1); PG8_BAR; PG8_SCHED;
;             PG8_LDA(At, 0, 1); PG8_STAGE(PG8_SB(0, 0), b2, voffB); PG8_STAGE(PG8_SB(0, 1), b2 + hstep, voffB); PG8_STAGE(PG8_SA(0, 0), a2, voffA);
;             PG8_WAIT_V(8); PG8_WAIT_L(0); PG8_BAR; PG8_MMA(1, 0, At, B0); PG8_MMA(1, 1, At, B1); PG8_BAR; PG8_SCHED;
.LBB0_3627:
	s_add_i32 s72, s26, 2
	s_add_u32 s0, s24, 0x100
	s_addc_u32 s1, s25, 0
	s_add_i32 s73, 0, 0x10000
	s_cmp_eq_u32 s44, s26
	s_cselect_b32 s35, s79, s1
	s_cselect_b32 s34, s78, s0
	s_cselect_b32 s27, s81, s47
	s_cselect_b32 s26, s80, s45
	s_add_i32 vcc_lo, 0, 0x14000
	s_waitcnt lgkmcnt(0)
	ds_read_b128 v[132:135], v162
	ds_read_b128 v[136:139], v162 offset:1024
	ds_read_b128 v[140:143], v162 offset:2048
	ds_read_b128 v[154:157], v162 offset:3072
	ds_read_b128 v[158:161], v162 offset:16384
	ds_read_b128 v[170:173], v162 offset:17408
	ds_read_b128 v[174:177], v162 offset:18432
	ds_read_b128 v[178:181], v162 offset:19456
	s_add_i32 m0, s92, 0xc000
	ds_read_b128 v[182:185], v169
	ds_read_b128 v[186:189], v169 offset:1024
	ds_read_b128 v[190:193], v169 offset:2048
	ds_read_b128 v[194:197], v169 offset:3072
	ds_read_b128 v[198:201], v169 offset:4096
	ds_read_b128 v[202:205], v169 offset:5120
	ds_read_b128 v[206:209], v169 offset:6144
	ds_read_b128 v[210:213], v169 offset:7168
	global_load_lds_dwordx4 v150, s[24:25]
	s_add_i32 m0, s92, 0xe000
	s_nop 0
	global_load_lds_dwordx4 v152, s[24:25]
	s_waitcnt vmcnt(8)
	s_waitcnt lgkmcnt(0)
	s_setprio 1
	s_barrier
	v_mfma_f32_16x16x32_bf16 v[128:131], v[132:135], v[182:185], v[128:131]
	v_mfma_f32_16x16x32_bf16 v[128:131], v[136:139], v[186:189], v[128:131]
	v_mfma_f32_16x16x32_bf16 v[124:127], v[140:143], v[182:185], v[124:127]
	v_mfma_f32_16x16x32_bf16 v[124:127], v[154:157], v[186:189], v[124:127]
	v_mfma_f32_16x16x32_bf16 v[116:119], v[140:143], v[190:193], v[116:119]
	v_mfma_f32_16x16x32_bf16 v[116:119], v[154:157], v[194:197], v[116:119]
	v_mfma_f32_16x16x32_bf16 v[120:123], v[132:135], v[190:193], v[120:123]
	v_mfma_f32_16x16x32_bf16 v[120:123], v[136:139], v[194:197], v[120:123]
	v_mfma_f32_16x16x32_bf16 v[112:115], v[132:135], v[198:201], v[112:115]
	v_mfma_f32_16x16x32_bf16 v[112:115], v[136:139], v[202:205], v[112:115]
	v_mfma_f32_16x16x32_bf16 v[108:111], v[140:143], v[198:201], v[108:111]
	v_mfma_f32_16x16x32_bf16 v[108:111], v[154:157], v[202:205], v[108:111]
	v_mfma_f32_16x16x32_bf16 v[100:103], v[140:143], v[206:209], v[100:103]
	v_mfma_f32_16x16x32_bf16 v[100:103], v[154:157], v[210:213], v[100:103]
	v_mfma_f32_16x16x32_bf16 v[104:107], v[132:135], v[206:209], v[104:107]
	v_mfma_f32_16x16x32_bf16 v[104:107], v[136:139], v[210:213], v[104:107]
	s_setprio 0
	s_setprio 1
	v_mfma_f32_16x16x32_bf16 v[96:99], v[158:161], v[182:185], v[96:99]
	v_mfma_f32_16x16x32_bf16 v[96:99], v[170:173], v[186:189], v[96:99]
	v_mfma_f32_16x16x32_bf16 v[92:95], v[174:177], v[182:185], v[92:95]
	v_mfma_f32_16x16x32_bf16 v[92:95], v[178:181], v[186:189], v[92:95]
	v_mfma_f32_16x16x32_bf16 v[84:87], v[174:177], v[190:193], v[84:87]
	v_mfma_f32_16x16x32_bf16 v[84:87], v[178:181], v[194:197], v[84:87]
	v_mfma_f32_16x16x32_bf16 v[88:91], v[158:161], v[190:193], v[88:91]
	v_mfma_f32_16x16x32_bf16 v[88:91], v[170:173], v[194:197], v[88:91]
	v_mfma_f32_16x16x32_bf16 v[80:83], v[158:161], v[198:201], v[80:83]
	v_mfma_f32_16x16x32_bf16 v[80:83], v[170:173], v[202:205], v[80:83]
	v_mfma_f32_16x16x32_bf16 v[76:79], v[174:177], v[198:201], v[76:79]
	v_mfma_f32_16x16x32_bf16 v[76:79], v[178:181], v[202:205], v[76:79]
	v_mfma_f32_16x16x32_bf16 v[68:71], v[174:177], v[206:209], v[68:71]
	v_mfma_f32_16x16x32_bf16 v[68:71], v[178:181], v[210:213], v[68:71]
	v_mfma_f32_16x16x32_bf16 v[72:75], v[158:161], v[206:209], v[72:75]
	v_mfma_f32_16x16x32_bf16 v[72:75], v[170:173], v[210:213], v[72:75]
	s_barrier
	s_setprio 0
	s_add_i32 s24, s73, s83
	s_mov_b32 m0, s24
	ds_read_b128 v[182:185], v169 offset:16384
	ds_read_b128 v[186:189], v169 offset:17408
	ds_read_b128 v[190:193], v169 offset:18432
	ds_read_b128 v[194:197], v169 offset:19456
	ds_read_b128 v[198:201], v169 offset:20480
	ds_read_b128 v[202:205], v169 offset:21504
	ds_read_b128 v[206:209], v169 offset:22528
	ds_read_b128 v[210:213], v169 offset:23552
	global_load_lds_dwordx4 v2, s[26:27]
	s_add_i32 m0, s24, 0x2000
	s_add_u32 s24, s26, 0x2b0000
	s_addc_u32 s25, s27, 0
	s_add_i32 s73, vcc_lo, s83
	global_load_lds_dwordx4 v148, s[26:27]
	s_mov_b32 m0, s73
	s_nop 0
	global_load_lds_dwordx4 v2, s[24:25]
	s_add_i32 m0, s73, 0x2000
	s_nop 0
	global_load_lds_dwordx4 v148, s[24:25]
	s_mov_b32 m0, s92
	s_nop 0
	global_load_lds_dwordx4 v144, s[34:35]
	s_mov_b32 m0, s93
	s_nop 0
	global_load_lds_dwordx4 v146, s[34:35]
	s_waitcnt vmcnt(8)
	s_waitcnt lgkmcnt(0)
	s_setprio 1
	s_barrier
	v_mfma_f32_16x16x32_bf16 v[64:67], v[132:135], v[182:185], v[64:67]
	v_mfma_f32_16x16x32_bf16 v[64:67], v[136:139], v[186:189], v[64:67]
	v_mfma_f32_16x16x32_bf16 v[60:63], v[140:143], v[182:185], v[60:63]
	v_mfma_f32_16x16x32_bf16 v[60:63], v[154:157], v[186:189], v[60:63]
	v_mfma_f32_16x16x32_bf16 v[52:55], v[140:143], v[190:193], v[52:55]
	v_mfma_f32_16x16x32_bf16 v[52:55], v[154:157], v[194:197], v[52:55]
	v_mfma_f32_16x16x32_bf16 v[56:59], v[132:135], v[190:193], v[56:59]
	v_mfma_f32_16x16x32_bf16 v[56:59], v[136:139], v[194:197], v[56:59]
	v_mfma_f32_16x16x32_bf16 v[48:51], v[132:135], v[198:201], v[48:51]
	v_mfma_f32_16x16x32_bf16 v[48:51], v[136:139], v[202:205], v[48:51]
	v_mfma_f32_16x16x32_bf16 v[44:47], v[140:143], v[198:201], v[44:47]
	v_mfma_f32_16x16x32_bf16 v[44:47], v[154:157], v[202:205], v[44:47]
	v_mfma_f32_16x16x32_bf16 v[36:39], v[140:143], v[206:209], v[36:39]
	v_mfma_f32_16x16x32_bf16 v[36:39], v[154:157], v[210:213], v[36:39]
	v_mfma_f32_16x16x32_bf16 v[40:43], v[132:135], v[206:209], v[40:43]
	v_mfma_f32_16x16x32_bf16 v[40:43], v[136:139], v[210:213], v[40:43]
	s_setprio 0
	s_setprio 1
	v_mfma_f32_16x16x32_bf16 v[32:35], v[158:161], v[182:185], v[32:35]
	v_mfma_f32_16x16x32_bf16 v[32:35], v[170:173], v[186:189], v[32:35]
	v_mfma_f32_16x16x32_bf16 v[28:31], v[174:177], v[182:185], v[28:31]
	v_mfma_f32_16x16x32_bf16 v[28:31], v[178:181], v[186:189], v[28:31]
	v_mfma_f32_16x16x32_bf16 v[20:23], v[174:177], v[190:193], v[20:23]
	v_mfma_f32_16x16x32_bf16 v[20:23], v[178:181], v[194:197], v[20:23]
	v_mfma_f32_16x16x32_bf16 v[24:27], v[158:161], v[190:193], v[24:27]
	v_mfma_f32_16x16x32_bf16 v[24:27], v[170:173], v[194:197], v[24:27]
	v_mfma_f32_16x16x32_bf16 v[16:19], v[158:161], v[198:201], v[16:19]
	v_mfma_f32_16x16x32_bf16 v[16:19], v[170:173], v[202:205], v[16:19]
	v_mfma_f32_16x16x32_bf16 v[12:15], v[174:177], v[198:201], v[12:15]
	v_mfma_f32_16x16x32_bf16 v[12:15], v[178:181], v[202:205], v[12:15]
	v_mfma_f32_16x16x32_bf16 v[4:7], v[174:177], v[206:209], v[4:7]
	v_mfma_f32_16x16x32_bf16 v[4:7], v[178:181], v[210:213], v[4:7]
	v_mfma_f32_16x16x32_bf16 v[8:11], v[158:161], v[206:209], v[8:11]
	v_mfma_f32_16x16x32_bf16 v[8:11], v[170:173], v[210:213], v[8:11]
	s_barrier
; #define PG8_STAGE(bufoff, gbase, voff) do { _Pragma("unroll") for (int _i = 0; _i < 2; ++_i) \
;         __builtin_amdgcn_global_load_lds((const unsigned*)((const char*)(gbase) + (voff)[_i]), (PG8_LAS unsigned*)(lds + (bufoff) + ldsw + _i * 8192), 16, 0, 0); } while (0)
; #define PG8_LDA(dst, b, h) do { _Pragma("unroll") for (int m = 0; m < 4; ++m) _Pragma("unroll") for (int k = 0; k < 2; ++k) dst[m][k] = *(const PG8_LAS bf16x8*)(lds + PG8_SA(b, h) + aoff + m * 2048 + k * 1024); } while (0)
; #define PG8_LDB(dst, b, h) do { _Pragma("unroll") for (int n = 0; n < 2; ++n) _Pragma("unroll") for (int k = 0; k < 2; ++k) dst[n][k] = *(const PG8_LAS bf16x8*)(lds + PG8_SB(b, h) + boff + n * 2048 + k * 1024); } while (0)
; #define PG8_MMA(ai, bj, At, Bt) do { __builtin_amdgcn_s_setprio(1); _Pragma("unroll") for (int m = 0; m < 4; ++m) _Pragma("unroll") for (int n = 0; n < 2; ++n) _Pragma("unroll") for (int k = 0; k < 2; ++k) \
;         acc[ai][bj][m][n] = __builtin_amdgcn_mfma_f32_16x16x32_bf16(Bt[n][k], At[m][k], acc[ai][bj][m][n], 0, 0, 0); __builtin_amdgcn_s_setprio(0); } while (0)
; #define PG8_WAIT_V(n) asm volatile("s_waitcnt vmcnt(" #n ")" ::: "memory")
; #define PG8_WAIT_L(n) asm volatile("s_waitcnt lgkmcnt(" #n ")" ::: "memory")
; #define PG8_BAR __builtin_amdgcn_s_barrier()
; #define PG8_SCHED __builtin_amdgcn_sched_barrier(0)
; template <class Epi, class Sched, bool ALIGN_EPI = false, bool SP2 = false>
; __device__ __forceinline__ void gemm_phase(PG8_LAS unsigned char* lds, const Gemm g, const Sched& S, const Epi& E) {
;     ...
;             PG8_LDB(B0, 1, 0); PG8_LDB(B1, 1, 1); PG8_SCHED; PG8_LDA(At, 1, 0); PG8_STAGE(PG8_SA(0, 1), a2 + hstep, voffA);
;             PG8_WAIT_V(8); PG8_WAIT_L(0); PG8_BAR; PG8_MMA(0, 0, At, B0); PG8_MMA(0, 1, At, B1); PG8_BAR; PG8_SCHED;
;             PG8_LDA(At, 1, 1); PG8_STAGE(PG8_SB(1, 0), b3, voffB); PG8_STAGE(PG8_SB(1, 1), b3 + hstep, voffB); PG8_STAGE(PG8_SA(1, 0), a3, voffA);
;             PG8_WAIT_V(8); PG8_WAIT_L(0); PG8_BAR; PG8_MMA(1, 0, At, B0); PG8_MMA(1, 1, At, B1); PG8_BAR; PG8_SCHED;
	s_setprio 0
	s_add_i32 s73, 0, 0x18000
	s_add_i32 vcc_lo, 0, 0x1c000
	ds_read_b128 v[132:135], v162 offset:32768
	ds_read_b128 v[136:139], v162 offset:33792
	ds_read_b128 v[140:143], v162 offset:34816
	ds_read_b128 v[154:157], v162 offset:35840
	ds_read_b128 v[158:161], v162 offset:49152
	ds_read_b128 v[170:173], v162 offset:50176
	ds_read_b128 v[174:177], v162 offset:51200
	ds_read_b128 v[178:181], v162 offset:52224
	s_add_u32 s24, s34, 0x2b0000
	s_addc_u32 s25, s35, 0
	s_mov_b32 m0, s94
	ds_read_b128 v[182:185], v169 offset:32768
	ds_read_b128 v[186:189], v169 offset:33792
	ds_read_b128 v[190:193], v169 offset:34816
	ds_read_b128 v[194:197], v169 offset:35840
	ds_read_b128 v[198:201], v169 offset:36864
	ds_read_b128 v[202:205], v169 offset:37888
	ds_read_b128 v[206:209], v169 offset:38912
	ds_read_b128 v[210:213], v169 offset:39936
	global_load_lds_dwordx4 v144, s[24:25]
	s_mov_b32 m0, s95
	s_nop 0
	global_load_lds_dwordx4 v146, s[24:25]
	s_waitcnt vmcnt(8)
	s_waitcnt lgkmcnt(0)
	s_setprio 1
	s_barrier
	v_mfma_f32_16x16x32_bf16 v[128:131], v[132:135], v[182:185], v[128:131]
	v_mfma_f32_16x16x32_bf16 v[128:131], v[136:139], v[186:189], v[128:131]
	v_mfma_f32_16x16x32_bf16 v[124:127], v[140:143], v[182:185], v[124:127]
	v_mfma_f32_16x16x32_bf16 v[124:127], v[154:157], v[186:189], v[124:127]
	v_mfma_f32_16x16x32_bf16 v[116:119], v[140:143], v[190:193], v[116:119]
	v_mfma_f32_16x16x32_bf16 v[116:119], v[154:157], v[194:197], v[116:119]
	v_mfma_f32_16x16x32_bf16 v[120:123], v[132:135], v[190:193], v[120:123]
	v_mfma_f32_16x16x32_bf16 v[120:123], v[136:139], v[194:197], v[120:123]
	v_mfma_f32_16x16x32_bf16 v[112:115], v[132:135], v[198:201], v[112:115]
	v_mfma_f32_16x16x32_bf16 v[112:115], v[136:139], v[202:205], v[112:115]
	v_mfma_f32_16x16x32_bf16 v[108:111], v[140:143], v[198:201], v[108:111]
	v_mfma_f32_16x16x32_bf16 v[108:111], v[154:157], v[202:205], v[108:111]
	v_mfma_f32_16x16x32_bf16 v[100:103], v[140:143], v[206:209], v[100:103]
	v_mfma_f32_16x16x32_bf16 v[100:103], v[154:157], v[210:213], v[100:103]
	v_mfma_f32_16x16x32_bf16 v[104:107], v[132:135], v[206:209], v[104:107]
	v_mfma_f32_16x16x32_bf16 v[104:107], v[136:139], v[210:213], v[104:107]
	s_setprio 0
	s_setprio 1
	v_mfma_f32_16x16x32_bf16 v[96:99], v[158:161], v[182:185], v[96:99]
	v_mfma_f32_16x16x32_bf16 v[96:99], v[170:173], v[186:189], v[96:99]
	v_mfma_f32_16x16x32_bf16 v[92:95], v[174:177], v[182:185], v[92:95]
	v_mfma_f32_16x16x32_bf16 v[92:95], v[178:181], v[186:189], v[92:95]
	v_mfma_f32_16x16x32_bf16 v[84:87], v[174:177], v[190:193], v[84:87]
	v_mfma_f32_16x16x32_bf16 v[84:87], v[178:181], v[194:197], v[84:87]
	v_mfma_f32_16x16x32_bf16 v[88:91], v[158:161], v[190:193], v[88:91]
	v_mfma_f32_16x16x32_bf16 v[88:91], v[170:173], v[194:197], v[88:91]
	v_mfma_f32_16x16x32_bf16 v[80:83], v[158:161], v[198:201], v[80:83]
	v_mfma_f32_16x16x32_bf16 v[80:83], v[170:173], v[202:205], v[80:83]
	v_mfma_f32_16x16x32_bf16 v[76:79], v[174:177], v[198:201], v[76:79]
	v_mfma_f32_16x16x32_bf16 v[76:79], v[178:181], v[202:205], v[76:79]
	v_mfma_f32_16x16x32_bf16 v[68:71], v[174:177], v[206:209], v[68:71]
	v_mfma_f32_16x16x32_bf16 v[68:71], v[178:181], v[210:213], v[68:71]
	v_mfma_f32_16x16x32_bf16 v[72:75], v[158:161], v[206:209], v[72:75]
	v_mfma_f32_16x16x32_bf16 v[72:75], v[170:173], v[210:213], v[72:75]
	s_barrier
	s_setprio 0
	s_add_i32 s24, s73, s83
	s_add_u32 s100, s26, 0x80
	s_addc_u32 s101, s27, 0
	s_mov_b32 m0, s24
	ds_read_b128 v[182:185], v169 offset:49152
	ds_read_b128 v[186:189], v169 offset:50176
	ds_read_b128 v[190:193], v169 offset:51200
	ds_read_b128 v[194:197], v169 offset:52224
	ds_read_b128 v[198:201], v169 offset:53248
	ds_read_b128 v[202:205], v169 offset:54272
	ds_read_b128 v[206:209], v169 offset:55296
	ds_read_b128 v[210:213], v169 offset:56320
	global_load_lds_dwordx4 v2, s[100:101]
	s_add_i32 m0, s24, 0x2000
	s_add_u32 s24, s26, 0x2b0080
	s_addc_u32 s25, s27, 0
	s_add_i32 s26, vcc_lo, s83
	global_load_lds_dwordx4 v148, s[100:101]
	s_mov_b32 m0, s26
	s_nop 0
	global_load_lds_dwordx4 v2, s[24:25]
	s_add_i32 m0, s26, 0x2000
	s_nop 0
	global_load_lds_dwordx4 v148, s[24:25]
	s_add_u32 s100, s34, 0x80
	s_addc_u32 s101, s35, 0
	s_mov_b32 m0, s65
	s_nop 0
	global_load_lds_dwordx4 v144, s[100:101]
	s_mov_b32 m0, s4
	s_nop 0
	global_load_lds_dwordx4 v146, s[100:101]
	s_waitcnt vmcnt(8)
	s_waitcnt lgkmcnt(0)
	s_setprio 1
	s_barrier
	v_mfma_f32_16x16x32_bf16 v[64:67], v[132:135], v[182:185], v[64:67]
	v_mfma_f32_16x16x32_bf16 v[64:67], v[136:139], v[186:189], v[64:67]
	v_mfma_f32_16x16x32_bf16 v[60:63], v[140:143], v[182:185], v[60:63]
	v_mfma_f32_16x16x32_bf16 v[60:63], v[154:157], v[186:189], v[60:63]
	v_mfma_f32_16x16x32_bf16 v[52:55], v[140:143], v[190:193], v[52:55]
	v_mfma_f32_16x16x32_bf16 v[52:55], v[154:157], v[194:197], v[52:55]
	v_mfma_f32_16x16x32_bf16 v[56:59], v[132:135], v[190:193], v[56:59]
	v_mfma_f32_16x16x32_bf16 v[56:59], v[136:139], v[194:197], v[56:59]
	v_mfma_f32_16x16x32_bf16 v[48:51], v[132:135], v[198:201], v[48:51]
	v_mfma_f32_16x16x32_bf16 v[48:51], v[136:139], v[202:205], v[48:51]
	v_mfma_f32_16x16x32_bf16 v[44:47], v[140:143], v[198:201], v[44:47]
	v_mfma_f32_16x16x32_bf16 v[44:47], v[154:157], v[202:205], v[44:47]
	v_mfma_f32_16x16x32_bf16 v[36:39], v[140:143], v[206:209], v[36:39]
	v_mfma_f32_16x16x32_bf16 v[36:39], v[154:157], v[210:213], v[36:39]
	v_mfma_f32_16x16x32_bf16 v[40:43], v[132:135], v[206:209], v[40:43]
	v_mfma_f32_16x16x32_bf16 v[40:43], v[136:139], v[210:213], v[40:43]
	s_setprio 0
	s_setprio 1
	v_mfma_f32_16x16x32_bf16 v[32:35], v[158:161], v[182:185], v[32:35]
	v_mfma_f32_16x16x32_bf16 v[32:35], v[170:173], v[186:189], v[32:35]
	v_mfma_f32_16x16x32_bf16 v[28:31], v[174:177], v[182:185], v[28:31]
	v_mfma_f32_16x16x32_bf16 v[28:31], v[178:181], v[186:189], v[28:31]
	v_mfma_f32_16x16x32_bf16 v[20:23], v[174:177], v[190:193], v[20:23]
	v_mfma_f32_16x16x32_bf16 v[20:23], v[178:181], v[194:197], v[20:23]
	v_mfma_f32_16x16x32_bf16 v[24:27], v[158:161], v[190:193], v[24:27]
	v_mfma_f32_16x16x32_bf16 v[24:27], v[170:173], v[194:197], v[24:27]
	v_mfma_f32_16x16x32_bf16 v[16:19], v[158:161], v[198:201], v[16:19]
	v_mfma_f32_16x16x32_bf16 v[16:19], v[170:173], v[202:205], v[16:19]
	v_mfma_f32_16x16x32_bf16 v[12:15], v[174:177], v[198:201], v[12:15]
	v_mfma_f32_16x16x32_bf16 v[12:15], v[178:181], v[202:205], v[12:15]
	v_mfma_f32_16x16x32_bf16 v[4:7], v[174:177], v[206:209], v[4:7]
	v_mfma_f32_16x16x32_bf16 v[4:7], v[178:181], v[210:213], v[4:7]
	v_mfma_f32_16x16x32_bf16 v[8:11], v[158:161], v[206:209], v[8:11]
	v_mfma_f32_16x16x32_bf16 v[8:11], v[170:173], v[210:213], v[8:11]
	s_barrier
	s_setprio 0
	s_add_u32 s45, s45, 0x100
	s_addc_u32 s47, s47, 0
	s_cmp_ge_i32 s72, s46
	s_mov_b64 s[24:25], s[0:1]
	s_mov_b32 s26, s72
	s_cbranch_scc0 .LBB0_3627
	s_and_b64 vcc, exec, s[50:51]
	s_cbranch_vccz .LBB0_3630
	s_barrier
